# DMA saddr form + read-slot DMA hoist + nt on final f32 outputs + layer-1 weight transposes moved from ATT0 into GU0 idle half-round
# speedup vs baseline: 1.0079x; 1.0079x over previous
.LBB0_185:
	v_or_b32_e32 v150, s7, v167
	s_and_b32 s7, s64, 0x380
	s_or_b32 s10, s7, s19
	s_cmp_eq_u32 s6, 1
	s_cselect_b64 s[94:95], -1, 0
	s_cmp_lt_i32 s6, 1
	s_cselect_b64 s[6:7], -1, 0
	s_or_b64 s[4:5], s[6:7], s[4:5]
	s_and_b64 s[6:7], s[94:95], exec
	s_brev_b32 s6, 64
	s_cselect_b32 s6, s6, 0x3000000
	s_add_u32 s6, s54, s6
	s_addc_u32 s7, s55, 0
	s_lshl_b32 s11, s10, 2
	s_add_u32 s6, s6, s11
	s_addc_u32 s7, s7, 0
	v_mov_b32_e32 v159, v151
	v_lshl_add_u64 v[64:65], s[6:7], 0, v[158:159]
	v_lshlrev_b64 v[66:67], 12, v[150:151]
	v_lshl_add_u64 v[66:67], v[64:65], 0, v[66:67]
	s_and_b64 vcc, exec, s[4:5]
	s_cbranch_vccnz .LBB0_187
	global_store_dwordx4 v[66:67], v[56:59], off nt

.LBB0_190:
	global_store_dwordx4 v[66:67], v[44:47], off offset:192 nt

.LBB0_195:
	global_store_dwordx4 v[42:43], v[28:31], off offset:192 nt

.LBB0_200:
	global_store_dwordx4 v[26:27], v[20:23], off offset:192 nt

.LBB0_210:
	s_waitcnt vmcnt(6) lgkmcnt(0)
	s_barrier
	s_waitcnt lgkmcnt(0)
	v_mfma_f32_16x16x32_bf16 v[124:127], v[52:55], v[64:67], v[124:127]
	s_mul_i32 s23, s26, 0xc000
	s_add_i32 s27, s23, 0xffff4000
	v_mfma_f32_16x16x32_bf16 v[120:123], v[48:51], v[64:67], v[120:123]
	s_cmp_lg_u32 s26, 0
	s_cselect_b32 s27, s27, 0x18000
	s_add_i32 s33, s16, s27
	v_mfma_f32_16x16x32_bf16 v[116:119], v[44:47], v[64:67], v[116:119]
	v_mfma_f32_16x16x32_bf16 v[64:67], v[40:43], v[64:67], v[112:115]
	v_mfma_f32_16x16x32_bf16 v[108:111], v[52:55], v[56:59], v[108:111]
	v_mfma_f32_16x16x32_bf16 v[104:107], v[48:51], v[56:59], v[104:107]
	v_mfma_f32_16x16x32_bf16 v[100:103], v[44:47], v[56:59], v[100:103]
	v_mfma_f32_16x16x32_bf16 v[56:59], v[40:43], v[56:59], v[96:99]
	s_add_u32 s60, s10, s6
	v_mov_b32_e32 v150, v178
	s_addc_u32 s61, s11, s7
	s_mov_b32 m0, s33
	s_add_u32 s98, s60, s72
	s_addc_u32 s99, s61, s73
	global_load_lds_dwordx4 v178, s[98:99]
	v_mfma_f32_16x16x32_bf16 v[92:95], v[52:55], v[36:39], v[92:95]
	v_mfma_f32_16x16x32_bf16 v[88:91], v[48:51], v[36:39], v[88:91]
	v_mfma_f32_16x16x32_bf16 v[84:87], v[44:47], v[36:39], v[84:87]
	v_mfma_f32_16x16x32_bf16 v[36:39], v[40:43], v[36:39], v[80:83]
	v_mfma_f32_16x16x32_bf16 v[52:55], v[52:55], v[32:35], v[76:79]
	v_mfma_f32_16x16x32_bf16 v[48:51], v[48:51], v[32:35], v[72:75]
	v_mfma_f32_16x16x32_bf16 v[44:47], v[44:47], v[32:35], v[68:71]
	v_mfma_f32_16x16x32_bf16 v[32:35], v[40:43], v[32:35], v[60:63]
	v_mov_b32_e32 v150, v179
	s_add_i32 m0, s33, 0x400
	s_add_u32 s100, s60, s74
	s_addc_u32 s101, s61, s75
	global_load_lds_dwordx4 v179, s[100:101]
	v_mfma_f32_16x16x32_bf16 v[124:127], v[20:23], v[28:31], v[124:127]
	v_mfma_f32_16x16x32_bf16 v[120:123], v[16:19], v[28:31], v[120:123]
	v_mfma_f32_16x16x32_bf16 v[116:119], v[12:15], v[28:31], v[116:119]
	v_mfma_f32_16x16x32_bf16 v[112:115], v[8:11], v[28:31], v[64:67]
	v_mfma_f32_16x16x32_bf16 v[108:111], v[20:23], v[24:27], v[108:111]
	v_mfma_f32_16x16x32_bf16 v[104:107], v[16:19], v[24:27], v[104:107]
	v_mfma_f32_16x16x32_bf16 v[100:103], v[12:15], v[24:27], v[100:103]
	v_mfma_f32_16x16x32_bf16 v[96:99], v[8:11], v[24:27], v[56:59]
	v_mov_b32_e32 v150, v178
	s_add_i32 m0, s33, 0x800
	s_add_u32 s98, s60, s76
	s_addc_u32 s99, s61, s77
	global_load_lds_dwordx4 v178, s[98:99]
	v_mfma_f32_16x16x32_bf16 v[92:95], v[20:23], v[4:7], v[92:95]
	s_waitcnt lgkmcnt(0)
	v_mfma_f32_16x16x32_bf16 v[88:91], v[16:19], v[4:7], v[88:91]
	v_mfma_f32_16x16x32_bf16 v[84:87], v[12:15], v[4:7], v[84:87]
	v_mfma_f32_16x16x32_bf16 v[80:83], v[8:11], v[4:7], v[36:39]
	v_mfma_f32_16x16x32_bf16 v[76:79], v[20:23], v[0:3], v[52:55]
	v_mfma_f32_16x16x32_bf16 v[72:75], v[16:19], v[0:3], v[48:51]
	v_mfma_f32_16x16x32_bf16 v[68:71], v[12:15], v[0:3], v[44:47]
	v_mfma_f32_16x16x32_bf16 v[60:63], v[8:11], v[0:3], v[32:35]
	s_barrier
	s_add_i32 s23, s23, 0
	v_add_u32_e32 v0, s23, v164
	v_add_u32_e32 v8, s23, v165
	s_add_i32 s23, s27, 0
	s_add_i32 s27, s23, s3
	s_add_i32 m0, s27, 0xc00
	s_add_u32 s100, s60, s78
	s_addc_u32 s101, s61, s79
	s_add_u32 s60, vcc_lo, s6
	s_addc_u32 s61, vcc_hi, s7
	global_load_lds_dwordx4 v179, s[100:101]
	s_add_i32 s23, s23, s17
	s_add_i32 m0, s23, 0x8000
	s_add_u32 s98, s60, s80
	s_addc_u32 s99, s61, s81
	global_load_lds_dwordx4 v178, s[98:99]
	s_add_i32 m0, s23, 0x8400
	s_add_u32 s100, s60, s82
	s_addc_u32 s101, s61, s83
	global_load_lds_dwordx4 v179, s[100:101]
	v_add3_u32 v1, v0, s21, v169
	v_add3_u32 v0, v0, s20, v169
	ds_read_b128 v[64:67], v1
	ds_read_b128 v[56:59], v1 offset:2048
	ds_read_b128 v[36:39], v1 offset:4096
	ds_read_b128 v[32:35], v1 offset:6144
	ds_read_b128 v[52:55], v0 offset:32768
	ds_read_b128 v[48:51], v0 offset:34816
	ds_read_b128 v[44:47], v0 offset:36864
	ds_read_b128 v[40:43], v0 offset:38912
	v_add3_u32 v0, v8, s21, v169
	v_add3_u32 v8, v8, s20, v169
	ds_read_b128 v[28:31], v0
	ds_read_b128 v[24:27], v0 offset:2048
	ds_read_b128 v[4:7], v0 offset:4096
	ds_read_b128 v[0:3], v0 offset:6144
	ds_read_b128 v[20:23], v8 offset:32768
	ds_read_b128 v[16:19], v8 offset:34816
	ds_read_b128 v[12:15], v8 offset:36864
	ds_read_b128 v[8:11], v8 offset:38912
	s_waitcnt lgkmcnt(0)
	v_mov_b32_e32 v150, v179
	v_mov_b32_e32 v150, v178
	v_mov_b32_e32 v150, v179
	s_add_i32 s23, s26, 1
	s_cmp_lg_u32 s26, 2
	s_cselect_b32 s26, s23, 0
	s_add_u32 s6, s6, 0x80
	s_addc_u32 s7, s7, 0
	s_cmpk_eq_i32 s6, 0x680
	s_cbranch_scc0 .LBB0_210
	s_waitcnt vmcnt(6) lgkmcnt(0)
	s_barrier
	s_waitcnt lgkmcnt(0)
	v_mfma_f32_16x16x32_bf16 v[124:127], v[52:55], v[64:67], v[124:127]
	s_mul_i32 s11, s26, 0xc000
	s_add_i32 s6, s11, 0xffff4000
	v_mfma_f32_16x16x32_bf16 v[120:123], v[48:51], v[64:67], v[120:123]
	s_cmp_lg_u32 s26, 0
	s_cselect_b32 s10, s6, 0x18000
	s_andn2_b64 vcc, exec, s[94:95]
	v_mfma_f32_16x16x32_bf16 v[116:119], v[44:47], v[64:67], v[116:119]
	v_mfma_f32_16x16x32_bf16 v[64:67], v[40:43], v[64:67], v[112:115]
	v_mfma_f32_16x16x32_bf16 v[108:111], v[52:55], v[56:59], v[108:111]
	s_nop 1
	v_cndmask_b32_e64 v112, 0, 1, s[94:95]
	v_cmp_ne_u32_e64 s[6:7], 1, v112
	v_mfma_f32_16x16x32_bf16 v[104:107], v[48:51], v[56:59], v[104:107]
	v_mfma_f32_16x16x32_bf16 v[100:103], v[44:47], v[56:59], v[100:103]
	v_mfma_f32_16x16x32_bf16 v[140:143], v[40:43], v[56:59], v[96:99]
	s_cbranch_vccnz .LBB0_213
	s_add_u32 s60, s66, s8
	v_mov_b32_e32 v56, v178
	s_addc_u32 s61, s67, s9
	s_add_i32 m0, s16, s10
	s_nop 0
	global_load_lds_dwordx4 v56, s[60:61]

.LBB0_237:
	s_waitcnt vmcnt(6) lgkmcnt(0)
	s_barrier
	s_mul_i32 s23, s10, 0xc000
	s_add_i32 s26, s23, 0
	v_add_u32_e32 v80, s26, v164
	v_add_u32_e32 v112, s26, v165
	s_add_i32 s23, s23, 0xffff4000
	s_cmp_lg_u32 s10, 0
	s_cselect_b32 s23, s23, 0x18000
	s_add_i32 s29, s23, 0
	s_add_u32 s26, s6, s4
	s_addc_u32 s27, s7, s5
	s_add_i32 s60, s29, s3
	s_add_i32 m0, s60, 0xc00
	s_add_u32 s60, s11, s4
	s_addc_u32 s61, s22, s5
	s_add_u32 s98, s26, s78
	s_addc_u32 s99, s27, s79
	global_load_lds_dwordx4 v179, s[98:99]
	s_add_i32 s29, s29, s17
	s_add_i32 m0, s29, 0x8000
	s_add_u32 s100, s60, s80
	s_addc_u32 s101, s61, s81
	global_load_lds_dwordx4 v178, s[100:101]
	s_add_i32 m0, s29, 0x8400
	s_add_u32 s98, s60, s82
	s_addc_u32 s99, s61, s83
	global_load_lds_dwordx4 v179, s[98:99]
	v_add3_u32 v76, v80, s21, v169
	v_add3_u32 v92, v80, s20, v169
	v_add3_u32 v108, v112, s21, v169
	v_add3_u32 v124, v112, s20, v169
	ds_read_b128 v[64:67], v76
	ds_read_b128 v[68:71], v76 offset:2048
	ds_read_b128 v[72:75], v76 offset:4096
	ds_read_b128 v[76:79], v76 offset:6144
	ds_read_b128 v[80:83], v92 offset:32768
	ds_read_b128 v[84:87], v92 offset:34816
	ds_read_b128 v[88:91], v92 offset:36864
	ds_read_b128 v[92:95], v92 offset:38912
	ds_read_b128 v[96:99], v108
	ds_read_b128 v[100:103], v108 offset:2048
	ds_read_b128 v[104:107], v108 offset:4096
	ds_read_b128 v[108:111], v108 offset:6144
	ds_read_b128 v[112:115], v124 offset:32768
	ds_read_b128 v[116:119], v124 offset:34816
	ds_read_b128 v[120:123], v124 offset:36864
	ds_read_b128 v[124:127], v124 offset:38912
	s_waitcnt lgkmcnt(0)
	v_mov_b32_e32 v150, v179
	v_mov_b32_e32 v150, v178
	v_mov_b32_e32 v150, v179
	s_waitcnt lgkmcnt(0)
	s_barrier
	s_waitcnt lgkmcnt(0)
	v_mfma_f32_16x16x32_bf16 v[60:63], v[80:83], v[64:67], v[60:63]
	s_add_i32 s23, s16, s23
	v_mfma_f32_16x16x32_bf16 v[56:59], v[84:87], v[64:67], v[56:59]
	v_mfma_f32_16x16x32_bf16 v[52:55], v[88:91], v[64:67], v[52:55]
	v_mfma_f32_16x16x32_bf16 v[48:51], v[92:95], v[64:67], v[48:51]
	v_mfma_f32_16x16x32_bf16 v[44:47], v[80:83], v[68:71], v[44:47]
	v_mfma_f32_16x16x32_bf16 v[40:43], v[84:87], v[68:71], v[40:43]
	v_mfma_f32_16x16x32_bf16 v[36:39], v[88:91], v[68:71], v[36:39]
	v_mfma_f32_16x16x32_bf16 v[28:31], v[92:95], v[68:71], v[28:31]
	v_mov_b32_e32 v150, v178
	s_mov_b32 m0, s23
	s_add_u32 s100, s26, s72
	s_addc_u32 s101, s27, s73
	global_load_lds_dwordx4 v178, s[100:101]
	v_mfma_f32_16x16x32_bf16 v[24:27], v[80:83], v[72:75], v[24:27]
	v_mfma_f32_16x16x32_bf16 v[20:23], v[84:87], v[72:75], v[20:23]
	v_mfma_f32_16x16x32_bf16 v[16:19], v[88:91], v[72:75], v[16:19]
	v_mfma_f32_16x16x32_bf16 v[12:15], v[92:95], v[72:75], v[12:15]
	v_mfma_f32_16x16x32_bf16 v[8:11], v[80:83], v[76:79], v[8:11]
	v_mfma_f32_16x16x32_bf16 v[4:7], v[84:87], v[76:79], v[4:7]
	v_mfma_f32_16x16x32_bf16 v[0:3], v[88:91], v[76:79], v[0:3]
	v_mfma_f32_16x16x32_bf16 v[32:35], v[92:95], v[76:79], v[32:35]
	v_mov_b32_e32 v150, v179
	s_add_i32 m0, s23, 0x400
	s_add_u32 s98, s26, s74
	s_addc_u32 s99, s27, s75
	global_load_lds_dwordx4 v179, s[98:99]
	v_mfma_f32_16x16x32_bf16 v[60:63], v[112:115], v[96:99], v[60:63]
	v_mfma_f32_16x16x32_bf16 v[56:59], v[116:119], v[96:99], v[56:59]
	v_mfma_f32_16x16x32_bf16 v[52:55], v[120:123], v[96:99], v[52:55]
	v_mfma_f32_16x16x32_bf16 v[48:51], v[124:127], v[96:99], v[48:51]
	v_mfma_f32_16x16x32_bf16 v[44:47], v[112:115], v[100:103], v[44:47]
	v_mfma_f32_16x16x32_bf16 v[40:43], v[116:119], v[100:103], v[40:43]
	v_mfma_f32_16x16x32_bf16 v[36:39], v[120:123], v[100:103], v[36:39]
	v_mfma_f32_16x16x32_bf16 v[28:31], v[124:127], v[100:103], v[28:31]
	v_mov_b32_e32 v150, v178
	s_add_i32 m0, s23, 0x800
	s_add_u32 s100, s26, s76
	s_addc_u32 s101, s27, s77
	global_load_lds_dwordx4 v178, s[100:101]
	s_add_i32 s23, s10, 1
	v_mfma_f32_16x16x32_bf16 v[24:27], v[112:115], v[104:107], v[24:27]
	s_cmp_lg_u32 s10, 2
	s_cselect_b32 s10, s23, 0
	s_add_u32 s4, s4, 0x80
	v_mfma_f32_16x16x32_bf16 v[20:23], v[116:119], v[104:107], v[20:23]
	s_addc_u32 s5, s5, 0
	s_cmpk_eq_i32 s4, 0x680
	v_mfma_f32_16x16x32_bf16 v[16:19], v[120:123], v[104:107], v[16:19]
	v_mfma_f32_16x16x32_bf16 v[12:15], v[124:127], v[104:107], v[12:15]
	v_mfma_f32_16x16x32_bf16 v[8:11], v[112:115], v[108:111], v[8:11]
	v_mfma_f32_16x16x32_bf16 v[4:7], v[116:119], v[108:111], v[4:7]
	v_mfma_f32_16x16x32_bf16 v[0:3], v[120:123], v[108:111], v[0:3]
	v_mfma_f32_16x16x32_bf16 v[32:35], v[124:127], v[108:111], v[32:35]
	s_cbranch_scc0 .LBB0_237
	s_waitcnt vmcnt(6) lgkmcnt(0)
	s_barrier
	s_mul_i32 s4, s10, 0xc000
	s_add_i32 s4, s4, 0
	v_add_u32_e32 v64, s4, v164
	v_add3_u32 v65, v64, s21, v169
	v_add3_u32 v64, v64, s20, v169
	v_add_u32_e32 v68, s4, v165
	ds_read_b128 v[124:127], v65
	ds_read_b128 v[120:123], v65 offset:2048
	ds_read_b128 v[100:103], v65 offset:4096
	ds_read_b128 v[96:99], v65 offset:6144
	ds_read_b128 v[108:111], v64 offset:32768
	ds_read_b128 v[112:115], v64 offset:34816
	ds_read_b128 v[116:119], v64 offset:36864
	ds_read_b128 v[104:107], v64 offset:38912
	v_add3_u32 v64, v68, s21, v169
	v_add3_u32 v68, v68, s20, v169
	ds_read_b128 v[92:95], v64
	ds_read_b128 v[88:91], v64 offset:2048
	ds_read_b128 v[72:75], v64 offset:4096
	ds_read_b128 v[64:67], v64 offset:6144
	ds_read_b128 v[76:79], v68 offset:32768
	ds_read_b128 v[80:83], v68 offset:34816
	ds_read_b128 v[84:87], v68 offset:36864
	ds_read_b128 v[68:71], v68 offset:38912
	s_waitcnt lgkmcnt(0)
	v_sub_co_u32_e64 v128, s[4:5], s10, 1
	s_and_b64 s[4:5], s[4:5], exec
	v_readfirstlane_b32 s4, v128
	s_cselect_b32 s23, 2, s4
	v_cndmask_b32_e64 v128, 0, 1, s[92:93]
	s_mov_b64 s[4:5], -1
	v_cmp_ne_u32_e64 s[6:7], 1, v128
	s_andn2_b64 vcc, exec, s[92:93]
	s_mul_i32 s22, s23, 0xc000
	s_cbranch_vccnz .LBB0_240
	s_mul_i32 s11, s23, 0xc000
	s_mov_b64 s[4:5], 0

.LBB0_261:
	global_store_dwordx4 v[66:67], v[40:43], off offset:64 nt
	s_and_b64 vcc, exec, s[6:7]
	s_cbranch_vccnz .LBB0_189
.LBB0_262:
	global_store_dwordx4 v[66:67], v[60:63], off offset:128 nt
	s_and_b64 vcc, exec, s[6:7]
	s_cbranch_vccz .LBB0_190
	s_branch .LBB0_191
.LBB0_263:
	global_store_dwordx4 v[42:43], v[48:51], off nt
	s_and_b64 vcc, exec, s[6:7]
	s_cbranch_vccnz .LBB0_193
.LBB0_264:
	global_store_dwordx4 v[42:43], v[24:27], off offset:64 nt
	s_and_b64 vcc, exec, s[6:7]
	s_cbranch_vccnz .LBB0_194
.LBB0_265:
	global_store_dwordx4 v[42:43], v[52:55], off offset:128 nt
	s_and_b64 vcc, exec, s[6:7]
	s_cbranch_vccz .LBB0_195
	s_branch .LBB0_196
.LBB0_266:
	global_store_dwordx4 v[26:27], v[32:35], off nt
	s_and_b64 vcc, exec, s[6:7]
	s_cbranch_vccnz .LBB0_198
.LBB0_267:
	global_store_dwordx4 v[26:27], v[16:19], off offset:64 nt
	s_and_b64 vcc, exec, s[6:7]
	s_cbranch_vccnz .LBB0_199
.LBB0_268:
	global_store_dwordx4 v[26:27], v[36:39], off offset:128 nt
	s_and_b64 vcc, exec, s[6:7]
	s_cbranch_vccz .LBB0_200
	s_branch .LBB0_201
.LBB0_269:
	global_store_dwordx4 v[16:17], v[12:15], off nt
	s_and_b64 vcc, exec, s[6:7]
	s_cbranch_vccnz .LBB0_203
.LBB0_270:
	global_store_dwordx4 v[16:17], v[0:3], off offset:64 nt
	s_and_b64 vcc, exec, s[6:7]
	s_cbranch_vccnz .LBB0_204
.LBB0_271:
	global_store_dwordx4 v[16:17], v[4:7], off offset:128 nt
	s_and_b64 vcc, exec, s[6:7]
	s_cbranch_vccnz .LBB0_178
.LBB0_272:
	global_store_dwordx4 v[16:17], v[8:11], off offset:192 nt
	s_branch .LBB0_178

.LBB0_326:
	s_or_b64 exec, exec, s[4:5]
	v_readlane_b32 s0, v219, 9
	v_lshlrev_b32_e32 v20, 2, v149
	v_readlane_b32 s8, v219, 17
	v_readlane_b32 s9, v219, 18
	s_waitcnt lgkmcnt(0)
	s_barrier
	s_nop 2
	global_load_dword v0, v20, s[8:9]
	global_load_dword v1, v20, s[8:9] offset:256
	global_load_dword v2, v20, s[8:9] offset:512
	global_load_dword v3, v20, s[8:9] offset:768
	v_mbcnt_hi_u32_b32 v4, -1, v163
	v_and_b32_e32 v5, 64, v4
	v_xor_b32_e32 v6, 32, v4
	v_add_u32_e32 v5, 64, v5
	v_cmp_lt_i32_e32 vcc, v6, v5
	v_xor_b32_e32 v7, 16, v4
	v_xor_b32_e32 v8, 8, v4
	v_cndmask_b32_e32 v6, v4, v6, vcc
	v_lshlrev_b32_e32 v172, 2, v6
	v_cmp_lt_i32_e32 vcc, v7, v5
	v_xor_b32_e32 v9, 4, v4
	v_xor_b32_e32 v10, 2, v4
	v_cndmask_b32_e32 v7, v4, v7, vcc
	v_lshlrev_b32_e32 v173, 2, v7
	v_cmp_lt_i32_e32 vcc, v8, v5
	v_xor_b32_e32 v11, 1, v4
	s_bcnt1_i32_b32 s0, s78
	s_bitcmp0_b32 s0, 0
	s_cselect_b64 s[8:9], -1, 0
	v_readlane_b32 s1, v219, 10
	v_readlane_b32 s2, v219, 11
	v_readlane_b32 s3, v219, 12
	v_readlane_b32 s4, v219, 13
	v_readlane_b32 s5, v219, 14
	v_readlane_b32 s6, v219, 15
	v_readlane_b32 s7, v219, 16
	v_readlane_b32 s10, v219, 19
	v_readlane_b32 s11, v219, 20
	v_readlane_b32 s12, v219, 21
	v_readlane_b32 s13, v219, 22
	v_readlane_b32 s14, v219, 23
	v_readlane_b32 s15, v219, 24
	s_waitcnt vmcnt(2)
	v_mul_f32_e32 v6, v0, v1
	ds_bpermute_b32 v6, v172, v6
	s_waitcnt vmcnt(0)
	v_mul_f32_e32 v12, v2, v3
	ds_bpermute_b32 v12, v172, v12
	s_waitcnt lgkmcnt(1)
	v_fmac_f32_e32 v6, v0, v1
	ds_bpermute_b32 v0, v173, v6
	s_waitcnt lgkmcnt(1)
	v_fmac_f32_e32 v12, v2, v3
	ds_bpermute_b32 v1, v173, v12
	v_cndmask_b32_e32 v2, v4, v8, vcc
	v_lshlrev_b32_e32 v174, 2, v2
	s_waitcnt lgkmcnt(1)
	v_add_f32_e32 v0, v6, v0
	ds_bpermute_b32 v2, v174, v0
	s_waitcnt lgkmcnt(1)
	v_add_f32_e32 v1, v12, v1
	ds_bpermute_b32 v3, v174, v1
	v_cmp_lt_i32_e32 vcc, v9, v5
	s_waitcnt lgkmcnt(1)
	v_add_f32_e32 v0, v0, v2
	v_cndmask_b32_e32 v6, v4, v9, vcc
	v_lshlrev_b32_e32 v175, 2, v6
	s_waitcnt lgkmcnt(0)
	v_add_f32_e32 v1, v1, v3
	ds_bpermute_b32 v2, v175, v0
	ds_bpermute_b32 v3, v175, v1
	v_cmp_lt_i32_e32 vcc, v10, v5
	s_waitcnt lgkmcnt(1)
	v_add_f32_e32 v0, v0, v2
	v_cndmask_b32_e32 v6, v4, v10, vcc
	v_lshlrev_b32_e32 v176, 2, v6
	s_waitcnt lgkmcnt(0)
	v_add_f32_e32 v1, v1, v3
	ds_bpermute_b32 v2, v176, v0
	ds_bpermute_b32 v3, v176, v1
	v_cmp_lt_i32_e32 vcc, v11, v5
	s_waitcnt lgkmcnt(1)
	v_add_f32_e32 v21, v0, v2
	v_cndmask_b32_e32 v4, v4, v11, vcc
	v_lshlrev_b32_e32 v177, 2, v4
	s_waitcnt lgkmcnt(0)
	v_add_f32_e32 v22, v1, v3
	ds_bpermute_b32 v23, v177, v21
	ds_bpermute_b32 v24, v177, v22
	s_and_b64 vcc, exec, s[8:9]
	s_cbranch_vccnz .LBB0_347
	s_add_i32 s0, s78, 0xc0
	s_cmpk_gt_i32 s0, 0x30f
	s_waitcnt lgkmcnt(0)
	s_barrier
	s_cbranch_scc1 .LBB0_346
	s_movk_i32 s1, 0x2100
	v_lshrrev_b32_e32 v25, 3, v149
	v_and_b32_e32 v4, 56, v144
	s_cmpk_eq_i32 s58, 0x100
	v_mad_u32_u24 v1, v148, s1, 0
	v_lshrrev_b32_e32 v0, 5, v149
	v_and_b32_e32 v2, 31, v168
	v_mul_u32_u24_e32 v3, 0x84, v4
	v_lshlrev_b32_e32 v7, 2, v25
	s_cselect_b64 s[6:7], -1, 0
	v_mov_b32_e32 v5, 0
	v_lshl_add_u32 v6, v2, 2, v1
	s_movk_i32 s1, 0x84
	v_add3_u32 v26, v1, v3, v7
	v_or_b32_e32 v27, 8, v25
	v_or_b32_e32 v28, 16, v25
	v_or_b32_e32 v29, 24, v25
	v_mov_b32_e32 v1, v0
	s_movk_i32 s2, 0x187f
	s_movk_i32 s3, 0x1ff
	s_movk_i32 s10, 0xcff
	v_lshlrev_b32_e32 v8, 2, v2
	v_lshlrev_b32_e32 v10, 1, v4
	v_mov_b32_e32 v30, 0xffffe780
	v_mov_b32_e32 v31, 0xc00
	v_mov_b32_e32 v32, 0x600
	v_mov_b32_e32 v33, 0x2c0000
	v_mov_b32_e32 v34, 0x1400000
	v_mov_b32_e32 v35, 0x2980000
	v_mov_b32_e32 v36, 0x900000
	v_mov_b32_e32 v37, 0x1e80000
	v_mov_b32_e32 v38, 0x700000
	v_mov_b32_e32 v39, 0x1c80000
	v_mov_b32_e32 v40, 0x100000
	v_mov_b32_e32 v41, 0x1980000
	s_branch .LBB0_330
.LBB0_329:
	s_add_i32 s0, s0, s58
	s_cmpk_lt_i32 s0, 0x310
	s_cbranch_scc0 .LBB0_346

.LBB0_375:
	s_and_b64 vcc, exec, s[8:9]
	s_cbranch_vccz .LBB0_396
	s_add_i32 s0, s78, 0xc0
	s_cmpk_gt_i32 s0, 0x30f
	s_waitcnt lgkmcnt(0)
	s_barrier
	s_cbranch_scc1 .LBB0_395
	s_movk_i32 s1, 0x2100
	v_lshrrev_b32_e32 v20, 3, v149
	v_and_b32_e32 v4, 56, v144
	s_cmpk_eq_i32 s58, 0x100
	v_mad_u32_u24 v1, v148, s1, 0
	v_lshrrev_b32_e32 v0, 5, v149
	v_and_b32_e32 v2, 31, v168
	v_mul_u32_u24_e32 v3, 0x84, v4
	v_lshlrev_b32_e32 v7, 2, v20
	s_cselect_b64 s[6:7], -1, 0
	v_mov_b32_e32 v5, 0
	v_lshl_add_u32 v6, v2, 2, v1
	s_movk_i32 s1, 0x84
	v_add3_u32 v21, v1, v3, v7
	v_or_b32_e32 v22, 8, v20
	v_or_b32_e32 v23, 16, v20
	v_or_b32_e32 v24, 24, v20
	v_mov_b32_e32 v1, v0
	s_movk_i32 s2, 0x187f
	s_movk_i32 s3, 0x1ff
	s_movk_i32 s10, 0xcff
	v_lshlrev_b32_e32 v8, 2, v2
	v_lshlrev_b32_e32 v10, 1, v4
	v_mov_b32_e32 v25, 0xffffe780
	v_mov_b32_e32 v26, 0xc00
	v_mov_b32_e32 v27, 0x600
	v_mov_b32_e32 v28, 0x2c0000
	v_mov_b32_e32 v29, 0x1400000
	v_mov_b32_e32 v30, 0x2980000
	v_mov_b32_e32 v31, 0x900000
	v_mov_b32_e32 v32, 0x1e80000
	v_mov_b32_e32 v33, 0x700000
	v_mov_b32_e32 v34, 0x1c80000
	v_mov_b32_e32 v35, 0x100000
	v_mov_b32_e32 v36, 0x1980000
	s_branch .LBB0_379

.LBB0_459:
	s_waitcnt vmcnt(6) lgkmcnt(0)
	s_barrier
	s_waitcnt lgkmcnt(0)
	v_mfma_f32_16x16x32_bf16 v[124:127], v[52:55], v[64:67], v[124:127]
	s_mul_i32 s66, s29, 0xc000
	s_add_i32 s64, s66, 0xffff4000
	v_mfma_f32_16x16x32_bf16 v[120:123], v[48:51], v[64:67], v[120:123]
	s_cmp_lg_u32 s29, 0
	s_cselect_b32 s67, s64, 0x18000
	s_add_i32 s61, s16, s67
	v_mfma_f32_16x16x32_bf16 v[116:119], v[44:47], v[64:67], v[116:119]
	v_mfma_f32_16x16x32_bf16 v[64:67], v[40:43], v[64:67], v[112:115]
	v_mfma_f32_16x16x32_bf16 v[108:111], v[52:55], v[56:59], v[108:111]
	v_mfma_f32_16x16x32_bf16 v[104:107], v[48:51], v[56:59], v[104:107]
	v_mfma_f32_16x16x32_bf16 v[100:103], v[44:47], v[56:59], v[100:103]
	v_mfma_f32_16x16x32_bf16 v[56:59], v[40:43], v[56:59], v[96:99]
	s_add_u32 s64, s10, s6
	v_mov_b32_e32 v150, v162
	s_addc_u32 s65, s11, s7
	s_mov_b32 m0, s61
	s_add_u32 s98, s64, s48
	s_addc_u32 s99, s65, s49
	global_load_lds_dwordx4 v162, s[98:99]
	v_mfma_f32_16x16x32_bf16 v[92:95], v[52:55], v[36:39], v[92:95]
	v_mfma_f32_16x16x32_bf16 v[88:91], v[48:51], v[36:39], v[88:91]
	v_mfma_f32_16x16x32_bf16 v[84:87], v[44:47], v[36:39], v[84:87]
	v_mfma_f32_16x16x32_bf16 v[36:39], v[40:43], v[36:39], v[80:83]
	v_mfma_f32_16x16x32_bf16 v[52:55], v[52:55], v[32:35], v[76:79]
	v_mfma_f32_16x16x32_bf16 v[48:51], v[48:51], v[32:35], v[72:75]
	v_mfma_f32_16x16x32_bf16 v[44:47], v[44:47], v[32:35], v[68:71]
	v_mfma_f32_16x16x32_bf16 v[32:35], v[40:43], v[32:35], v[60:63]
	v_mov_b32_e32 v150, v163
	s_add_i32 m0, s61, 0x400
	s_add_u32 s100, s64, s50
	s_addc_u32 s101, s65, s51
	global_load_lds_dwordx4 v163, s[100:101]
	v_mfma_f32_16x16x32_bf16 v[124:127], v[20:23], v[28:31], v[124:127]
	v_mfma_f32_16x16x32_bf16 v[120:123], v[16:19], v[28:31], v[120:123]
	v_mfma_f32_16x16x32_bf16 v[116:119], v[12:15], v[28:31], v[116:119]
	v_mfma_f32_16x16x32_bf16 v[112:115], v[8:11], v[28:31], v[64:67]
	v_mfma_f32_16x16x32_bf16 v[108:111], v[20:23], v[24:27], v[108:111]
	v_mfma_f32_16x16x32_bf16 v[104:107], v[16:19], v[24:27], v[104:107]
	v_mfma_f32_16x16x32_bf16 v[100:103], v[12:15], v[24:27], v[100:103]
	v_mfma_f32_16x16x32_bf16 v[96:99], v[8:11], v[24:27], v[56:59]
	v_mov_b32_e32 v150, v162
	s_add_i32 m0, s61, 0x800
	s_add_u32 s98, s64, s68
	s_addc_u32 s99, s65, s69
	global_load_lds_dwordx4 v162, s[98:99]
	v_mfma_f32_16x16x32_bf16 v[92:95], v[20:23], v[4:7], v[92:95]
	s_waitcnt lgkmcnt(0)
	v_mfma_f32_16x16x32_bf16 v[88:91], v[16:19], v[4:7], v[88:91]
	v_mfma_f32_16x16x32_bf16 v[84:87], v[12:15], v[4:7], v[84:87]
	v_mfma_f32_16x16x32_bf16 v[80:83], v[8:11], v[4:7], v[36:39]
	v_mfma_f32_16x16x32_bf16 v[76:79], v[20:23], v[0:3], v[52:55]
	v_mfma_f32_16x16x32_bf16 v[72:75], v[16:19], v[0:3], v[48:51]
	v_mfma_f32_16x16x32_bf16 v[68:71], v[12:15], v[0:3], v[44:47]
	v_mfma_f32_16x16x32_bf16 v[60:63], v[8:11], v[0:3], v[32:35]
	s_barrier
	s_add_i32 s61, s66, 0
	v_add_u32_e32 v0, s61, v157
	v_add_u32_e32 v8, s61, v158
	s_add_i32 s61, s67, 0
	s_add_u32 s100, s64, s70
	s_addc_u32 s101, s65, s71
	s_add_i32 s64, s61, s3
	s_add_i32 m0, s64, 0xc00
	s_add_u32 s64, vcc_lo, s6
	s_addc_u32 s65, vcc_hi, s7
	global_load_lds_dwordx4 v163, s[100:101]
	s_add_i32 s61, s61, s17
	s_add_i32 m0, s61, 0x8000
	s_add_u32 s98, s64, s72
	s_addc_u32 s99, s65, s73
	global_load_lds_dwordx4 v162, s[98:99]
	s_add_i32 m0, s61, 0x8400
	s_add_u32 s100, s64, s74
	s_addc_u32 s101, s65, s75
	global_load_lds_dwordx4 v163, s[100:101]
	v_add3_u32 v1, v0, s25, v169
	v_add3_u32 v0, v0, s24, v169
	ds_read_b128 v[64:67], v1
	ds_read_b128 v[56:59], v1 offset:2048
	ds_read_b128 v[36:39], v1 offset:4096
	ds_read_b128 v[32:35], v1 offset:6144
	ds_read_b128 v[52:55], v0 offset:32768
	ds_read_b128 v[48:51], v0 offset:34816
	ds_read_b128 v[44:47], v0 offset:36864
	ds_read_b128 v[40:43], v0 offset:38912
	v_add3_u32 v0, v8, s25, v169
	v_add3_u32 v8, v8, s24, v169
	ds_read_b128 v[28:31], v0
	ds_read_b128 v[24:27], v0 offset:2048
	ds_read_b128 v[4:7], v0 offset:4096
	ds_read_b128 v[0:3], v0 offset:6144
	ds_read_b128 v[20:23], v8 offset:32768
	ds_read_b128 v[16:19], v8 offset:34816
	ds_read_b128 v[12:15], v8 offset:36864
	ds_read_b128 v[8:11], v8 offset:38912
	s_waitcnt lgkmcnt(0)
	v_mov_b32_e32 v150, v163
	v_mov_b32_e32 v150, v162
	v_mov_b32_e32 v150, v163
	s_add_i32 s61, s29, 1
	s_cmp_lg_u32 s29, 2
	s_cselect_b32 s29, s61, 0
	s_add_u32 s6, s6, 0x80
	s_addc_u32 s7, s7, 0
	s_cmpk_eq_i32 s6, 0x680
	s_cbranch_scc0 .LBB0_459
	s_waitcnt vmcnt(6) lgkmcnt(0)
	s_barrier
	s_waitcnt lgkmcnt(0)
	v_mfma_f32_16x16x32_bf16 v[124:127], v[52:55], v[64:67], v[124:127]
	s_mul_i32 s11, s29, 0xc000
	s_add_i32 s6, s11, 0xffff4000
	v_mfma_f32_16x16x32_bf16 v[120:123], v[48:51], v[64:67], v[120:123]
	s_cmp_lg_u32 s29, 0
	s_cselect_b32 s10, s6, 0x18000
	s_andn2_b64 vcc, exec, s[12:13]
	v_mfma_f32_16x16x32_bf16 v[116:119], v[44:47], v[64:67], v[116:119]
	v_mfma_f32_16x16x32_bf16 v[64:67], v[40:43], v[64:67], v[112:115]
	v_mfma_f32_16x16x32_bf16 v[108:111], v[52:55], v[56:59], v[108:111]
	s_nop 1
	v_cndmask_b32_e64 v112, 0, 1, s[12:13]
	v_cmp_ne_u32_e64 s[6:7], 1, v112
	v_mfma_f32_16x16x32_bf16 v[104:107], v[48:51], v[56:59], v[104:107]
	v_mfma_f32_16x16x32_bf16 v[100:103], v[44:47], v[56:59], v[100:103]
	v_mfma_f32_16x16x32_bf16 v[140:143], v[40:43], v[56:59], v[96:99]
	s_cbranch_vccnz .LBB0_462
	s_add_u32 s64, s8, s94
	v_mov_b32_e32 v56, v162
	s_addc_u32 s65, s9, s95
	s_add_i32 m0, s16, s10
	s_nop 0
	global_load_lds_dwordx4 v56, s[64:65]

.LBB0_486:
	s_waitcnt vmcnt(6) lgkmcnt(0)
	s_barrier
	s_mul_i32 s19, s18, 0xc000
	s_add_i32 s26, s19, 0
	v_add_u32_e32 v80, s26, v157
	v_add_u32_e32 v112, s26, v158
	s_add_i32 s19, s19, 0xffff4000
	s_cmp_lg_u32 s18, 0
	s_cselect_b32 s19, s19, 0x18000
	s_add_i32 s26, s19, 0
	s_add_u32 s64, s6, s4
	s_addc_u32 s65, s7, s5
	s_add_i32 s66, s26, s3
	s_add_i32 m0, s66, 0xc00
	s_add_u32 s66, s29, s4
	s_addc_u32 s67, s92, s5
	s_add_u32 s98, s64, s70
	s_addc_u32 s99, s65, s71
	global_load_lds_dwordx4 v163, s[98:99]
	s_add_i32 s26, s26, s17
	s_add_i32 m0, s26, 0x8000
	s_add_u32 s100, s66, s72
	s_addc_u32 s101, s67, s73
	global_load_lds_dwordx4 v162, s[100:101]
	s_add_i32 m0, s26, 0x8400
	s_add_u32 s98, s66, s74
	s_addc_u32 s99, s67, s75
	global_load_lds_dwordx4 v163, s[98:99]
	v_add3_u32 v76, v80, s25, v169
	v_add3_u32 v92, v80, s24, v169
	v_add3_u32 v108, v112, s25, v169
	v_add3_u32 v124, v112, s24, v169
	ds_read_b128 v[64:67], v76
	ds_read_b128 v[68:71], v76 offset:2048
	ds_read_b128 v[72:75], v76 offset:4096
	ds_read_b128 v[76:79], v76 offset:6144
	ds_read_b128 v[80:83], v92 offset:32768
	ds_read_b128 v[84:87], v92 offset:34816
	ds_read_b128 v[88:91], v92 offset:36864
	ds_read_b128 v[92:95], v92 offset:38912
	ds_read_b128 v[96:99], v108
	ds_read_b128 v[100:103], v108 offset:2048
	ds_read_b128 v[104:107], v108 offset:4096
	ds_read_b128 v[108:111], v108 offset:6144
	ds_read_b128 v[112:115], v124 offset:32768
	ds_read_b128 v[116:119], v124 offset:34816
	ds_read_b128 v[120:123], v124 offset:36864
	ds_read_b128 v[124:127], v124 offset:38912
	s_waitcnt lgkmcnt(0)
	v_mov_b32_e32 v150, v163
	v_mov_b32_e32 v150, v162
	v_mov_b32_e32 v150, v163
	s_waitcnt lgkmcnt(0)
	s_barrier
	s_waitcnt lgkmcnt(0)
	v_mfma_f32_16x16x32_bf16 v[56:59], v[80:83], v[64:67], v[56:59]
	s_add_i32 s19, s16, s19
	v_mfma_f32_16x16x32_bf16 v[52:55], v[84:87], v[64:67], v[52:55]
	v_mfma_f32_16x16x32_bf16 v[48:51], v[88:91], v[64:67], v[48:51]
	v_mfma_f32_16x16x32_bf16 v[44:47], v[92:95], v[64:67], v[44:47]
	v_mfma_f32_16x16x32_bf16 v[40:43], v[80:83], v[68:71], v[40:43]
	v_mfma_f32_16x16x32_bf16 v[36:39], v[84:87], v[68:71], v[36:39]
	v_mfma_f32_16x16x32_bf16 v[32:35], v[88:91], v[68:71], v[32:35]
	v_mfma_f32_16x16x32_bf16 v[0:3], v[92:95], v[68:71], v[0:3]
	v_mov_b32_e32 v150, v162
	s_mov_b32 m0, s19
	s_add_u32 s100, s64, s48
	s_addc_u32 s101, s65, s49
	global_load_lds_dwordx4 v162, s[100:101]
	v_mfma_f32_16x16x32_bf16 v[28:31], v[80:83], v[72:75], v[28:31]
	v_mfma_f32_16x16x32_bf16 v[24:27], v[84:87], v[72:75], v[24:27]
	v_mfma_f32_16x16x32_bf16 v[20:23], v[88:91], v[72:75], v[20:23]
	v_mfma_f32_16x16x32_bf16 v[16:19], v[92:95], v[72:75], v[16:19]
	v_mfma_f32_16x16x32_bf16 v[12:15], v[80:83], v[76:79], v[12:15]
	v_mfma_f32_16x16x32_bf16 v[8:11], v[84:87], v[76:79], v[8:11]
	v_mfma_f32_16x16x32_bf16 v[4:7], v[88:91], v[76:79], v[4:7]
	v_mfma_f32_16x16x32_bf16 v[60:63], v[92:95], v[76:79], v[60:63]
	v_mov_b32_e32 v150, v163
	s_add_i32 m0, s19, 0x400
	s_add_u32 s98, s64, s50
	s_addc_u32 s99, s65, s51
	global_load_lds_dwordx4 v163, s[98:99]
	v_mfma_f32_16x16x32_bf16 v[56:59], v[112:115], v[96:99], v[56:59]
	v_mfma_f32_16x16x32_bf16 v[52:55], v[116:119], v[96:99], v[52:55]
	v_mfma_f32_16x16x32_bf16 v[48:51], v[120:123], v[96:99], v[48:51]
	v_mfma_f32_16x16x32_bf16 v[44:47], v[124:127], v[96:99], v[44:47]
	v_mfma_f32_16x16x32_bf16 v[40:43], v[112:115], v[100:103], v[40:43]
	v_mfma_f32_16x16x32_bf16 v[36:39], v[116:119], v[100:103], v[36:39]
	v_mfma_f32_16x16x32_bf16 v[32:35], v[120:123], v[100:103], v[32:35]
	v_mfma_f32_16x16x32_bf16 v[0:3], v[124:127], v[100:103], v[0:3]
	v_mov_b32_e32 v150, v162
	s_add_i32 m0, s19, 0x800
	s_add_u32 s100, s64, s68
	s_addc_u32 s101, s65, s69
	global_load_lds_dwordx4 v162, s[100:101]
	s_add_i32 s19, s18, 1
	v_mfma_f32_16x16x32_bf16 v[28:31], v[112:115], v[104:107], v[28:31]
	s_cmp_lg_u32 s18, 2
	s_cselect_b32 s18, s19, 0
	s_add_u32 s4, s4, 0x80
	v_mfma_f32_16x16x32_bf16 v[24:27], v[116:119], v[104:107], v[24:27]
	s_addc_u32 s5, s5, 0
	s_cmpk_eq_i32 s4, 0x680
	v_mfma_f32_16x16x32_bf16 v[20:23], v[120:123], v[104:107], v[20:23]
	v_mfma_f32_16x16x32_bf16 v[16:19], v[124:127], v[104:107], v[16:19]
	v_mfma_f32_16x16x32_bf16 v[12:15], v[112:115], v[108:111], v[12:15]
	v_mfma_f32_16x16x32_bf16 v[8:11], v[116:119], v[108:111], v[8:11]
	v_mfma_f32_16x16x32_bf16 v[4:7], v[120:123], v[108:111], v[4:7]
	v_mfma_f32_16x16x32_bf16 v[60:63], v[124:127], v[108:111], v[60:63]
	s_cbranch_scc0 .LBB0_486
	s_waitcnt vmcnt(6) lgkmcnt(0)
	s_barrier
	s_mul_i32 s4, s18, 0xc000
	s_add_i32 s4, s4, 0
	v_add_u32_e32 v64, s4, v157
	v_add3_u32 v65, v64, s25, v169
	v_add3_u32 v64, v64, s24, v169
	v_add_u32_e32 v68, s4, v158
	ds_read_b128 v[124:127], v65
	ds_read_b128 v[120:123], v65 offset:2048
	ds_read_b128 v[96:99], v65 offset:4096
	ds_read_b128 v[92:95], v65 offset:6144
	ds_read_b128 v[108:111], v64 offset:32768
	ds_read_b128 v[112:115], v64 offset:34816
	ds_read_b128 v[116:119], v64 offset:36864
	ds_read_b128 v[100:103], v64 offset:38912
	v_add3_u32 v64, v68, s25, v169
	v_add3_u32 v68, v68, s24, v169
	ds_read_b128 v[88:91], v64
	ds_read_b128 v[104:107], v64 offset:2048
	ds_read_b128 v[72:75], v64 offset:4096
	ds_read_b128 v[64:67], v64 offset:6144
	ds_read_b128 v[76:79], v68 offset:32768
	ds_read_b128 v[80:83], v68 offset:34816
	ds_read_b128 v[84:87], v68 offset:36864
	ds_read_b128 v[68:71], v68 offset:38912
	s_waitcnt lgkmcnt(0)
	v_sub_co_u32_e64 v128, s[4:5], s18, 1
	s_and_b64 s[4:5], s[4:5], exec
	v_readfirstlane_b32 s4, v128
	s_cselect_b32 s29, 2, s4
	v_cndmask_b32_e64 v128, 0, 1, s[86:87]
	s_mov_b64 s[4:5], -1
	v_cmp_ne_u32_e64 s[6:7], 1, v128
	s_andn2_b64 vcc, exec, s[86:87]
	s_mul_i32 s26, s29, 0xc000
	s_cbranch_vccnz .LBB0_489
	s_mul_i32 s19, s29, 0xc000
	s_mov_b64 s[4:5], 0

.LBB0_640:
	s_waitcnt vmcnt(6) lgkmcnt(0)
	s_barrier
	s_waitcnt lgkmcnt(0)
	v_mfma_f32_16x16x32_bf16 v[124:127], v[52:55], v[64:67], v[124:127]
	s_mul_i32 s86, s97, 0xc000
	s_add_i32 s87, s86, 0xffff4000
	v_mfma_f32_16x16x32_bf16 v[120:123], v[48:51], v[64:67], v[120:123]
	s_cmp_lg_u32 s97, 0
	s_cselect_b32 s87, s87, 0x18000
	s_add_i32 s84, s3, s87
	v_mfma_f32_16x16x32_bf16 v[116:119], v[44:47], v[64:67], v[116:119]
	v_mfma_f32_16x16x32_bf16 v[64:67], v[40:43], v[64:67], v[112:115]
	v_mfma_f32_16x16x32_bf16 v[108:111], v[52:55], v[56:59], v[108:111]
	v_mfma_f32_16x16x32_bf16 v[104:107], v[48:51], v[56:59], v[104:107]
	v_mfma_f32_16x16x32_bf16 v[100:103], v[44:47], v[56:59], v[100:103]
	v_mfma_f32_16x16x32_bf16 v[56:59], v[40:43], v[56:59], v[96:99]
	s_add_u32 s88, s10, s6
	v_mov_b32_e32 v150, v178
	s_addc_u32 s89, s11, s7
	s_mov_b32 m0, s84
	s_add_u32 s98, s88, s72
	s_addc_u32 s99, s89, s73
	global_load_lds_dwordx4 v178, s[98:99]
	v_mfma_f32_16x16x32_bf16 v[92:95], v[52:55], v[36:39], v[92:95]
	v_mfma_f32_16x16x32_bf16 v[88:91], v[48:51], v[36:39], v[88:91]
	v_mfma_f32_16x16x32_bf16 v[84:87], v[44:47], v[36:39], v[84:87]
	v_mfma_f32_16x16x32_bf16 v[36:39], v[40:43], v[36:39], v[80:83]
	v_mfma_f32_16x16x32_bf16 v[52:55], v[52:55], v[32:35], v[76:79]
	v_mfma_f32_16x16x32_bf16 v[48:51], v[48:51], v[32:35], v[72:75]
	v_mfma_f32_16x16x32_bf16 v[44:47], v[44:47], v[32:35], v[68:71]
	v_mfma_f32_16x16x32_bf16 v[32:35], v[40:43], v[32:35], v[60:63]
	v_mov_b32_e32 v150, v179
	s_add_i32 m0, s84, 0x400
	s_add_u32 s100, s88, s74
	s_addc_u32 s101, s89, s75
	global_load_lds_dwordx4 v179, s[100:101]
	v_mfma_f32_16x16x32_bf16 v[124:127], v[20:23], v[28:31], v[124:127]
	v_mfma_f32_16x16x32_bf16 v[120:123], v[16:19], v[28:31], v[120:123]
	v_mfma_f32_16x16x32_bf16 v[116:119], v[12:15], v[28:31], v[116:119]
	v_mfma_f32_16x16x32_bf16 v[112:115], v[8:11], v[28:31], v[64:67]
	v_mfma_f32_16x16x32_bf16 v[108:111], v[20:23], v[24:27], v[108:111]
	v_mfma_f32_16x16x32_bf16 v[104:107], v[16:19], v[24:27], v[104:107]
	v_mfma_f32_16x16x32_bf16 v[100:103], v[12:15], v[24:27], v[100:103]
	v_mfma_f32_16x16x32_bf16 v[96:99], v[8:11], v[24:27], v[56:59]
	v_mov_b32_e32 v150, v178
	s_add_i32 m0, s84, 0x800
	s_add_u32 s98, s88, s76
	s_addc_u32 s99, s89, s77
	global_load_lds_dwordx4 v178, s[98:99]
	v_mfma_f32_16x16x32_bf16 v[92:95], v[20:23], v[4:7], v[92:95]
	s_waitcnt lgkmcnt(0)
	v_mfma_f32_16x16x32_bf16 v[88:91], v[16:19], v[4:7], v[88:91]
	v_mfma_f32_16x16x32_bf16 v[84:87], v[12:15], v[4:7], v[84:87]
	v_mfma_f32_16x16x32_bf16 v[80:83], v[8:11], v[4:7], v[36:39]
	v_mfma_f32_16x16x32_bf16 v[76:79], v[20:23], v[0:3], v[52:55]
	v_mfma_f32_16x16x32_bf16 v[72:75], v[16:19], v[0:3], v[48:51]
	v_mfma_f32_16x16x32_bf16 v[68:71], v[12:15], v[0:3], v[44:47]
	v_mfma_f32_16x16x32_bf16 v[60:63], v[8:11], v[0:3], v[32:35]
	s_barrier
	s_add_i32 s84, s86, 0
	v_add_u32_e32 v0, s84, v157
	v_add_u32_e32 v8, s84, v158
	s_add_i32 s84, s87, 0
	s_add_i32 s85, s84, s2
	s_add_i32 m0, s85, 0xc00
	s_add_u32 s100, s88, s78
	s_addc_u32 s101, s89, s79
	s_add_u32 s88, vcc_lo, s6
	s_addc_u32 s89, vcc_hi, s7
	global_load_lds_dwordx4 v179, s[100:101]
	s_add_i32 s84, s84, s16
	s_add_i32 m0, s84, 0x8000
	s_add_u32 s98, s88, s80
	s_addc_u32 s99, s89, s81
	global_load_lds_dwordx4 v178, s[98:99]
	s_add_i32 m0, s84, 0x8400
	s_add_u32 s100, s88, s82
	s_addc_u32 s101, s89, s83
	global_load_lds_dwordx4 v179, s[100:101]
	v_add3_u32 v1, v0, s18, v169
	v_add3_u32 v0, v0, s17, v169
	ds_read_b128 v[64:67], v1
	ds_read_b128 v[56:59], v1 offset:2048
	ds_read_b128 v[36:39], v1 offset:4096
	ds_read_b128 v[32:35], v1 offset:6144
	ds_read_b128 v[52:55], v0 offset:32768
	ds_read_b128 v[48:51], v0 offset:34816
	ds_read_b128 v[44:47], v0 offset:36864
	ds_read_b128 v[40:43], v0 offset:38912
	v_add3_u32 v0, v8, s18, v169
	v_add3_u32 v8, v8, s17, v169
	ds_read_b128 v[28:31], v0
	ds_read_b128 v[24:27], v0 offset:2048
	ds_read_b128 v[4:7], v0 offset:4096
	ds_read_b128 v[0:3], v0 offset:6144
	ds_read_b128 v[20:23], v8 offset:32768
	ds_read_b128 v[16:19], v8 offset:34816
	ds_read_b128 v[12:15], v8 offset:36864
	ds_read_b128 v[8:11], v8 offset:38912
	s_waitcnt lgkmcnt(0)
	v_mov_b32_e32 v150, v179
	v_mov_b32_e32 v150, v178
	v_mov_b32_e32 v150, v179
	s_add_i32 s84, s97, 1
	s_cmp_lg_u32 s97, 2
	s_cselect_b32 s97, s84, 0
	s_add_u32 s6, s6, 0x80
	s_addc_u32 s7, s7, 0
	s_cmpk_eq_i32 s6, 0x680
	s_cbranch_scc0 .LBB0_640
	s_waitcnt vmcnt(6) lgkmcnt(0)
	s_barrier
	s_waitcnt lgkmcnt(0)
	v_mfma_f32_16x16x32_bf16 v[124:127], v[52:55], v[64:67], v[124:127]
	s_mul_i32 s11, s97, 0xc000
	s_add_i32 s6, s11, 0xffff4000
	v_mfma_f32_16x16x32_bf16 v[120:123], v[48:51], v[64:67], v[120:123]
	s_cmp_lg_u32 s97, 0
	s_cselect_b32 s10, s6, 0x18000
	s_andn2_b64 vcc, exec, s[94:95]
	v_mfma_f32_16x16x32_bf16 v[116:119], v[44:47], v[64:67], v[116:119]
	v_mfma_f32_16x16x32_bf16 v[64:67], v[40:43], v[64:67], v[112:115]
	v_mfma_f32_16x16x32_bf16 v[108:111], v[52:55], v[56:59], v[108:111]
	s_nop 1
	v_cndmask_b32_e64 v112, 0, 1, s[94:95]
	v_cmp_ne_u32_e64 s[6:7], 1, v112
	v_mfma_f32_16x16x32_bf16 v[104:107], v[48:51], v[56:59], v[104:107]
	v_mfma_f32_16x16x32_bf16 v[100:103], v[44:47], v[56:59], v[100:103]
	v_mfma_f32_16x16x32_bf16 v[140:143], v[40:43], v[56:59], v[96:99]
	s_cbranch_vccnz .LBB0_643
	s_add_u32 s88, s64, s14
	v_mov_b32_e32 v56, v178
	s_addc_u32 s89, s65, s15
	s_add_i32 m0, s3, s10
	s_nop 0
	global_load_lds_dwordx4 v56, s[88:89]

.LBB0_667:
	s_waitcnt vmcnt(6) lgkmcnt(0)
	s_barrier
	s_mul_i32 s13, s10, 0xc000
	s_add_i32 s20, s13, 0
	v_add_u32_e32 v80, s20, v157
	v_add_u32_e32 v112, s20, v158
	s_add_i32 s13, s13, 0xffff4000
	s_cmp_lg_u32 s10, 0
	s_cselect_b32 s13, s13, 0x18000
	s_add_i32 s88, s13, 0
	s_add_u32 s20, s6, s4
	s_addc_u32 s21, s7, s5
	s_add_i32 s66, s88, s2
	s_add_i32 m0, s66, 0xc00
	s_add_u32 s66, s11, s4
	s_addc_u32 s67, s12, s5
	s_add_u32 s98, s20, s78
	s_addc_u32 s99, s21, s79
	global_load_lds_dwordx4 v179, s[98:99]
	s_add_i32 s88, s88, s16
	s_add_i32 m0, s88, 0x8000
	s_add_u32 s100, s66, s80
	s_addc_u32 s101, s67, s81
	global_load_lds_dwordx4 v178, s[100:101]
	s_add_i32 m0, s88, 0x8400
	s_add_u32 s98, s66, s82
	s_addc_u32 s99, s67, s83
	global_load_lds_dwordx4 v179, s[98:99]
	v_add3_u32 v76, v80, s18, v169
	v_add3_u32 v92, v80, s17, v169
	v_add3_u32 v108, v112, s18, v169
	v_add3_u32 v124, v112, s17, v169
	ds_read_b128 v[64:67], v76
	ds_read_b128 v[68:71], v76 offset:2048
	ds_read_b128 v[72:75], v76 offset:4096
	ds_read_b128 v[76:79], v76 offset:6144
	ds_read_b128 v[80:83], v92 offset:32768
	ds_read_b128 v[84:87], v92 offset:34816
	ds_read_b128 v[88:91], v92 offset:36864
	ds_read_b128 v[92:95], v92 offset:38912
	ds_read_b128 v[96:99], v108
	ds_read_b128 v[100:103], v108 offset:2048
	ds_read_b128 v[104:107], v108 offset:4096
	ds_read_b128 v[108:111], v108 offset:6144
	ds_read_b128 v[112:115], v124 offset:32768
	ds_read_b128 v[116:119], v124 offset:34816
	ds_read_b128 v[120:123], v124 offset:36864
	ds_read_b128 v[124:127], v124 offset:38912
	s_waitcnt lgkmcnt(0)
	v_mov_b32_e32 v150, v179
	v_mov_b32_e32 v150, v178
	v_mov_b32_e32 v150, v179
	s_waitcnt lgkmcnt(0)
	s_barrier
	s_waitcnt lgkmcnt(0)
	v_mfma_f32_16x16x32_bf16 v[60:63], v[80:83], v[64:67], v[60:63]
	s_add_i32 s13, s3, s13
	v_mfma_f32_16x16x32_bf16 v[56:59], v[84:87], v[64:67], v[56:59]
	v_mfma_f32_16x16x32_bf16 v[52:55], v[88:91], v[64:67], v[52:55]
	v_mfma_f32_16x16x32_bf16 v[48:51], v[92:95], v[64:67], v[48:51]
	v_mfma_f32_16x16x32_bf16 v[44:47], v[80:83], v[68:71], v[44:47]
	v_mfma_f32_16x16x32_bf16 v[40:43], v[84:87], v[68:71], v[40:43]
	v_mfma_f32_16x16x32_bf16 v[36:39], v[88:91], v[68:71], v[36:39]
	v_mfma_f32_16x16x32_bf16 v[24:27], v[92:95], v[68:71], v[24:27]
	v_mov_b32_e32 v150, v178
	s_mov_b32 m0, s13
	s_add_u32 s100, s20, s72
	s_addc_u32 s101, s21, s73
	global_load_lds_dwordx4 v178, s[100:101]
	v_mfma_f32_16x16x32_bf16 v[20:23], v[80:83], v[72:75], v[20:23]
	v_mfma_f32_16x16x32_bf16 v[16:19], v[84:87], v[72:75], v[16:19]
	v_mfma_f32_16x16x32_bf16 v[12:15], v[88:91], v[72:75], v[12:15]
	v_mfma_f32_16x16x32_bf16 v[8:11], v[92:95], v[72:75], v[8:11]
	v_mfma_f32_16x16x32_bf16 v[4:7], v[80:83], v[76:79], v[4:7]
	v_mfma_f32_16x16x32_bf16 v[0:3], v[84:87], v[76:79], v[0:3]
	v_mfma_f32_16x16x32_bf16 v[28:31], v[88:91], v[76:79], v[28:31]
	v_mfma_f32_16x16x32_bf16 v[32:35], v[92:95], v[76:79], v[32:35]
	v_mov_b32_e32 v150, v179
	s_add_i32 m0, s13, 0x400
	s_add_u32 s98, s20, s74
	s_addc_u32 s99, s21, s75
	global_load_lds_dwordx4 v179, s[98:99]
	v_mfma_f32_16x16x32_bf16 v[60:63], v[112:115], v[96:99], v[60:63]
	v_mfma_f32_16x16x32_bf16 v[56:59], v[116:119], v[96:99], v[56:59]
	v_mfma_f32_16x16x32_bf16 v[52:55], v[120:123], v[96:99], v[52:55]
	v_mfma_f32_16x16x32_bf16 v[48:51], v[124:127], v[96:99], v[48:51]
	v_mfma_f32_16x16x32_bf16 v[44:47], v[112:115], v[100:103], v[44:47]
	v_mfma_f32_16x16x32_bf16 v[40:43], v[116:119], v[100:103], v[40:43]
	v_mfma_f32_16x16x32_bf16 v[36:39], v[120:123], v[100:103], v[36:39]
	v_mfma_f32_16x16x32_bf16 v[24:27], v[124:127], v[100:103], v[24:27]
	v_mov_b32_e32 v150, v178
	s_add_i32 m0, s13, 0x800
	s_add_u32 s100, s20, s76
	s_addc_u32 s101, s21, s77
	global_load_lds_dwordx4 v178, s[100:101]
	s_add_i32 s13, s10, 1
	v_mfma_f32_16x16x32_bf16 v[20:23], v[112:115], v[104:107], v[20:23]
	s_cmp_lg_u32 s10, 2
	s_cselect_b32 s10, s13, 0
	s_add_u32 s4, s4, 0x80
	v_mfma_f32_16x16x32_bf16 v[16:19], v[116:119], v[104:107], v[16:19]
	s_addc_u32 s5, s5, 0
	s_cmpk_eq_i32 s4, 0x680
	v_mfma_f32_16x16x32_bf16 v[12:15], v[120:123], v[104:107], v[12:15]
	v_mfma_f32_16x16x32_bf16 v[8:11], v[124:127], v[104:107], v[8:11]
	v_mfma_f32_16x16x32_bf16 v[4:7], v[112:115], v[108:111], v[4:7]
	v_mfma_f32_16x16x32_bf16 v[0:3], v[116:119], v[108:111], v[0:3]
	v_mfma_f32_16x16x32_bf16 v[28:31], v[120:123], v[108:111], v[28:31]
	v_mfma_f32_16x16x32_bf16 v[32:35], v[124:127], v[108:111], v[32:35]
	s_cbranch_scc0 .LBB0_667
	s_waitcnt vmcnt(6) lgkmcnt(0)
	s_barrier
	s_mul_i32 s4, s10, 0xc000
	s_add_i32 s4, s4, 0
	v_add_u32_e32 v64, s4, v157
	v_add3_u32 v65, v64, s18, v169
	v_add3_u32 v64, v64, s17, v169
	v_add_u32_e32 v68, s4, v158
	ds_read_b128 v[124:127], v65
	ds_read_b128 v[120:123], v65 offset:2048
	ds_read_b128 v[100:103], v65 offset:4096
	ds_read_b128 v[96:99], v65 offset:6144
	ds_read_b128 v[108:111], v64 offset:32768
	ds_read_b128 v[112:115], v64 offset:34816
	ds_read_b128 v[116:119], v64 offset:36864
	ds_read_b128 v[104:107], v64 offset:38912
	v_add3_u32 v64, v68, s18, v169
	v_add3_u32 v68, v68, s17, v169
	ds_read_b128 v[92:95], v64
	ds_read_b128 v[88:91], v64 offset:2048
	ds_read_b128 v[72:75], v64 offset:4096
	ds_read_b128 v[64:67], v64 offset:6144
	ds_read_b128 v[76:79], v68 offset:32768
	ds_read_b128 v[80:83], v68 offset:34816
	ds_read_b128 v[84:87], v68 offset:36864
	ds_read_b128 v[68:71], v68 offset:38912
	s_waitcnt lgkmcnt(0)
	v_sub_co_u32_e64 v128, s[4:5], s10, 1
	s_and_b64 s[4:5], s[4:5], exec
	v_readfirstlane_b32 s4, v128
	s_cselect_b32 s13, 2, s4
	v_cndmask_b32_e64 v128, 0, 1, s[90:91]
	s_mov_b64 s[4:5], -1
	v_cmp_ne_u32_e64 s[6:7], 1, v128
	s_andn2_b64 vcc, exec, s[90:91]
	s_mul_i32 s12, s13, 0xc000
	s_cbranch_vccnz .LBB0_670
	s_mul_i32 s11, s13, 0xc000
	s_mov_b64 s[4:5], 0

.LBB0_693:
	v_readlane_b32 s78, v219, 30
	s_nop 3
	s_cmpk_lt_u32 s78, 0x80
	s_cbranch_scc1 .Lgu0h_skip
	v_writelane_b32 v220, s0, 0
	v_writelane_b32 v220, s1, 1
	v_writelane_b32 v220, s2, 2
	v_writelane_b32 v220, s3, 3
	v_writelane_b32 v220, s4, 4
	v_writelane_b32 v220, s5, 5
	v_writelane_b32 v220, s6, 6
	v_writelane_b32 v220, s7, 7
	v_writelane_b32 v220, s8, 8
	v_writelane_b32 v220, s9, 9
	v_writelane_b32 v220, s10, 10
	v_writelane_b32 v220, s11, 11
	v_writelane_b32 v220, s12, 12
	v_writelane_b32 v220, s13, 13
	v_writelane_b32 v220, s14, 14
	v_writelane_b32 v220, s15, 15
	v_writelane_b32 v220, s16, 16
	v_writelane_b32 v220, s17, 17
	v_writelane_b32 v220, s18, 18
	v_writelane_b32 v220, s19, 19
	v_writelane_b32 v220, s20, 20
	v_writelane_b32 v220, s21, 21
	v_writelane_b32 v220, s22, 22
	v_writelane_b32 v220, s23, 23
	v_writelane_b32 v220, s24, 24
	v_writelane_b32 v220, s25, 25
	v_writelane_b32 v220, s26, 26
	v_writelane_b32 v220, s27, 27
	v_writelane_b32 v220, s36, 28
	v_writelane_b32 v220, s37, 29
	v_writelane_b32 v220, s38, 30
	v_writelane_b32 v220, s39, 31
	v_writelane_b32 v220, s40, 32
	v_writelane_b32 v220, s41, 33
	v_writelane_b32 v220, s42, 34
	v_writelane_b32 v220, s43, 35
	v_writelane_b32 v220, s44, 36
	v_writelane_b32 v220, s45, 37
	v_writelane_b32 v220, s46, 38
	v_writelane_b32 v220, s47, 39
	v_writelane_b32 v220, s48, 40
	v_writelane_b32 v220, s49, 41
	v_writelane_b32 v220, s50, 42
	v_writelane_b32 v220, s51, 43
	s_cmpk_gt_i32 s78, 0x17f
	s_waitcnt vmcnt(0) lgkmcnt(0)
	s_barrier
	s_cbranch_scc1 .Lgu0h_BB0_1034
	s_movk_i32 s1, 0x2100
	v_and_b32_e32 v4, 56, v144
	v_mad_u32_u24 v1, v148, s1, 0
	v_lshrrev_b32_e32 v0, 5, v149
	v_and_b32_e32 v2, 31, v168
	v_mul_u32_u24_e32 v3, 0x84, v4
	v_lshlrev_b32_e32 v7, 2, v185
	s_add_i32 s0, s78, 0x290
	s_cmpk_lt_u32 s78, 0xe0
	s_cbranch_scc1 .Lgu0h_init_done
	s_add_i32 s0, s78, 0x390
.Lgu0h_init_done:
	v_mov_b32_e32 v5, 0
	v_lshl_add_u32 v6, v2, 2, v1
	s_movk_i32 s1, 0x84
	v_add3_u32 v20, v1, v3, v7
	v_or_b32_e32 v21, 8, v185
	v_or_b32_e32 v22, 16, v185
	v_or_b32_e32 v23, 24, v185
	v_mov_b32_e32 v1, v0
	s_movk_i32 s2, 0x187f
	v_mov_b32_e32 v24, 0xffffe780
	v_mov_b32_e32 v25, 0xc00
	v_mov_b32_e32 v26, 0x600
	s_movk_i32 s3, 0x1ff
	s_movk_i32 s4, 0xcff
	v_lshlrev_b32_e32 v8, 2, v2
	v_lshlrev_b32_e32 v10, 1, v4
	v_mov_b32_e32 v27, 0x2c0000
	v_mov_b32_e32 v28, 0x1400000
	v_mov_b32_e32 v29, 0x2980000
	v_mov_b32_e32 v30, 0x900000
	v_mov_b32_e32 v31, 0x1e80000
	v_mov_b32_e32 v32, 0x700000
	v_mov_b32_e32 v33, 0x1c80000
	v_mov_b32_e32 v34, 0x100000
	v_mov_b32_e32 v35, 0x1980000

.Lgu0h_BB0_1032:
	s_lshl_b32 s8, s6, 1
	s_lshl_b32 s9, s5, 1
	v_or_b32_e32 v9, s8, v1
	v_or_b32_e32 v11, s9, v0
	s_add_i32 s10, s8, 4
	s_add_i32 s11, s9, 4
	s_add_i32 s12, s8, 8
	s_add_i32 s13, s9, 8
	s_add_i32 s14, s8, 12
	s_add_i32 s15, s9, 12
	s_add_i32 s16, s8, 16
	s_add_i32 s17, s9, 16
	s_add_i32 s18, s8, 20
	s_add_i32 s19, s9, 20
	s_add_i32 s20, s8, 24
	s_add_i32 s21, s9, 24
	s_add_i32 s8, s8, 28
	s_add_i32 s9, s9, 28
	v_add_u32_e32 v17, v9, v7
	v_add_u32_e32 v37, v11, v16
	v_or_b32_e32 v70, s10, v1
	v_or_b32_e32 v71, s11, v0
	v_or_b32_e32 v72, s12, v1
	v_or_b32_e32 v73, s13, v0
	v_or_b32_e32 v74, s14, v1
	v_or_b32_e32 v75, s15, v0
	v_or_b32_e32 v76, s16, v1
	v_or_b32_e32 v77, s17, v0
	v_or_b32_e32 v78, s18, v1
	v_or_b32_e32 v79, s19, v0
	v_or_b32_e32 v80, s20, v1
	v_or_b32_e32 v81, s21, v0
	v_or_b32_e32 v82, s8, v1
	v_or_b32_e32 v83, s9, v0
	v_ashrrev_i32_e32 v42, 31, v37
	v_ashrrev_i32_e32 v43, 31, v17
	v_mul_lo_u32 v84, v3, v17
	v_mad_u64_u32 v[38:39], s[8:9], v2, v17, 0
	v_mul_lo_u32 v17, v13, v37
	v_mad_u64_u32 v[40:41], s[8:9], v12, v37, 0
	v_add_u32_e32 v37, v70, v7
	v_add_u32_e32 v44, v71, v16
	v_add_u32_e32 v46, v72, v7
	v_add_u32_e32 v48, v73, v16
	v_add_u32_e32 v50, v74, v7
	v_add_u32_e32 v52, v75, v16
	v_add_u32_e32 v54, v76, v7
	v_add_u32_e32 v56, v77, v16
	v_add_u32_e32 v58, v78, v7
	v_add_u32_e32 v60, v79, v16
	v_add_u32_e32 v62, v80, v7
	v_add_u32_e32 v64, v81, v16
	v_add_u32_e32 v66, v82, v7
	v_add_u32_e32 v68, v83, v16
	v_mul_lo_u32 v85, v2, v43
	v_mul_lo_u32 v86, v12, v42
	v_ashrrev_i32_e32 v87, 31, v44
	v_ashrrev_i32_e32 v88, 31, v37
	v_ashrrev_i32_e32 v90, 31, v48
	v_ashrrev_i32_e32 v91, 31, v46
	v_ashrrev_i32_e32 v94, 31, v52
	v_ashrrev_i32_e32 v95, 31, v50
	v_ashrrev_i32_e32 v98, 31, v56
	v_ashrrev_i32_e32 v99, 31, v54
	v_ashrrev_i32_e32 v102, 31, v60
	v_ashrrev_i32_e32 v103, 31, v58
	v_ashrrev_i32_e32 v106, 31, v64
	v_ashrrev_i32_e32 v107, 31, v62
	v_ashrrev_i32_e32 v110, 31, v68
	v_ashrrev_i32_e32 v111, 31, v66
	v_mul_lo_u32 v89, v3, v37
	v_mad_u64_u32 v[42:43], s[8:9], v2, v37, 0
	v_mul_lo_u32 v37, v13, v44
	v_mad_u64_u32 v[44:45], s[8:9], v12, v44, 0
	v_mul_lo_u32 v92, v3, v46
	v_mad_u64_u32 v[46:47], s[8:9], v2, v46, 0
	v_mul_lo_u32 v93, v13, v48
	v_mad_u64_u32 v[48:49], s[8:9], v12, v48, 0
	v_mul_lo_u32 v96, v3, v50
	v_mad_u64_u32 v[50:51], s[8:9], v2, v50, 0
	v_mul_lo_u32 v97, v13, v52
	v_mad_u64_u32 v[52:53], s[8:9], v12, v52, 0
	v_mul_lo_u32 v100, v3, v54
	v_mad_u64_u32 v[54:55], s[8:9], v2, v54, 0
	v_mul_lo_u32 v101, v13, v56
	v_mad_u64_u32 v[56:57], s[8:9], v12, v56, 0
	v_mul_lo_u32 v104, v3, v58
	v_mad_u64_u32 v[58:59], s[8:9], v2, v58, 0
	v_mul_lo_u32 v105, v13, v60
	v_mad_u64_u32 v[60:61], s[8:9], v12, v60, 0
	v_mul_lo_u32 v108, v3, v62
	v_mad_u64_u32 v[62:63], s[8:9], v2, v62, 0
	v_mul_lo_u32 v109, v13, v64
	v_mad_u64_u32 v[64:65], s[8:9], v12, v64, 0
	v_mul_lo_u32 v112, v3, v66
	v_mad_u64_u32 v[66:67], s[8:9], v2, v66, 0
	v_mul_lo_u32 v113, v13, v68
	v_mad_u64_u32 v[68:69], s[8:9], v12, v68, 0
	v_add3_u32 v39, v39, v85, v84
	v_add3_u32 v41, v41, v86, v17
	v_mul_lo_u32 v17, v2, v88
	v_mul_lo_u32 v84, v12, v87
	v_mul_lo_u32 v85, v2, v91
	v_mul_lo_u32 v86, v12, v90
	v_mul_lo_u32 v87, v2, v95
	v_mul_lo_u32 v88, v12, v94
	v_mul_lo_u32 v90, v2, v99
	v_mul_lo_u32 v91, v12, v98
	v_mul_lo_u32 v94, v2, v103
	v_mul_lo_u32 v95, v12, v102
	v_mul_lo_u32 v98, v2, v107
	v_mul_lo_u32 v99, v12, v106
	v_mul_lo_u32 v102, v2, v111
	v_mul_lo_u32 v103, v12, v110
	v_lshl_add_u64 v[40:41], v[40:41], 2, v[18:19]
	v_add3_u32 v43, v43, v17, v89
	v_add3_u32 v45, v45, v84, v37
	v_add3_u32 v47, v47, v85, v92
	v_add3_u32 v49, v49, v86, v93
	v_add3_u32 v51, v51, v87, v96
	v_add3_u32 v53, v53, v88, v97
	v_add3_u32 v55, v55, v90, v100
	v_add3_u32 v57, v57, v91, v101
	v_add3_u32 v59, v59, v94, v104
	v_add3_u32 v61, v61, v95, v105
	v_add3_u32 v63, v63, v98, v108
	v_add3_u32 v65, v65, v99, v109
	v_add3_u32 v67, v67, v102, v112
	v_add3_u32 v69, v69, v103, v113
	v_lshl_add_u64 v[38:39], v[38:39], 2, v[18:19]
	v_lshl_add_u64 v[44:45], v[44:45], 2, v[18:19]
	v_lshl_add_u64 v[42:43], v[42:43], 2, v[18:19]
	v_lshl_add_u64 v[48:49], v[48:49], 2, v[18:19]
	v_lshl_add_u64 v[46:47], v[46:47], 2, v[18:19]
	v_lshl_add_u64 v[52:53], v[52:53], 2, v[18:19]
	v_lshl_add_u64 v[50:51], v[50:51], 2, v[18:19]
	v_lshl_add_u64 v[56:57], v[56:57], 2, v[18:19]
	v_lshl_add_u64 v[54:55], v[54:55], 2, v[18:19]
	v_lshl_add_u64 v[60:61], v[60:61], 2, v[18:19]
	v_lshl_add_u64 v[58:59], v[58:59], 2, v[18:19]
	v_lshl_add_u64 v[64:65], v[64:65], 2, v[18:19]
	v_lshl_add_u64 v[62:63], v[62:63], 2, v[18:19]
	v_lshl_add_u64 v[68:69], v[68:69], 2, v[18:19]
	v_lshl_add_u64 v[66:67], v[66:67], 2, v[18:19]
	global_load_dword v17, v[40:41], off
	global_load_dword v37, v[38:39], off
	global_load_dword v84, v[44:45], off
	global_load_dword v85, v[42:43], off
	global_load_dword v86, v[48:49], off
	global_load_dword v87, v[46:47], off
	global_load_dword v88, v[52:53], off
	global_load_dword v89, v[50:51], off
	global_load_dword v90, v[56:57], off
	global_load_dword v91, v[54:55], off
	global_load_dword v92, v[60:61], off
	global_load_dword v93, v[58:59], off
	global_load_dword v94, v[64:65], off
	global_load_dword v95, v[62:63], off
	global_load_dword v96, v[68:69], off
	global_load_dword v97, v[66:67], off
	s_add_i32 s5, s5, 16
	s_add_i32 s6, s6, 16
	s_add_i32 s7, s7, -16
	v_mad_u64_u32 v[38:39], s[8:9], v11, s1, v[6:7]
	s_cmp_lg_u32 s7, 0
	v_mad_u64_u32 v[40:41], s[8:9], v9, s1, v[6:7]
	v_mad_u64_u32 v[42:43], s[8:9], v71, s1, v[6:7]
	v_mad_u64_u32 v[44:45], s[8:9], v70, s1, v[6:7]
	v_mad_u64_u32 v[46:47], s[8:9], v73, s1, v[6:7]
	v_mad_u64_u32 v[48:49], s[8:9], v72, s1, v[6:7]
	v_mad_u64_u32 v[50:51], s[8:9], v75, s1, v[6:7]
	v_mad_u64_u32 v[52:53], s[8:9], v74, s1, v[6:7]
	v_mad_u64_u32 v[54:55], s[8:9], v77, s1, v[6:7]
	v_mad_u64_u32 v[56:57], s[8:9], v76, s1, v[6:7]
	v_mad_u64_u32 v[58:59], s[8:9], v79, s1, v[6:7]
	v_mad_u64_u32 v[60:61], s[8:9], v78, s1, v[6:7]
	v_mad_u64_u32 v[62:63], s[8:9], v81, s1, v[6:7]
	v_mad_u64_u32 v[64:65], s[8:9], v80, s1, v[6:7]
	v_mad_u64_u32 v[66:67], s[8:9], v83, s1, v[6:7]
	v_mad_u64_u32 v[68:69], s[8:9], v82, s1, v[6:7]
	s_waitcnt vmcnt(15)
	ds_write_b32 v38, v17
	s_waitcnt vmcnt(14)
	ds_write_b32 v40, v37
	s_waitcnt vmcnt(13)
	ds_write_b32 v42, v84
	s_waitcnt vmcnt(12)
	ds_write_b32 v44, v85
	s_waitcnt vmcnt(11)
	ds_write_b32 v46, v86
	s_waitcnt vmcnt(10)
	ds_write_b32 v48, v87
	s_waitcnt vmcnt(9)
	ds_write_b32 v50, v88
	s_waitcnt vmcnt(8)
	ds_write_b32 v52, v89
	s_waitcnt vmcnt(7)
	ds_write_b32 v54, v90
	s_waitcnt vmcnt(6)
	ds_write_b32 v56, v91
	s_waitcnt vmcnt(5)
	ds_write_b32 v58, v92
	s_waitcnt vmcnt(4)
	ds_write_b32 v60, v93
	s_waitcnt vmcnt(3)
	ds_write_b32 v62, v94
	s_waitcnt vmcnt(2)
	ds_write_b32 v64, v95
	s_waitcnt vmcnt(1)
	ds_write_b32 v66, v96
	s_waitcnt vmcnt(0)
	ds_write_b32 v68, v97
	s_cbranch_scc1 .Lgu0h_BB0_1032
	s_waitcnt lgkmcnt(0)
	v_ashrrev_i32_e32 v17, 31, v16
	v_lshl_add_u64 v[2:3], v[16:17], 1, v[14:15]
	ds_read2_b32 v[16:17], v20 offset0:33 offset1:41
	ds_read2_b32 v[18:19], v20 offset1:8
	ds_read2_b32 v[38:39], v20 offset0:66 offset1:74
	ds_read2_b32 v[40:41], v20 offset0:99 offset1:107
	ds_read2_b32 v[42:43], v20 offset0:132 offset1:140
	ds_read2_b32 v[44:45], v20 offset0:165 offset1:173
	ds_read2_b32 v[46:47], v20 offset0:198 offset1:206
	ds_read2_b32 v[48:49], v20 offset0:231 offset1:239
	v_or_b32_e32 v7, v4, v185
	v_ashrrev_i32_e32 v9, 31, v4
	v_mov_b32_e32 v11, v5
	v_mul_lo_u32 v9, v9, v36
	v_mad_u64_u32 v[50:51], s[6:7], v7, v36, 0
	v_lshl_add_u64 v[2:3], v[2:3], 0, v[10:11]
	v_add_u32_e32 v51, v51, v9
	s_waitcnt lgkmcnt(6)
	v_cvt_pk_bf16_f32 v12, v18, v16
	s_waitcnt lgkmcnt(4)
	v_cvt_pk_bf16_f32 v13, v38, v40
	s_waitcnt lgkmcnt(2)
	v_cvt_pk_bf16_f32 v14, v42, v44
	s_waitcnt lgkmcnt(0)
	v_cvt_pk_bf16_f32 v15, v46, v48
	v_lshl_add_u64 v[50:51], v[50:51], 1, v[2:3]
	global_store_dwordx4 v[50:51], v[12:15], off
	v_or_b32_e32 v7, v4, v21
	s_add_i32 s5, s0, 0x80
	v_cvt_pk_bf16_f32 v12, v19, v17
	v_cvt_pk_bf16_f32 v13, v39, v41
	v_cvt_pk_bf16_f32 v14, v43, v45
	v_cvt_pk_bf16_f32 v15, v47, v49
	v_mad_u64_u32 v[16:17], s[6:7], v7, v36, 0
	ds_read2_b32 v[18:19], v20 offset0:16 offset1:24
	ds_read2_b32 v[38:39], v20 offset0:49 offset1:57
	ds_read2_b32 v[40:41], v20 offset0:82 offset1:90
	ds_read2_b32 v[42:43], v20 offset0:115 offset1:123
	ds_read2_b32 v[44:45], v20 offset0:148 offset1:156
	ds_read2_b32 v[46:47], v20 offset0:181 offset1:189
	ds_read2_b32 v[48:49], v20 offset0:214 offset1:222
	ds_read2_b32 v[50:51], v20 offset0:247 offset1:255
	v_add_u32_e32 v17, v17, v9
	v_lshl_add_u64 v[16:17], v[16:17], 1, v[2:3]
	v_or_b32_e32 v7, v4, v22
	global_store_dwordx4 v[16:17], v[12:15], off
	v_mad_u64_u32 v[16:17], s[6:7], v7, v36, 0
	v_add_u32_e32 v17, v17, v9
	s_waitcnt lgkmcnt(6)
	v_cvt_pk_bf16_f32 v12, v18, v38
	s_waitcnt lgkmcnt(4)
	v_cvt_pk_bf16_f32 v13, v40, v42
	s_waitcnt lgkmcnt(2)
	v_cvt_pk_bf16_f32 v14, v44, v46
	s_waitcnt lgkmcnt(0)
	v_cvt_pk_bf16_f32 v15, v48, v50
	v_lshl_add_u64 v[16:17], v[16:17], 1, v[2:3]
	v_or_b32_e32 v4, v4, v23
	global_store_dwordx4 v[16:17], v[12:15], off
	v_mad_u64_u32 v[16:17], s[6:7], v4, v36, 0
	v_add_u32_e32 v17, v17, v9
	v_cvt_pk_bf16_f32 v12, v19, v39
	v_cvt_pk_bf16_f32 v13, v41, v43
	v_cvt_pk_bf16_f32 v14, v45, v47
	v_cvt_pk_bf16_f32 v15, v49, v51
	v_lshl_add_u64 v[2:3], v[16:17], 1, v[2:3]
	global_store_dwordx4 v[2:3], v[12:15], off
	s_waitcnt lgkmcnt(0)
	s_add_i32 s5, s0, 0x80
	s_cmpk_gt_i32 s0, 0x36f
	s_cbranch_scc1 .Lgu0h_nx
	s_add_i32 s5, s0, 0x180
.Lgu0h_nx:
	s_cmpk_gt_i32 s5, 0x5bf
	s_mov_b32 s0, s5
	s_cbranch_scc0 .Lgu0h_BB0_1019
.Lgu0h_BB0_1034:
	s_barrier
	v_readlane_b32 s0, v220, 0
	v_readlane_b32 s1, v220, 1
	v_readlane_b32 s2, v220, 2
	v_readlane_b32 s3, v220, 3
	v_readlane_b32 s4, v220, 4
	v_readlane_b32 s5, v220, 5
	v_readlane_b32 s6, v220, 6
	v_readlane_b32 s7, v220, 7
	v_readlane_b32 s8, v220, 8
	v_readlane_b32 s9, v220, 9
	v_readlane_b32 s10, v220, 10
	v_readlane_b32 s11, v220, 11
	v_readlane_b32 s12, v220, 12
	v_readlane_b32 s13, v220, 13
	v_readlane_b32 s14, v220, 14
	v_readlane_b32 s15, v220, 15
	v_readlane_b32 s16, v220, 16
	v_readlane_b32 s17, v220, 17
	v_readlane_b32 s18, v220, 18
	v_readlane_b32 s19, v220, 19
	v_readlane_b32 s20, v220, 20
	v_readlane_b32 s21, v220, 21
	v_readlane_b32 s22, v220, 22
	v_readlane_b32 s23, v220, 23
	v_readlane_b32 s24, v220, 24
	v_readlane_b32 s25, v220, 25
	v_readlane_b32 s26, v220, 26
	v_readlane_b32 s27, v220, 27
	v_readlane_b32 s36, v220, 28
	v_readlane_b32 s37, v220, 29
	v_readlane_b32 s38, v220, 30
	v_readlane_b32 s39, v220, 31
	v_readlane_b32 s40, v220, 32
	v_readlane_b32 s41, v220, 33
	v_readlane_b32 s42, v220, 34
	v_readlane_b32 s43, v220, 35
	v_readlane_b32 s44, v220, 36
	v_readlane_b32 s45, v220, 37
	v_readlane_b32 s46, v220, 38
	v_readlane_b32 s47, v220, 39
	v_readlane_b32 s48, v220, 40
	v_readlane_b32 s49, v220, 41
	v_readlane_b32 s50, v220, 42
	v_readlane_b32 s51, v220, 43
	s_nop 3

.LBB0_756:
	s_waitcnt vmcnt(6) lgkmcnt(0)
	s_barrier
	s_waitcnt lgkmcnt(0)
	v_mfma_f32_16x16x32_bf16 v[124:127], v[52:55], v[64:67], v[124:127]
	s_mul_i32 s19, s96, 0xc000
	s_add_i32 s24, s19, 0xffff4000
	v_mfma_f32_16x16x32_bf16 v[120:123], v[48:51], v[64:67], v[120:123]
	s_cmp_lg_u32 s96, 0
	s_cselect_b32 s24, s24, 0x18000
	s_add_i32 vcc_hi, s5, s24
	v_mfma_f32_16x16x32_bf16 v[116:119], v[44:47], v[64:67], v[116:119]
	v_mfma_f32_16x16x32_bf16 v[64:67], v[40:43], v[64:67], v[112:115]
	v_mfma_f32_16x16x32_bf16 v[108:111], v[52:55], v[56:59], v[108:111]
	v_mfma_f32_16x16x32_bf16 v[104:107], v[48:51], v[56:59], v[104:107]
	v_mfma_f32_16x16x32_bf16 v[100:103], v[44:47], v[56:59], v[100:103]
	v_mfma_f32_16x16x32_bf16 v[56:59], v[40:43], v[56:59], v[96:99]
	s_add_u32 s26, s10, s8
	v_mov_b32_e32 v150, v164
	s_addc_u32 s27, s11, s9
	s_mov_b64 s[60:61], 0x4400180
	s_mov_b32 m0, vcc_hi
	s_add_u32 s98, s26, 0x4400180
	s_addc_u32 s99, s27, 0x0
	global_load_lds_dwordx4 v164, s[98:99]
	v_mfma_f32_16x16x32_bf16 v[92:95], v[52:55], v[36:39], v[92:95]
	v_mfma_f32_16x16x32_bf16 v[88:91], v[48:51], v[36:39], v[88:91]
	v_mfma_f32_16x16x32_bf16 v[84:87], v[44:47], v[36:39], v[84:87]
	v_mfma_f32_16x16x32_bf16 v[36:39], v[40:43], v[36:39], v[80:83]
	v_mfma_f32_16x16x32_bf16 v[52:55], v[52:55], v[32:35], v[76:79]
	v_mfma_f32_16x16x32_bf16 v[48:51], v[48:51], v[32:35], v[72:75]
	v_mfma_f32_16x16x32_bf16 v[44:47], v[44:47], v[32:35], v[68:71]
	v_mfma_f32_16x16x32_bf16 v[32:35], v[40:43], v[32:35], v[60:63]
	v_mov_b32_e32 v150, v165
	s_mov_b64 s[60:61], 0x440b180
	s_add_i32 m0, vcc_hi, 0x400
	s_add_u32 s100, s26, 0x440b180
	s_addc_u32 s101, s27, 0x0
	global_load_lds_dwordx4 v165, s[100:101]
	v_mfma_f32_16x16x32_bf16 v[124:127], v[20:23], v[28:31], v[124:127]
	v_mfma_f32_16x16x32_bf16 v[120:123], v[16:19], v[28:31], v[120:123]
	v_mfma_f32_16x16x32_bf16 v[116:119], v[12:15], v[28:31], v[116:119]
	v_mfma_f32_16x16x32_bf16 v[112:115], v[8:11], v[28:31], v[64:67]
	v_mfma_f32_16x16x32_bf16 v[108:111], v[20:23], v[24:27], v[108:111]
	v_mfma_f32_16x16x32_bf16 v[104:107], v[16:19], v[24:27], v[104:107]
	v_mfma_f32_16x16x32_bf16 v[100:103], v[12:15], v[24:27], v[100:103]
	v_mfma_f32_16x16x32_bf16 v[96:99], v[8:11], v[24:27], v[56:59]
	v_mov_b32_e32 v150, v164
	s_mov_b64 s[60:61], 0x4416180
	s_add_i32 m0, vcc_hi, 0x800
	s_add_u32 s98, s26, 0x4416180
	s_addc_u32 s99, s27, 0x0
	global_load_lds_dwordx4 v164, s[98:99]
	v_mfma_f32_16x16x32_bf16 v[92:95], v[20:23], v[4:7], v[92:95]
	s_waitcnt lgkmcnt(0)
	v_mfma_f32_16x16x32_bf16 v[88:91], v[16:19], v[4:7], v[88:91]
	v_mfma_f32_16x16x32_bf16 v[84:87], v[12:15], v[4:7], v[84:87]
	v_mfma_f32_16x16x32_bf16 v[80:83], v[8:11], v[4:7], v[36:39]
	v_mfma_f32_16x16x32_bf16 v[76:79], v[20:23], v[0:3], v[52:55]
	v_mfma_f32_16x16x32_bf16 v[72:75], v[16:19], v[0:3], v[48:51]
	v_mfma_f32_16x16x32_bf16 v[68:71], v[12:15], v[0:3], v[44:47]
	v_mfma_f32_16x16x32_bf16 v[60:63], v[8:11], v[0:3], v[32:35]
	s_barrier
	s_add_i32 s19, s19, 0
	v_add_u32_e32 v0, s19, v155
	v_add_u32_e32 v8, s19, v156
	s_add_i32 s19, s24, 0
	s_add_i32 s24, s19, s4
	s_add_i32 m0, s24, 0xc00
	s_add_u32 s100, s26, 0x4421180
	s_addc_u32 s101, s27, 0x0
	s_mov_b64 s[26:27], 0x4421180
	s_add_u32 s26, s97, s8
	s_addc_u32 s27, vcc_lo, s9
	global_load_lds_dwordx4 v165, s[100:101]
	s_add_i32 s19, s19, s16
	s_add_i32 m0, s19, 0x8000
	s_add_u32 s98, s26, 0x1400180
	s_addc_u32 s99, s27, 0x0
	global_load_lds_dwordx4 v164, s[98:99]
	s_add_i32 m0, s19, 0x8400
	s_add_u32 s100, s26, 0x140b180
	s_addc_u32 s101, s27, 0x0
	global_load_lds_dwordx4 v165, s[100:101]
	v_add3_u32 v1, v0, s18, v169
	v_add3_u32 v0, v0, s17, v169
	ds_read_b128 v[64:67], v1
	ds_read_b128 v[56:59], v1 offset:2048
	ds_read_b128 v[36:39], v1 offset:4096
	ds_read_b128 v[32:35], v1 offset:6144
	ds_read_b128 v[52:55], v0 offset:32768
	ds_read_b128 v[48:51], v0 offset:34816
	ds_read_b128 v[44:47], v0 offset:36864
	ds_read_b128 v[40:43], v0 offset:38912
	v_add3_u32 v0, v8, s18, v169
	v_add3_u32 v8, v8, s17, v169
	ds_read_b128 v[28:31], v0
	ds_read_b128 v[24:27], v0 offset:2048
	ds_read_b128 v[4:7], v0 offset:4096
	ds_read_b128 v[0:3], v0 offset:6144
	ds_read_b128 v[20:23], v8 offset:32768
	ds_read_b128 v[16:19], v8 offset:34816
	ds_read_b128 v[12:15], v8 offset:36864
	ds_read_b128 v[8:11], v8 offset:38912
	s_waitcnt lgkmcnt(0)
	v_mov_b32_e32 v150, v165
	v_mov_b32_e32 v150, v164
	s_mov_b64 s[60:61], 0x1400180
	v_mov_b32_e32 v150, v165
	s_mov_b64 s[26:27], 0x140b180
	s_add_i32 s19, s96, 1
	s_cmp_lg_u32 s96, 2
	s_cselect_b32 s96, s19, 0
	s_add_u32 s8, s8, 0x80
	s_addc_u32 s9, s9, 0
	s_cmpk_eq_i32 s8, 0x1480
	s_cbranch_scc0 .LBB0_756
	s_waitcnt vmcnt(6) lgkmcnt(0)
	s_barrier
	s_waitcnt lgkmcnt(0)
	v_mfma_f32_16x16x32_bf16 v[124:127], v[52:55], v[64:67], v[124:127]
	s_mul_i32 s11, s96, 0xc000
	s_add_i32 s8, s11, 0xffff4000
	v_mfma_f32_16x16x32_bf16 v[120:123], v[48:51], v[64:67], v[120:123]
	s_cmp_lg_u32 s96, 0
	s_cselect_b32 s10, s8, 0x18000
	s_andn2_b64 vcc, exec, s[12:13]
	v_mfma_f32_16x16x32_bf16 v[116:119], v[44:47], v[64:67], v[116:119]
	v_mfma_f32_16x16x32_bf16 v[64:67], v[40:43], v[64:67], v[112:115]
	v_mfma_f32_16x16x32_bf16 v[108:111], v[52:55], v[56:59], v[108:111]
	s_nop 1
	v_cndmask_b32_e64 v112, 0, 1, s[12:13]
	v_cmp_ne_u32_e64 s[8:9], 1, v112
	v_mfma_f32_16x16x32_bf16 v[104:107], v[48:51], v[56:59], v[104:107]
	v_mfma_f32_16x16x32_bf16 v[100:103], v[44:47], v[56:59], v[100:103]
	v_mfma_f32_16x16x32_bf16 v[140:143], v[40:43], v[56:59], v[96:99]
	s_cbranch_vccnz .LBB0_759
	s_add_u32 s26, s83, s14
	v_mov_b32_e32 v56, v164
	s_addc_u32 s27, s89, s15
	s_add_i32 m0, s5, s10
	s_nop 0
	global_load_lds_dwordx4 v56, s[26:27]

.LBB0_783:
	s_waitcnt vmcnt(6) lgkmcnt(0)
	s_barrier
	s_mul_i32 s20, s10, 0xc000
	s_add_i32 s21, s20, 0
	v_add_u32_e32 v80, s21, v155
	v_add_u32_e32 v112, s21, v156
	s_add_i32 s20, s20, 0xffff4000
	s_cmp_lg_u32 s10, 0
	s_cselect_b32 s22, s20, 0x18000
	s_add_i32 s23, s22, 0
	s_add_u32 s20, s95, s6
	s_addc_u32 s21, vcc_hi, s7
	s_add_i32 s26, s23, s4
	v_mov_b32_e32 v128, v165
	s_add_i32 m0, s26, 0xc00
	s_nop 0
	global_load_lds_dwordx4 v128, s[20:21]
	s_add_u32 s20, s19, s6
	s_addc_u32 s21, s24, s7
	s_add_i32 s23, s23, s16
	v_mov_b32_e32 v128, v164
	s_add_i32 m0, s23, 0x8000
	s_nop 0
	global_load_lds_dwordx4 v128, s[20:21]
	s_add_u32 s20, s93, s6
	v_mov_b32_e32 v128, v165
	s_addc_u32 s21, s92, s7
	s_add_i32 m0, s23, 0x8400
	s_nop 0
	global_load_lds_dwordx4 v128, s[20:21]
	v_add3_u32 v76, v80, s18, v169
	v_add3_u32 v92, v80, s17, v169
	v_add3_u32 v108, v112, s18, v169
	v_add3_u32 v124, v112, s17, v169
	ds_read_b128 v[64:67], v76
	ds_read_b128 v[68:71], v76 offset:2048
	ds_read_b128 v[72:75], v76 offset:4096
	ds_read_b128 v[76:79], v76 offset:6144
	ds_read_b128 v[80:83], v92 offset:32768
	ds_read_b128 v[84:87], v92 offset:34816
	ds_read_b128 v[88:91], v92 offset:36864
	ds_read_b128 v[92:95], v92 offset:38912
	ds_read_b128 v[96:99], v108
	ds_read_b128 v[100:103], v108 offset:2048
	ds_read_b128 v[104:107], v108 offset:4096
	ds_read_b128 v[108:111], v108 offset:6144
	ds_read_b128 v[112:115], v124 offset:32768
	ds_read_b128 v[116:119], v124 offset:34816
	ds_read_b128 v[120:123], v124 offset:36864
	ds_read_b128 v[124:127], v124 offset:38912
	s_waitcnt lgkmcnt(0)
	s_waitcnt lgkmcnt(0)
	s_barrier
	s_waitcnt lgkmcnt(0)
	v_mfma_f32_16x16x32_bf16 v[60:63], v[80:83], v[64:67], v[60:63]
	s_add_i32 s22, s5, s22
	v_mfma_f32_16x16x32_bf16 v[56:59], v[84:87], v[64:67], v[56:59]
	v_mfma_f32_16x16x32_bf16 v[52:55], v[88:91], v[64:67], v[52:55]
	v_mfma_f32_16x16x32_bf16 v[48:51], v[92:95], v[64:67], v[48:51]
	v_mfma_f32_16x16x32_bf16 v[44:47], v[80:83], v[68:71], v[44:47]
	v_mfma_f32_16x16x32_bf16 v[40:43], v[84:87], v[68:71], v[40:43]
	v_mfma_f32_16x16x32_bf16 v[36:39], v[88:91], v[68:71], v[36:39]
	v_mfma_f32_16x16x32_bf16 v[0:3], v[92:95], v[68:71], v[0:3]
	s_add_u32 s20, s8, s6
	v_mov_b32_e32 v64, v164
	s_addc_u32 s21, s9, s7
	s_mov_b32 m0, s22
	s_nop 0
	global_load_lds_dwordx4 v64, s[20:21]
	v_mfma_f32_16x16x32_bf16 v[28:31], v[80:83], v[72:75], v[28:31]
	v_mfma_f32_16x16x32_bf16 v[24:27], v[84:87], v[72:75], v[24:27]
	v_mfma_f32_16x16x32_bf16 v[20:23], v[88:91], v[72:75], v[20:23]
	v_mfma_f32_16x16x32_bf16 v[16:19], v[92:95], v[72:75], v[16:19]
	v_mfma_f32_16x16x32_bf16 v[12:15], v[80:83], v[76:79], v[12:15]
	v_mfma_f32_16x16x32_bf16 v[8:11], v[84:87], v[76:79], v[8:11]
	v_mfma_f32_16x16x32_bf16 v[4:7], v[88:91], v[76:79], v[4:7]
	v_mfma_f32_16x16x32_bf16 v[32:35], v[92:95], v[76:79], v[32:35]
	s_add_u32 s20, s11, s6
	v_mov_b32_e32 v64, v165
	s_addc_u32 s21, s96, s7
	s_add_i32 m0, s22, 0x400
	s_nop 0
	global_load_lds_dwordx4 v64, s[20:21]
	v_mfma_f32_16x16x32_bf16 v[60:63], v[112:115], v[96:99], v[60:63]
	v_mfma_f32_16x16x32_bf16 v[56:59], v[116:119], v[96:99], v[56:59]
	v_mfma_f32_16x16x32_bf16 v[52:55], v[120:123], v[96:99], v[52:55]
	v_mfma_f32_16x16x32_bf16 v[48:51], v[124:127], v[96:99], v[48:51]
	v_mfma_f32_16x16x32_bf16 v[44:47], v[112:115], v[100:103], v[44:47]
	v_mfma_f32_16x16x32_bf16 v[40:43], v[116:119], v[100:103], v[40:43]
	v_mfma_f32_16x16x32_bf16 v[36:39], v[120:123], v[100:103], v[36:39]
	v_mfma_f32_16x16x32_bf16 v[0:3], v[124:127], v[100:103], v[0:3]
	s_add_u32 s20, s97, s6
	v_mov_b32_e32 v64, v164
	s_addc_u32 s21, vcc_lo, s7
	s_add_i32 m0, s22, 0x800
	s_nop 0
	global_load_lds_dwordx4 v64, s[20:21]
	s_add_i32 s20, s10, 1
	v_mfma_f32_16x16x32_bf16 v[28:31], v[112:115], v[104:107], v[28:31]
	s_cmp_lg_u32 s10, 2
	s_cselect_b32 s10, s20, 0
	s_add_u32 s6, s6, 0x80
	v_mfma_f32_16x16x32_bf16 v[24:27], v[116:119], v[104:107], v[24:27]
	s_addc_u32 s7, s7, 0
	s_cmpk_eq_i32 s6, 0x1480
	v_mfma_f32_16x16x32_bf16 v[20:23], v[120:123], v[104:107], v[20:23]
	v_mfma_f32_16x16x32_bf16 v[16:19], v[124:127], v[104:107], v[16:19]
	v_mfma_f32_16x16x32_bf16 v[12:15], v[112:115], v[108:111], v[12:15]
	v_mfma_f32_16x16x32_bf16 v[8:11], v[116:119], v[108:111], v[8:11]
	v_mfma_f32_16x16x32_bf16 v[4:7], v[120:123], v[108:111], v[4:7]
	v_mfma_f32_16x16x32_bf16 v[32:35], v[124:127], v[108:111], v[32:35]
	s_cbranch_scc0 .LBB0_783
	s_waitcnt vmcnt(6) lgkmcnt(0)
	s_barrier
	s_mul_i32 s6, s10, 0xc000
	s_add_i32 s6, s6, 0
	v_add_u32_e32 v64, s6, v155
	v_add3_u32 v65, v64, s18, v169
	v_add3_u32 v64, v64, s17, v169
	v_add_u32_e32 v68, s6, v156
	ds_read_b128 v[124:127], v65
	ds_read_b128 v[120:123], v65 offset:2048
	ds_read_b128 v[96:99], v65 offset:4096
	ds_read_b128 v[92:95], v65 offset:6144
	ds_read_b128 v[108:111], v64 offset:32768
	ds_read_b128 v[112:115], v64 offset:34816
	ds_read_b128 v[116:119], v64 offset:36864
	ds_read_b128 v[100:103], v64 offset:38912
	v_add3_u32 v64, v68, s18, v169
	v_add3_u32 v68, v68, s17, v169
	ds_read_b128 v[88:91], v64
	ds_read_b128 v[104:107], v64 offset:2048
	ds_read_b128 v[72:75], v64 offset:4096
	ds_read_b128 v[64:67], v64 offset:6144
	ds_read_b128 v[76:79], v68 offset:32768
	ds_read_b128 v[80:83], v68 offset:34816
	ds_read_b128 v[84:87], v68 offset:36864
	ds_read_b128 v[68:71], v68 offset:38912
	s_waitcnt lgkmcnt(0)
	v_sub_co_u32_e64 v128, s[6:7], s10, 1
	s_and_b64 s[6:7], s[6:7], exec
	v_readfirstlane_b32 s6, v128
	s_cselect_b32 s20, 2, s6
	v_cndmask_b32_e64 v128, 0, 1, s[80:81]
	s_mov_b64 s[6:7], -1
	v_cmp_ne_u32_e64 s[8:9], 1, v128
	s_andn2_b64 vcc, exec, s[80:81]
	s_mul_i32 s19, s20, 0xc000
	s_cbranch_vccnz .LBB0_786
	s_mul_i32 s11, s20, 0xc000
	s_mov_b64 s[6:7], 0

.LBB0_927:
	s_cmpk_lt_i32 s10, 0x400
	v_or_b32_e32 v150, s6, v167
	s_cselect_b64 s[6:7], -1, 0
	s_xor_b64 s[12:13], s[6:7], s[12:13]
	s_and_b64 s[16:17], s[12:13], exec
	s_movk_i32 s2, 0xfc00
	s_cselect_b32 s2, s2, 0xfffffb00
	s_add_i32 s22, s2, s10
	s_or_b64 s[8:9], s[8:9], s[6:7]
	s_and_b64 s[16:17], s[12:13], exec
	s_brev_b32 s2, 32
	s_cselect_b32 s2, s2, 0x4400000
	s_add_u32 s2, s54, s2
	s_addc_u32 s11, s55, 0
	s_ashr_i32 s23, s22, 31
	s_lshl_b64 s[16:17], s[22:23], 2
	s_add_u32 s16, s2, s16
	s_addc_u32 s17, s11, s17
	v_mov_b32_e32 v159, v151
	v_lshl_add_u64 v[40:41], s[16:17], 0, v[158:159]
	v_lshlrev_b64 v[42:43], 10, v[150:151]
	v_lshl_add_u64 v[42:43], v[40:41], 0, v[42:43]
	s_and_b64 vcc, exec, s[8:9]
	s_cbranch_vccnz .LBB0_929
	global_store_dwordx4 v[42:43], v[72:75], off nt

.LBB0_932:
	global_store_dwordx4 v[42:43], v[36:39], off offset:192 nt

.LBB0_937:
	global_store_dwordx4 v[34:35], v[28:31], off offset:192 nt

.LBB0_952:
	s_waitcnt vmcnt(6) lgkmcnt(0)
	s_barrier
	s_waitcnt lgkmcnt(0)
	v_mfma_f32_16x16x32_bf16 v[124:127], v[52:55], v[64:67], v[124:127]
	s_mul_i32 s48, s97, 0xc000
	s_add_i32 s16, s48, 0xffff4000
	v_mfma_f32_16x16x32_bf16 v[120:123], v[48:51], v[64:67], v[120:123]
	s_cmp_lg_u32 s97, 0
	s_cselect_b32 s49, s16, 0x18000
	s_add_i32 s2, s61, s49
	v_mfma_f32_16x16x32_bf16 v[116:119], v[44:47], v[64:67], v[116:119]
	v_mfma_f32_16x16x32_bf16 v[64:67], v[40:43], v[64:67], v[112:115]
	v_mfma_f32_16x16x32_bf16 v[108:111], v[52:55], v[56:59], v[108:111]
	v_mfma_f32_16x16x32_bf16 v[104:107], v[48:51], v[56:59], v[104:107]
	v_mfma_f32_16x16x32_bf16 v[100:103], v[44:47], v[56:59], v[100:103]
	v_mfma_f32_16x16x32_bf16 v[56:59], v[40:43], v[56:59], v[96:99]
	s_add_u32 s16, s10, s8
	v_mov_b32_e32 v150, v178
	s_addc_u32 s17, s11, s9
	s_mov_b32 m0, s2
	s_add_u32 s98, s16, s74
	s_addc_u32 s99, s17, s75
	global_load_lds_dwordx4 v178, s[98:99]
	v_mfma_f32_16x16x32_bf16 v[92:95], v[52:55], v[36:39], v[92:95]
	v_mfma_f32_16x16x32_bf16 v[88:91], v[48:51], v[36:39], v[88:91]
	v_mfma_f32_16x16x32_bf16 v[84:87], v[44:47], v[36:39], v[84:87]
	v_mfma_f32_16x16x32_bf16 v[36:39], v[40:43], v[36:39], v[80:83]
	v_mfma_f32_16x16x32_bf16 v[52:55], v[52:55], v[32:35], v[76:79]
	v_mfma_f32_16x16x32_bf16 v[48:51], v[48:51], v[32:35], v[72:75]
	v_mfma_f32_16x16x32_bf16 v[44:47], v[44:47], v[32:35], v[68:71]
	v_mfma_f32_16x16x32_bf16 v[32:35], v[40:43], v[32:35], v[60:63]
	v_mov_b32_e32 v150, v179
	s_add_i32 m0, s2, 0x400
	s_add_u32 s100, s16, s76
	s_addc_u32 s101, s17, s77
	global_load_lds_dwordx4 v179, s[100:101]
	v_mfma_f32_16x16x32_bf16 v[124:127], v[20:23], v[28:31], v[124:127]
	v_mfma_f32_16x16x32_bf16 v[120:123], v[16:19], v[28:31], v[120:123]
	v_mfma_f32_16x16x32_bf16 v[116:119], v[12:15], v[28:31], v[116:119]
	v_mfma_f32_16x16x32_bf16 v[112:115], v[8:11], v[28:31], v[64:67]
	v_mfma_f32_16x16x32_bf16 v[108:111], v[20:23], v[24:27], v[108:111]
	v_mfma_f32_16x16x32_bf16 v[104:107], v[16:19], v[24:27], v[104:107]
	v_mfma_f32_16x16x32_bf16 v[100:103], v[12:15], v[24:27], v[100:103]
	v_mfma_f32_16x16x32_bf16 v[96:99], v[8:11], v[24:27], v[56:59]
	v_mov_b32_e32 v150, v178
	s_add_i32 m0, s2, 0x800
	s_add_u32 s98, s16, s78
	s_addc_u32 s99, s17, s79
	global_load_lds_dwordx4 v178, s[98:99]
	v_mfma_f32_16x16x32_bf16 v[92:95], v[20:23], v[4:7], v[92:95]
	s_waitcnt lgkmcnt(0)
	v_mfma_f32_16x16x32_bf16 v[88:91], v[16:19], v[4:7], v[88:91]
	v_mfma_f32_16x16x32_bf16 v[84:87], v[12:15], v[4:7], v[84:87]
	v_mfma_f32_16x16x32_bf16 v[80:83], v[8:11], v[4:7], v[36:39]
	v_mfma_f32_16x16x32_bf16 v[76:79], v[20:23], v[0:3], v[52:55]
	v_mfma_f32_16x16x32_bf16 v[72:75], v[16:19], v[0:3], v[48:51]
	v_mfma_f32_16x16x32_bf16 v[68:71], v[12:15], v[0:3], v[44:47]
	v_mfma_f32_16x16x32_bf16 v[60:63], v[8:11], v[0:3], v[32:35]
	s_barrier
	s_add_i32 s2, s48, 0
	v_add_u32_e32 v0, s2, v186
	v_add_u32_e32 v8, s2, v187
	s_add_i32 s2, s49, 0
	s_add_u32 s100, s16, s80
	s_addc_u32 s101, s17, s81
	s_add_i32 s16, s2, s60
	s_add_i32 m0, s16, 0xc00
	s_add_u32 s16, vcc_lo, s8
	s_addc_u32 s17, vcc_hi, s9
	global_load_lds_dwordx4 v179, s[100:101]
	s_add_i32 s2, s2, s62
	s_add_i32 m0, s2, 0x8000
	s_add_u32 s98, s16, s82
	s_addc_u32 s99, s17, s83
	global_load_lds_dwordx4 v178, s[98:99]
	s_add_i32 m0, s2, 0x8400
	s_add_u32 s100, s16, s84
	s_addc_u32 s101, s17, s85
	global_load_lds_dwordx4 v179, s[100:101]
	v_add3_u32 v1, v0, s66, v169
	v_add3_u32 v0, v0, s65, v169
	ds_read_b128 v[64:67], v1
	ds_read_b128 v[56:59], v1 offset:2048
	ds_read_b128 v[36:39], v1 offset:4096
	ds_read_b128 v[32:35], v1 offset:6144
	ds_read_b128 v[52:55], v0 offset:32768
	ds_read_b128 v[48:51], v0 offset:34816
	ds_read_b128 v[44:47], v0 offset:36864
	ds_read_b128 v[40:43], v0 offset:38912
	v_add3_u32 v0, v8, s66, v169
	v_add3_u32 v8, v8, s65, v169
	ds_read_b128 v[28:31], v0
	ds_read_b128 v[24:27], v0 offset:2048
	ds_read_b128 v[4:7], v0 offset:4096
	ds_read_b128 v[0:3], v0 offset:6144
	ds_read_b128 v[20:23], v8 offset:32768
	ds_read_b128 v[16:19], v8 offset:34816
	ds_read_b128 v[12:15], v8 offset:36864
	ds_read_b128 v[8:11], v8 offset:38912
	s_waitcnt lgkmcnt(0)
	v_mov_b32_e32 v150, v179
	v_mov_b32_e32 v150, v178
	v_mov_b32_e32 v150, v179
	s_add_i32 s2, s97, 1
	s_cmp_lg_u32 s97, 2
	s_cselect_b32 s97, s2, 0
	s_add_u32 s8, s8, 0x80
	s_addc_u32 s9, s9, 0
	s_cmpk_eq_i32 s8, 0x680
	s_cbranch_scc0 .LBB0_952
	s_waitcnt vmcnt(6) lgkmcnt(0)
	s_barrier
	s_waitcnt lgkmcnt(0)
	v_mfma_f32_16x16x32_bf16 v[124:127], v[52:55], v[64:67], v[124:127]
	s_mul_i32 s11, s97, 0xc000
	s_add_i32 s8, s11, 0xffff4000
	v_mfma_f32_16x16x32_bf16 v[120:123], v[48:51], v[64:67], v[120:123]
	s_cmp_lg_u32 s97, 0
	s_cselect_b32 s10, s8, 0x18000
	s_andn2_b64 vcc, exec, s[12:13]
	v_mfma_f32_16x16x32_bf16 v[116:119], v[44:47], v[64:67], v[116:119]
	v_mfma_f32_16x16x32_bf16 v[64:67], v[40:43], v[64:67], v[112:115]
	v_mfma_f32_16x16x32_bf16 v[108:111], v[52:55], v[56:59], v[108:111]
	s_nop 1
	v_cndmask_b32_e64 v112, 0, 1, s[12:13]
	v_cmp_ne_u32_e64 s[8:9], 1, v112
	v_mfma_f32_16x16x32_bf16 v[104:107], v[48:51], v[56:59], v[104:107]
	v_mfma_f32_16x16x32_bf16 v[100:103], v[44:47], v[56:59], v[100:103]
	v_mfma_f32_16x16x32_bf16 v[140:143], v[40:43], v[56:59], v[96:99]
	s_cbranch_vccnz .LBB0_955
	s_add_u32 s16, s24, s14
	v_mov_b32_e32 v56, v178
	s_addc_u32 s17, s25, s15
	s_add_i32 m0, s61, s10
	s_nop 0
	global_load_lds_dwordx4 v56, s[16:17]

.LBB0_979:
	s_waitcnt vmcnt(6) lgkmcnt(0)
	s_barrier
	s_mul_i32 s16, s10, 0xc000
	s_add_i32 s17, s16, 0
	v_add_u32_e32 v80, s17, v186
	v_add_u32_e32 v112, s17, v187
	s_add_i32 s16, s16, 0xffff4000
	s_cmp_lg_u32 s10, 0
	s_cselect_b32 s23, s16, 0x18000
	s_add_i32 s48, s23, 0
	s_add_u32 s16, s8, s6
	s_addc_u32 s17, s9, s7
	s_add_i32 s26, s48, s60
	s_add_i32 m0, s26, 0xc00
	s_add_u32 s26, s11, s6
	s_addc_u32 s27, s22, s7
	s_add_u32 s98, s16, s80
	s_addc_u32 s99, s17, s81
	global_load_lds_dwordx4 v179, s[98:99]
	s_add_i32 s48, s48, s62
	s_add_i32 m0, s48, 0x8000
	s_add_u32 s100, s26, s82
	s_addc_u32 s101, s27, s83
	global_load_lds_dwordx4 v178, s[100:101]
	s_add_i32 m0, s48, 0x8400
	s_add_u32 s98, s26, s84
	s_addc_u32 s99, s27, s85
	global_load_lds_dwordx4 v179, s[98:99]
	v_add3_u32 v76, v80, s66, v169
	v_add3_u32 v92, v80, s65, v169
	v_add3_u32 v108, v112, s66, v169
	v_add3_u32 v124, v112, s65, v169
	ds_read_b128 v[64:67], v76
	ds_read_b128 v[68:71], v76 offset:2048
	ds_read_b128 v[72:75], v76 offset:4096
	ds_read_b128 v[76:79], v76 offset:6144
	ds_read_b128 v[80:83], v92 offset:32768
	ds_read_b128 v[84:87], v92 offset:34816
	ds_read_b128 v[88:91], v92 offset:36864
	ds_read_b128 v[92:95], v92 offset:38912
	ds_read_b128 v[96:99], v108
	ds_read_b128 v[100:103], v108 offset:2048
	ds_read_b128 v[104:107], v108 offset:4096
	ds_read_b128 v[108:111], v108 offset:6144
	ds_read_b128 v[112:115], v124 offset:32768
	ds_read_b128 v[116:119], v124 offset:34816
	ds_read_b128 v[120:123], v124 offset:36864
	ds_read_b128 v[124:127], v124 offset:38912
	s_waitcnt lgkmcnt(0)
	v_mov_b32_e32 v150, v179
	v_mov_b32_e32 v150, v178
	v_mov_b32_e32 v150, v179
	s_waitcnt lgkmcnt(0)
	s_barrier
	s_waitcnt lgkmcnt(0)
	v_mfma_f32_16x16x32_bf16 v[60:63], v[80:83], v[64:67], v[60:63]
	s_add_i32 s23, s61, s23
	v_mfma_f32_16x16x32_bf16 v[56:59], v[84:87], v[64:67], v[56:59]
	v_mfma_f32_16x16x32_bf16 v[52:55], v[88:91], v[64:67], v[52:55]
	v_mfma_f32_16x16x32_bf16 v[48:51], v[92:95], v[64:67], v[48:51]
	v_mfma_f32_16x16x32_bf16 v[44:47], v[80:83], v[68:71], v[44:47]
	v_mfma_f32_16x16x32_bf16 v[40:43], v[84:87], v[68:71], v[40:43]
	v_mfma_f32_16x16x32_bf16 v[36:39], v[88:91], v[68:71], v[36:39]
	v_mfma_f32_16x16x32_bf16 v[28:31], v[92:95], v[68:71], v[28:31]
	v_mov_b32_e32 v150, v178
	s_mov_b32 m0, s23
	s_add_u32 s100, s16, s74
	s_addc_u32 s101, s17, s75
	global_load_lds_dwordx4 v178, s[100:101]
	v_mfma_f32_16x16x32_bf16 v[24:27], v[80:83], v[72:75], v[24:27]
	v_mfma_f32_16x16x32_bf16 v[20:23], v[84:87], v[72:75], v[20:23]
	v_mfma_f32_16x16x32_bf16 v[16:19], v[88:91], v[72:75], v[16:19]
	v_mfma_f32_16x16x32_bf16 v[12:15], v[92:95], v[72:75], v[12:15]
	v_mfma_f32_16x16x32_bf16 v[8:11], v[80:83], v[76:79], v[8:11]
	v_mfma_f32_16x16x32_bf16 v[4:7], v[84:87], v[76:79], v[4:7]
	v_mfma_f32_16x16x32_bf16 v[0:3], v[88:91], v[76:79], v[0:3]
	v_mfma_f32_16x16x32_bf16 v[32:35], v[92:95], v[76:79], v[32:35]
	v_mov_b32_e32 v150, v179
	s_add_i32 m0, s23, 0x400
	s_add_u32 s98, s16, s76
	s_addc_u32 s99, s17, s77
	global_load_lds_dwordx4 v179, s[98:99]
	v_mfma_f32_16x16x32_bf16 v[60:63], v[112:115], v[96:99], v[60:63]
	v_mfma_f32_16x16x32_bf16 v[56:59], v[116:119], v[96:99], v[56:59]
	v_mfma_f32_16x16x32_bf16 v[52:55], v[120:123], v[96:99], v[52:55]
	v_mfma_f32_16x16x32_bf16 v[48:51], v[124:127], v[96:99], v[48:51]
	v_mfma_f32_16x16x32_bf16 v[44:47], v[112:115], v[100:103], v[44:47]
	v_mfma_f32_16x16x32_bf16 v[40:43], v[116:119], v[100:103], v[40:43]
	v_mfma_f32_16x16x32_bf16 v[36:39], v[120:123], v[100:103], v[36:39]
	v_mfma_f32_16x16x32_bf16 v[28:31], v[124:127], v[100:103], v[28:31]
	v_mov_b32_e32 v150, v178
	s_add_i32 m0, s23, 0x800
	s_add_u32 s100, s16, s78
	s_addc_u32 s101, s17, s79
	global_load_lds_dwordx4 v178, s[100:101]
	s_add_i32 s16, s10, 1
	v_mfma_f32_16x16x32_bf16 v[24:27], v[112:115], v[104:107], v[24:27]
	s_cmp_lg_u32 s10, 2
	s_cselect_b32 s10, s16, 0
	s_add_u32 s6, s6, 0x80
	v_mfma_f32_16x16x32_bf16 v[20:23], v[116:119], v[104:107], v[20:23]
	s_addc_u32 s7, s7, 0
	s_cmpk_eq_i32 s6, 0x680
	v_mfma_f32_16x16x32_bf16 v[16:19], v[120:123], v[104:107], v[16:19]
	v_mfma_f32_16x16x32_bf16 v[12:15], v[124:127], v[104:107], v[12:15]
	v_mfma_f32_16x16x32_bf16 v[8:11], v[112:115], v[108:111], v[8:11]
	v_mfma_f32_16x16x32_bf16 v[4:7], v[116:119], v[108:111], v[4:7]
	v_mfma_f32_16x16x32_bf16 v[0:3], v[120:123], v[108:111], v[0:3]
	v_mfma_f32_16x16x32_bf16 v[32:35], v[124:127], v[108:111], v[32:35]
	s_cbranch_scc0 .LBB0_979
	s_waitcnt vmcnt(6) lgkmcnt(0)
	s_barrier
	s_mul_i32 s2, s10, 0xc000
	s_add_i32 s2, s2, 0
	v_add_u32_e32 v64, s2, v186
	v_add3_u32 v65, v64, s66, v169
	v_add3_u32 v64, v64, s65, v169
	v_add_u32_e32 v68, s2, v187
	ds_read_b128 v[124:127], v65
	ds_read_b128 v[120:123], v65 offset:2048
	ds_read_b128 v[100:103], v65 offset:4096
	ds_read_b128 v[96:99], v65 offset:6144
	ds_read_b128 v[108:111], v64 offset:32768
	ds_read_b128 v[112:115], v64 offset:34816
	ds_read_b128 v[116:119], v64 offset:36864
	ds_read_b128 v[104:107], v64 offset:38912
	v_add3_u32 v64, v68, s66, v169
	v_add3_u32 v68, v68, s65, v169
	ds_read_b128 v[92:95], v64
	ds_read_b128 v[88:91], v64 offset:2048
	ds_read_b128 v[72:75], v64 offset:4096
	ds_read_b128 v[64:67], v64 offset:6144
	ds_read_b128 v[76:79], v68 offset:32768
	ds_read_b128 v[80:83], v68 offset:34816
	ds_read_b128 v[84:87], v68 offset:36864
	ds_read_b128 v[68:71], v68 offset:38912
	s_waitcnt lgkmcnt(0)
	v_sub_co_u32_e64 v128, s[6:7], s10, 1
	s_and_b64 s[6:7], s[6:7], exec
	v_readfirstlane_b32 s2, v128
	s_cselect_b32 s23, 2, s2
	v_cndmask_b32_e64 v128, 0, 1, s[94:95]
	s_mov_b64 s[6:7], -1
	v_cmp_ne_u32_e64 s[8:9], 1, v128
	s_andn2_b64 vcc, exec, s[94:95]
	s_mul_i32 s22, s23, 0xc000
	s_cbranch_vccnz .LBB0_982
	s_mul_i32 s11, s23, 0xc000
	s_mov_b64 s[6:7], 0

.LBB0_1003:
	global_store_dwordx4 v[42:43], v[32:35], off offset:64 nt
	s_and_b64 vcc, exec, s[8:9]
	s_cbranch_vccnz .LBB0_931
.LBB0_1004:
	global_store_dwordx4 v[42:43], v[76:79], off offset:128 nt
	s_and_b64 vcc, exec, s[8:9]
	s_cbranch_vccz .LBB0_932
	s_branch .LBB0_933
.LBB0_1005:
	global_store_dwordx4 v[34:35], v[64:67], off nt
	s_and_b64 vcc, exec, s[8:9]
	s_cbranch_vccnz .LBB0_935
.LBB0_1006:
	global_store_dwordx4 v[34:35], v[24:27], off offset:64 nt
	s_and_b64 vcc, exec, s[8:9]
	s_cbranch_vccnz .LBB0_936
.LBB0_1007:
	global_store_dwordx4 v[34:35], v[68:71], off offset:128 nt
	s_and_b64 vcc, exec, s[8:9]
	s_cbranch_vccz .LBB0_937
	s_branch .LBB0_938
.LBB0_1008:
	global_store_dwordx4 v[26:27], v[54:57], off nt
	s_and_b64 vcc, exec, s[8:9]
	s_cbranch_vccnz .LBB0_940
.LBB0_1009:
	global_store_dwordx4 v[26:27], v[16:19], off offset:64 nt
	s_and_b64 vcc, exec, s[8:9]
	s_cbranch_vccnz .LBB0_941
.LBB0_1010:
	global_store_dwordx4 v[26:27], v[58:61], off offset:128 nt
	s_and_b64 vcc, exec, s[8:9]
	s_cbranch_vccz .LBB0_942
	s_branch .LBB0_943
.LBB0_1011:
	global_store_dwordx4 v[16:17], v[12:15], off nt
	s_and_b64 vcc, exec, s[8:9]
	s_cbranch_vccnz .LBB0_945
.LBB0_1012:
	global_store_dwordx4 v[16:17], v[0:3], off offset:64 nt
	s_and_b64 vcc, exec, s[8:9]
	s_cbranch_vccnz .LBB0_946
.LBB0_1013:
	global_store_dwordx4 v[16:17], v[4:7], off offset:128 nt
	s_and_b64 vcc, exec, s[8:9]
	s_cbranch_vccnz .LBB0_920

.LBB0_1183:
	s_waitcnt vmcnt(6) lgkmcnt(0)
	s_barrier
	s_waitcnt lgkmcnt(0)
	v_mfma_f32_16x16x32_bf16 v[124:127], v[52:55], v[64:67], v[124:127]
	s_mul_i32 s76, s97, 0xc000
	s_add_i32 s16, s76, 0xffff4000
	v_mfma_f32_16x16x32_bf16 v[120:123], v[48:51], v[64:67], v[120:123]
	s_cmp_lg_u32 s97, 0
	s_cselect_b32 s77, s16, 0x18000
	s_add_i32 s33, s4, s77
	v_mfma_f32_16x16x32_bf16 v[116:119], v[44:47], v[64:67], v[116:119]
	v_mfma_f32_16x16x32_bf16 v[64:67], v[40:43], v[64:67], v[112:115]
	v_mfma_f32_16x16x32_bf16 v[108:111], v[52:55], v[56:59], v[108:111]
	v_mfma_f32_16x16x32_bf16 v[104:107], v[48:51], v[56:59], v[104:107]
	v_mfma_f32_16x16x32_bf16 v[100:103], v[44:47], v[56:59], v[100:103]
	v_mfma_f32_16x16x32_bf16 v[56:59], v[40:43], v[56:59], v[96:99]
	s_add_u32 s16, s10, s8
	v_mov_b32_e32 v148, v162
	s_addc_u32 s17, s11, s9
	s_mov_b32 m0, s33
	s_add_u32 s98, s16, s38
	s_addc_u32 s99, s17, s39
	global_load_lds_dwordx4 v162, s[98:99]
	v_mfma_f32_16x16x32_bf16 v[92:95], v[52:55], v[36:39], v[92:95]
	v_mfma_f32_16x16x32_bf16 v[88:91], v[48:51], v[36:39], v[88:91]
	v_mfma_f32_16x16x32_bf16 v[84:87], v[44:47], v[36:39], v[84:87]
	v_mfma_f32_16x16x32_bf16 v[36:39], v[40:43], v[36:39], v[80:83]
	v_mfma_f32_16x16x32_bf16 v[52:55], v[52:55], v[32:35], v[76:79]
	v_mfma_f32_16x16x32_bf16 v[48:51], v[48:51], v[32:35], v[72:75]
	v_mfma_f32_16x16x32_bf16 v[44:47], v[44:47], v[32:35], v[68:71]
	v_mfma_f32_16x16x32_bf16 v[32:35], v[40:43], v[32:35], v[60:63]
	v_mov_b32_e32 v148, v163
	s_add_i32 m0, s33, 0x400
	s_add_u32 s100, s16, s40
	s_addc_u32 s101, s17, s41
	global_load_lds_dwordx4 v163, s[100:101]
	v_mfma_f32_16x16x32_bf16 v[124:127], v[20:23], v[28:31], v[124:127]
	v_mfma_f32_16x16x32_bf16 v[120:123], v[16:19], v[28:31], v[120:123]
	v_mfma_f32_16x16x32_bf16 v[116:119], v[12:15], v[28:31], v[116:119]
	v_mfma_f32_16x16x32_bf16 v[112:115], v[8:11], v[28:31], v[64:67]
	v_mfma_f32_16x16x32_bf16 v[108:111], v[20:23], v[24:27], v[108:111]
	v_mfma_f32_16x16x32_bf16 v[104:107], v[16:19], v[24:27], v[104:107]
	v_mfma_f32_16x16x32_bf16 v[100:103], v[12:15], v[24:27], v[100:103]
	v_mfma_f32_16x16x32_bf16 v[96:99], v[8:11], v[24:27], v[56:59]
	v_mov_b32_e32 v148, v162
	s_add_i32 m0, s33, 0x800
	s_add_u32 s98, s16, s42
	s_addc_u32 s99, s17, s43
	global_load_lds_dwordx4 v162, s[98:99]
	v_mfma_f32_16x16x32_bf16 v[92:95], v[20:23], v[4:7], v[92:95]
	s_waitcnt lgkmcnt(0)
	v_mfma_f32_16x16x32_bf16 v[88:91], v[16:19], v[4:7], v[88:91]
	v_mfma_f32_16x16x32_bf16 v[84:87], v[12:15], v[4:7], v[84:87]
	v_mfma_f32_16x16x32_bf16 v[80:83], v[8:11], v[4:7], v[36:39]
	v_mfma_f32_16x16x32_bf16 v[76:79], v[20:23], v[0:3], v[52:55]
	v_mfma_f32_16x16x32_bf16 v[72:75], v[16:19], v[0:3], v[48:51]
	v_mfma_f32_16x16x32_bf16 v[68:71], v[12:15], v[0:3], v[44:47]
	v_mfma_f32_16x16x32_bf16 v[60:63], v[8:11], v[0:3], v[32:35]
	s_barrier
	s_add_i32 s33, s76, 0
	v_add_u32_e32 v0, s33, v153
	v_add_u32_e32 v8, s33, v154
	s_add_i32 s33, s77, 0
	s_add_u32 s100, s16, s44
	s_addc_u32 s101, s17, s45
	s_add_i32 s16, s33, s3
	s_add_i32 m0, s16, 0xc00
	s_add_u32 s16, vcc_lo, s8
	s_addc_u32 s17, vcc_hi, s9
	global_load_lds_dwordx4 v163, s[100:101]
	s_add_i32 s33, s33, s5
	s_add_i32 m0, s33, 0x8000
	s_add_u32 s98, s16, s46
	s_addc_u32 s99, s17, s47
	global_load_lds_dwordx4 v162, s[98:99]
	s_add_i32 m0, s33, 0x8400
	s_add_u32 s100, s16, s48
	s_addc_u32 s101, s17, s49
	global_load_lds_dwordx4 v163, s[100:101]
	v_add3_u32 v1, v0, s29, v169
	v_add3_u32 v0, v0, s28, v169
	ds_read_b128 v[64:67], v1
	ds_read_b128 v[56:59], v1 offset:2048
	ds_read_b128 v[36:39], v1 offset:4096
	ds_read_b128 v[32:35], v1 offset:6144
	ds_read_b128 v[52:55], v0 offset:32768
	ds_read_b128 v[48:51], v0 offset:34816
	ds_read_b128 v[44:47], v0 offset:36864
	ds_read_b128 v[40:43], v0 offset:38912
	v_add3_u32 v0, v8, s29, v169
	v_add3_u32 v8, v8, s28, v169
	ds_read_b128 v[28:31], v0
	ds_read_b128 v[24:27], v0 offset:2048
	ds_read_b128 v[4:7], v0 offset:4096
	ds_read_b128 v[0:3], v0 offset:6144
	ds_read_b128 v[20:23], v8 offset:32768
	ds_read_b128 v[16:19], v8 offset:34816
	ds_read_b128 v[12:15], v8 offset:36864
	ds_read_b128 v[8:11], v8 offset:38912
	s_waitcnt lgkmcnt(0)
	v_mov_b32_e32 v148, v163
	v_mov_b32_e32 v148, v162
	v_mov_b32_e32 v148, v163
	s_add_i32 s16, s97, 1
	s_cmp_lg_u32 s97, 2
	s_cselect_b32 s97, s16, 0
	s_add_u32 s8, s8, 0x80
	s_addc_u32 s9, s9, 0
	s_cmpk_eq_i32 s8, 0x680
	s_cbranch_scc0 .LBB0_1183
	s_waitcnt vmcnt(6) lgkmcnt(0)
	s_barrier
	s_waitcnt lgkmcnt(0)
	v_mfma_f32_16x16x32_bf16 v[124:127], v[52:55], v[64:67], v[124:127]
	s_mul_i32 s11, s97, 0xc000
	s_add_i32 s8, s11, 0xffff4000
	v_mfma_f32_16x16x32_bf16 v[120:123], v[48:51], v[64:67], v[120:123]
	s_cmp_lg_u32 s97, 0
	s_cselect_b32 s10, s8, 0x18000
	s_andn2_b64 vcc, exec, s[70:71]
	v_mfma_f32_16x16x32_bf16 v[116:119], v[44:47], v[64:67], v[116:119]
	v_mfma_f32_16x16x32_bf16 v[64:67], v[40:43], v[64:67], v[112:115]
	v_mfma_f32_16x16x32_bf16 v[108:111], v[52:55], v[56:59], v[108:111]
	s_nop 1
	v_cndmask_b32_e64 v112, 0, 1, s[70:71]
	v_cmp_ne_u32_e64 s[8:9], 1, v112
	v_mfma_f32_16x16x32_bf16 v[104:107], v[48:51], v[56:59], v[104:107]
	v_mfma_f32_16x16x32_bf16 v[100:103], v[44:47], v[56:59], v[100:103]
	v_mfma_f32_16x16x32_bf16 v[140:143], v[40:43], v[56:59], v[96:99]
	s_cbranch_vccnz .LBB0_1186
	s_add_u32 s16, s89, s74
	v_mov_b32_e32 v56, v162
	s_addc_u32 s17, s90, s75
	s_add_i32 m0, s4, s10
	s_nop 0
	global_load_lds_dwordx4 v56, s[16:17]

.LBB0_1210:
	s_waitcnt vmcnt(6) lgkmcnt(0)
	s_barrier
	s_mul_i32 s16, s73, 0xc000
	s_add_i32 s17, s16, 0
	v_add_u32_e32 v80, s17, v153
	v_add_u32_e32 v112, s17, v154
	s_add_i32 s16, s16, 0xffff4000
	s_cmp_lg_u32 s73, 0
	s_cselect_b32 s91, s16, 0x18000
	s_add_i32 s92, s91, 0
	s_add_u32 s16, s8, s6
	s_addc_u32 s17, s9, s7
	s_add_i32 s76, s92, s3
	s_add_i32 m0, s76, 0xc00
	s_add_u32 s76, s22, s6
	s_addc_u32 s77, s23, s7
	s_add_u32 s98, s16, s44
	s_addc_u32 s99, s17, s45
	global_load_lds_dwordx4 v163, s[98:99]
	s_add_i32 s92, s92, s5
	s_add_i32 m0, s92, 0x8000
	s_add_u32 s100, s76, s46
	s_addc_u32 s101, s77, s47
	global_load_lds_dwordx4 v162, s[100:101]
	s_add_i32 m0, s92, 0x8400
	s_add_u32 s98, s76, s48
	s_addc_u32 s99, s77, s49
	global_load_lds_dwordx4 v163, s[98:99]
	v_add3_u32 v76, v80, s29, v169
	v_add3_u32 v92, v80, s28, v169
	v_add3_u32 v108, v112, s29, v169
	v_add3_u32 v124, v112, s28, v169
	ds_read_b128 v[64:67], v76
	ds_read_b128 v[68:71], v76 offset:2048
	ds_read_b128 v[72:75], v76 offset:4096
	ds_read_b128 v[76:79], v76 offset:6144
	ds_read_b128 v[80:83], v92 offset:32768
	ds_read_b128 v[84:87], v92 offset:34816
	ds_read_b128 v[88:91], v92 offset:36864
	ds_read_b128 v[92:95], v92 offset:38912
	ds_read_b128 v[96:99], v108
	ds_read_b128 v[100:103], v108 offset:2048
	ds_read_b128 v[104:107], v108 offset:4096
	ds_read_b128 v[108:111], v108 offset:6144
	ds_read_b128 v[112:115], v124 offset:32768
	ds_read_b128 v[116:119], v124 offset:34816
	ds_read_b128 v[120:123], v124 offset:36864
	ds_read_b128 v[124:127], v124 offset:38912
	s_waitcnt lgkmcnt(0)
	v_mov_b32_e32 v148, v163
	v_mov_b32_e32 v148, v162
	v_mov_b32_e32 v148, v163
	s_waitcnt lgkmcnt(0)
	s_barrier
	s_waitcnt lgkmcnt(0)
	v_mfma_f32_16x16x32_bf16 v[56:59], v[80:83], v[64:67], v[56:59]
	s_add_i32 s76, s4, s91
	v_mfma_f32_16x16x32_bf16 v[52:55], v[84:87], v[64:67], v[52:55]
	v_mfma_f32_16x16x32_bf16 v[48:51], v[88:91], v[64:67], v[48:51]
	v_mfma_f32_16x16x32_bf16 v[44:47], v[92:95], v[64:67], v[44:47]
	v_mfma_f32_16x16x32_bf16 v[40:43], v[80:83], v[68:71], v[40:43]
	v_mfma_f32_16x16x32_bf16 v[36:39], v[84:87], v[68:71], v[36:39]
	v_mfma_f32_16x16x32_bf16 v[32:35], v[88:91], v[68:71], v[32:35]
	v_mfma_f32_16x16x32_bf16 v[0:3], v[92:95], v[68:71], v[0:3]
	v_mov_b32_e32 v148, v162
	s_mov_b32 m0, s76
	s_add_u32 s100, s16, s38
	s_addc_u32 s101, s17, s39
	global_load_lds_dwordx4 v162, s[100:101]
	v_mfma_f32_16x16x32_bf16 v[28:31], v[80:83], v[72:75], v[28:31]
	v_mfma_f32_16x16x32_bf16 v[24:27], v[84:87], v[72:75], v[24:27]
	v_mfma_f32_16x16x32_bf16 v[20:23], v[88:91], v[72:75], v[20:23]
	v_mfma_f32_16x16x32_bf16 v[16:19], v[92:95], v[72:75], v[16:19]
	v_mfma_f32_16x16x32_bf16 v[12:15], v[80:83], v[76:79], v[12:15]
	v_mfma_f32_16x16x32_bf16 v[8:11], v[84:87], v[76:79], v[8:11]
	v_mfma_f32_16x16x32_bf16 v[4:7], v[88:91], v[76:79], v[4:7]
	v_mfma_f32_16x16x32_bf16 v[60:63], v[92:95], v[76:79], v[60:63]
	v_mov_b32_e32 v148, v163
	s_add_i32 m0, s76, 0x400
	s_add_u32 s98, s16, s40
	s_addc_u32 s99, s17, s41
	global_load_lds_dwordx4 v163, s[98:99]
	v_mfma_f32_16x16x32_bf16 v[56:59], v[112:115], v[96:99], v[56:59]
	v_mfma_f32_16x16x32_bf16 v[52:55], v[116:119], v[96:99], v[52:55]
	v_mfma_f32_16x16x32_bf16 v[48:51], v[120:123], v[96:99], v[48:51]
	v_mfma_f32_16x16x32_bf16 v[44:47], v[124:127], v[96:99], v[44:47]
	v_mfma_f32_16x16x32_bf16 v[40:43], v[112:115], v[100:103], v[40:43]
	v_mfma_f32_16x16x32_bf16 v[36:39], v[116:119], v[100:103], v[36:39]
	v_mfma_f32_16x16x32_bf16 v[32:35], v[120:123], v[100:103], v[32:35]
	v_mfma_f32_16x16x32_bf16 v[0:3], v[124:127], v[100:103], v[0:3]
	v_mov_b32_e32 v148, v162
	s_add_i32 m0, s76, 0x800
	s_add_u32 s100, s16, s42
	s_addc_u32 s101, s17, s43
	global_load_lds_dwordx4 v162, s[100:101]
	s_add_i32 s16, s73, 1
	v_mfma_f32_16x16x32_bf16 v[28:31], v[112:115], v[104:107], v[28:31]
	s_cmp_lg_u32 s73, 2
	s_cselect_b32 s73, s16, 0
	s_add_u32 s6, s6, 0x80
	v_mfma_f32_16x16x32_bf16 v[24:27], v[116:119], v[104:107], v[24:27]
	s_addc_u32 s7, s7, 0
	s_cmpk_eq_i32 s6, 0x680
	v_mfma_f32_16x16x32_bf16 v[20:23], v[120:123], v[104:107], v[20:23]
	v_mfma_f32_16x16x32_bf16 v[16:19], v[124:127], v[104:107], v[16:19]
	v_mfma_f32_16x16x32_bf16 v[12:15], v[112:115], v[108:111], v[12:15]
	v_mfma_f32_16x16x32_bf16 v[8:11], v[116:119], v[108:111], v[8:11]
	v_mfma_f32_16x16x32_bf16 v[4:7], v[120:123], v[108:111], v[4:7]
	v_mfma_f32_16x16x32_bf16 v[60:63], v[124:127], v[108:111], v[60:63]
	s_cbranch_scc0 .LBB0_1210
	s_waitcnt vmcnt(6) lgkmcnt(0)
	s_barrier
	s_mul_i32 s6, s73, 0xc000
	s_add_i32 s6, s6, 0
	v_add_u32_e32 v64, s6, v153
	v_add3_u32 v65, v64, s29, v169
	v_add3_u32 v64, v64, s28, v169
	v_add_u32_e32 v68, s6, v154
	ds_read_b128 v[124:127], v65
	ds_read_b128 v[120:123], v65 offset:2048
	ds_read_b128 v[96:99], v65 offset:4096
	ds_read_b128 v[92:95], v65 offset:6144
	ds_read_b128 v[108:111], v64 offset:32768
	ds_read_b128 v[112:115], v64 offset:34816
	ds_read_b128 v[116:119], v64 offset:36864
	ds_read_b128 v[100:103], v64 offset:38912
	v_add3_u32 v64, v68, s29, v169
	v_add3_u32 v68, v68, s28, v169
	ds_read_b128 v[88:91], v64
	ds_read_b128 v[104:107], v64 offset:2048
	ds_read_b128 v[72:75], v64 offset:4096
	ds_read_b128 v[64:67], v64 offset:6144
	ds_read_b128 v[76:79], v68 offset:32768
	ds_read_b128 v[80:83], v68 offset:34816
	ds_read_b128 v[84:87], v68 offset:36864
	ds_read_b128 v[68:71], v68 offset:38912
	s_waitcnt lgkmcnt(0)
	v_sub_co_u32_e64 v128, s[6:7], s73, 1
	s_and_b64 s[6:7], s[6:7], exec
	v_readfirstlane_b32 s6, v128
	s_cselect_b32 s91, 2, s6
	v_cndmask_b32_e64 v128, 0, 1, s[66:67]
	s_mov_b64 s[6:7], -1
	v_cmp_ne_u32_e64 s[8:9], 1, v128
	s_andn2_b64 vcc, exec, s[66:67]
	s_mul_i32 s23, s91, 0xc000
	s_cbranch_vccnz .LBB0_1213
	s_mul_i32 s22, s91, 0xc000
	s_mov_b64 s[6:7], 0

.LBB0_1356:
	s_waitcnt vmcnt(6) lgkmcnt(0)
	s_barrier
	s_waitcnt lgkmcnt(0)
	v_mfma_f32_16x16x32_bf16 v[124:127], v[52:55], v[64:67], v[124:127]
	s_mul_i32 vcc_lo, s93, 0xc000
	s_add_i32 s96, vcc_lo, 0xffff4000
	v_mfma_f32_16x16x32_bf16 v[120:123], v[48:51], v[64:67], v[120:123]
	s_cmp_lg_u32 s93, 0
	s_cselect_b32 vcc_hi, s96, 0x18000
	s_add_i32 s66, s3, vcc_hi
	v_mfma_f32_16x16x32_bf16 v[116:119], v[44:47], v[64:67], v[116:119]
	v_mfma_f32_16x16x32_bf16 v[64:67], v[40:43], v[64:67], v[112:115]
	v_mfma_f32_16x16x32_bf16 v[108:111], v[52:55], v[56:59], v[108:111]
	v_mfma_f32_16x16x32_bf16 v[104:107], v[48:51], v[56:59], v[104:107]
	v_mfma_f32_16x16x32_bf16 v[100:103], v[44:47], v[56:59], v[100:103]
	v_mfma_f32_16x16x32_bf16 v[56:59], v[40:43], v[56:59], v[96:99]
	s_add_u32 s96, s10, s8
	v_mov_b32_e32 v148, v178
	s_addc_u32 s97, s11, s9
	s_mov_b32 m0, s66
	s_add_u32 s98, s96, s44
	s_addc_u32 s99, s97, s45
	global_load_lds_dwordx4 v178, s[98:99]
	v_mfma_f32_16x16x32_bf16 v[92:95], v[52:55], v[36:39], v[92:95]
	v_mfma_f32_16x16x32_bf16 v[88:91], v[48:51], v[36:39], v[88:91]
	v_mfma_f32_16x16x32_bf16 v[84:87], v[44:47], v[36:39], v[84:87]
	v_mfma_f32_16x16x32_bf16 v[36:39], v[40:43], v[36:39], v[80:83]
	v_mfma_f32_16x16x32_bf16 v[52:55], v[52:55], v[32:35], v[76:79]
	v_mfma_f32_16x16x32_bf16 v[48:51], v[48:51], v[32:35], v[72:75]
	v_mfma_f32_16x16x32_bf16 v[44:47], v[44:47], v[32:35], v[68:71]
	v_mfma_f32_16x16x32_bf16 v[32:35], v[40:43], v[32:35], v[60:63]
	v_mov_b32_e32 v148, v179
	s_add_i32 m0, s66, 0x400
	s_add_u32 s100, s96, s46
	s_addc_u32 s101, s97, s47
	global_load_lds_dwordx4 v179, s[100:101]
	v_mfma_f32_16x16x32_bf16 v[124:127], v[20:23], v[28:31], v[124:127]
	v_mfma_f32_16x16x32_bf16 v[120:123], v[16:19], v[28:31], v[120:123]
	v_mfma_f32_16x16x32_bf16 v[116:119], v[12:15], v[28:31], v[116:119]
	v_mfma_f32_16x16x32_bf16 v[112:115], v[8:11], v[28:31], v[64:67]
	v_mfma_f32_16x16x32_bf16 v[108:111], v[20:23], v[24:27], v[108:111]
	v_mfma_f32_16x16x32_bf16 v[104:107], v[16:19], v[24:27], v[104:107]
	v_mfma_f32_16x16x32_bf16 v[100:103], v[12:15], v[24:27], v[100:103]
	v_mfma_f32_16x16x32_bf16 v[96:99], v[8:11], v[24:27], v[56:59]
	v_mov_b32_e32 v148, v178
	s_add_i32 m0, s66, 0x800
	s_add_u32 s98, s96, s48
	s_addc_u32 s99, s97, s49
	global_load_lds_dwordx4 v178, s[98:99]
	v_mfma_f32_16x16x32_bf16 v[92:95], v[20:23], v[4:7], v[92:95]
	s_waitcnt lgkmcnt(0)
	v_mfma_f32_16x16x32_bf16 v[88:91], v[16:19], v[4:7], v[88:91]
	v_mfma_f32_16x16x32_bf16 v[84:87], v[12:15], v[4:7], v[84:87]
	v_mfma_f32_16x16x32_bf16 v[80:83], v[8:11], v[4:7], v[36:39]
	v_mfma_f32_16x16x32_bf16 v[76:79], v[20:23], v[0:3], v[52:55]
	v_mfma_f32_16x16x32_bf16 v[72:75], v[16:19], v[0:3], v[48:51]
	v_mfma_f32_16x16x32_bf16 v[68:71], v[12:15], v[0:3], v[44:47]
	v_mfma_f32_16x16x32_bf16 v[60:63], v[8:11], v[0:3], v[32:35]
	s_barrier
	s_add_i32 s66, vcc_lo, 0
	v_add_u32_e32 v0, s66, v151
	v_add_u32_e32 v8, s66, v152
	s_add_i32 s66, vcc_hi, 0
	s_add_i32 s67, s66, s2
	s_add_i32 m0, s67, 0xc00
	s_add_u32 s100, s96, s50
	s_addc_u32 s101, s97, s51
	s_add_u32 s96, s94, s8
	s_addc_u32 s97, s95, s9
	global_load_lds_dwordx4 v179, s[100:101]
	s_add_i32 s66, s66, s4
	s_add_i32 m0, s66, 0x8000
	s_add_u32 s98, s96, s52
	s_addc_u32 s99, s97, s53
	global_load_lds_dwordx4 v178, s[98:99]
	s_add_i32 m0, s66, 0x8400
	s_add_u32 s100, s96, s60
	s_addc_u32 s101, s97, s61
	global_load_lds_dwordx4 v179, s[100:101]
	v_add3_u32 v1, v0, s16, v169
	v_add3_u32 v0, v0, s5, v169
	ds_read_b128 v[64:67], v1
	ds_read_b128 v[56:59], v1 offset:2048
	ds_read_b128 v[36:39], v1 offset:4096
	ds_read_b128 v[32:35], v1 offset:6144
	ds_read_b128 v[52:55], v0 offset:32768
	ds_read_b128 v[48:51], v0 offset:34816
	ds_read_b128 v[44:47], v0 offset:36864
	ds_read_b128 v[40:43], v0 offset:38912
	v_add3_u32 v0, v8, s16, v169
	v_add3_u32 v8, v8, s5, v169
	ds_read_b128 v[28:31], v0
	ds_read_b128 v[24:27], v0 offset:2048
	ds_read_b128 v[4:7], v0 offset:4096
	ds_read_b128 v[0:3], v0 offset:6144
	ds_read_b128 v[20:23], v8 offset:32768
	ds_read_b128 v[16:19], v8 offset:34816
	ds_read_b128 v[12:15], v8 offset:36864
	ds_read_b128 v[8:11], v8 offset:38912
	s_waitcnt lgkmcnt(0)
	v_mov_b32_e32 v148, v179
	v_mov_b32_e32 v148, v178
	v_mov_b32_e32 v148, v179
	s_add_i32 s66, s93, 1
	s_cmp_lg_u32 s93, 2
	s_cselect_b32 s93, s66, 0
	s_add_u32 s8, s8, 0x80
	s_addc_u32 s9, s9, 0
	s_cmpk_eq_i32 s8, 0x680
	s_cbranch_scc0 .LBB0_1356
	s_waitcnt vmcnt(6) lgkmcnt(0)
	s_barrier
	s_waitcnt lgkmcnt(0)
	v_mfma_f32_16x16x32_bf16 v[124:127], v[52:55], v[64:67], v[124:127]
	s_mul_i32 s11, s93, 0xc000
	s_add_i32 s8, s11, 0xffff4000
	v_mfma_f32_16x16x32_bf16 v[120:123], v[48:51], v[64:67], v[120:123]
	s_cmp_lg_u32 s93, 0
	s_cselect_b32 s10, s8, 0x18000
	s_andn2_b64 vcc, exec, s[70:71]
	v_mfma_f32_16x16x32_bf16 v[116:119], v[44:47], v[64:67], v[116:119]
	v_mfma_f32_16x16x32_bf16 v[64:67], v[40:43], v[64:67], v[112:115]
	v_mfma_f32_16x16x32_bf16 v[108:111], v[52:55], v[56:59], v[108:111]
	s_nop 1
	v_cndmask_b32_e64 v112, 0, 1, s[70:71]
	v_cmp_ne_u32_e64 s[8:9], 1, v112
	v_mfma_f32_16x16x32_bf16 v[104:107], v[48:51], v[56:59], v[104:107]
	v_mfma_f32_16x16x32_bf16 v[100:103], v[44:47], v[56:59], v[100:103]
	v_mfma_f32_16x16x32_bf16 v[140:143], v[40:43], v[56:59], v[96:99]
	s_cbranch_vccnz .LBB0_1359
	s_add_u32 s94, s86, s12
	v_mov_b32_e32 v56, v178
	s_addc_u32 s95, s87, s13
	s_add_i32 m0, s3, s10
	s_nop 0
	global_load_lds_dwordx4 v56, s[94:95]

.LBB0_1383:
	s_waitcnt vmcnt(6) lgkmcnt(0)
	s_barrier
	s_mul_i32 s73, s10, 0xc000
	s_add_i32 s74, s73, 0
	v_add_u32_e32 v80, s74, v151
	v_add_u32_e32 v112, s74, v152
	s_add_i32 s73, s73, 0xffff4000
	s_cmp_lg_u32 s10, 0
	s_cselect_b32 s73, s73, 0x18000
	s_add_i32 s90, s73, 0
	s_add_u32 s74, s8, s6
	s_addc_u32 s75, s9, s7
	s_add_i32 s88, s90, s2
	s_add_i32 m0, s88, 0xc00
	s_add_u32 s88, s11, s6
	s_addc_u32 s89, s72, s7
	s_add_u32 s98, s74, s50
	s_addc_u32 s99, s75, s51
	global_load_lds_dwordx4 v179, s[98:99]
	s_add_i32 s90, s90, s4
	s_add_i32 m0, s90, 0x8000
	s_add_u32 s100, s88, s52
	s_addc_u32 s101, s89, s53
	global_load_lds_dwordx4 v178, s[100:101]
	s_add_i32 m0, s90, 0x8400
	s_add_u32 s98, s88, s60
	s_addc_u32 s99, s89, s61
	global_load_lds_dwordx4 v179, s[98:99]
	v_add3_u32 v76, v80, s16, v169
	v_add3_u32 v92, v80, s5, v169
	v_add3_u32 v108, v112, s16, v169
	v_add3_u32 v124, v112, s5, v169
	ds_read_b128 v[64:67], v76
	ds_read_b128 v[68:71], v76 offset:2048
	ds_read_b128 v[72:75], v76 offset:4096
	ds_read_b128 v[76:79], v76 offset:6144
	ds_read_b128 v[80:83], v92 offset:32768
	ds_read_b128 v[84:87], v92 offset:34816
	ds_read_b128 v[88:91], v92 offset:36864
	ds_read_b128 v[92:95], v92 offset:38912
	ds_read_b128 v[96:99], v108
	ds_read_b128 v[100:103], v108 offset:2048
	ds_read_b128 v[104:107], v108 offset:4096
	ds_read_b128 v[108:111], v108 offset:6144
	ds_read_b128 v[112:115], v124 offset:32768
	ds_read_b128 v[116:119], v124 offset:34816
	ds_read_b128 v[120:123], v124 offset:36864
	ds_read_b128 v[124:127], v124 offset:38912
	s_waitcnt lgkmcnt(0)
	v_mov_b32_e32 v148, v179
	v_mov_b32_e32 v148, v178
	v_mov_b32_e32 v148, v179
	s_waitcnt lgkmcnt(0)
	s_barrier
	s_waitcnt lgkmcnt(0)
	v_mfma_f32_16x16x32_bf16 v[60:63], v[80:83], v[64:67], v[60:63]
	s_add_i32 s73, s3, s73
	v_mfma_f32_16x16x32_bf16 v[56:59], v[84:87], v[64:67], v[56:59]
	v_mfma_f32_16x16x32_bf16 v[52:55], v[88:91], v[64:67], v[52:55]
	v_mfma_f32_16x16x32_bf16 v[48:51], v[92:95], v[64:67], v[48:51]
	v_mfma_f32_16x16x32_bf16 v[44:47], v[80:83], v[68:71], v[44:47]
	v_mfma_f32_16x16x32_bf16 v[40:43], v[84:87], v[68:71], v[40:43]
	v_mfma_f32_16x16x32_bf16 v[36:39], v[88:91], v[68:71], v[36:39]
	v_mfma_f32_16x16x32_bf16 v[24:27], v[92:95], v[68:71], v[24:27]
	v_mov_b32_e32 v148, v178
	s_mov_b32 m0, s73
	s_add_u32 s100, s74, s44
	s_addc_u32 s101, s75, s45
	global_load_lds_dwordx4 v178, s[100:101]
	v_mfma_f32_16x16x32_bf16 v[20:23], v[80:83], v[72:75], v[20:23]
	v_mfma_f32_16x16x32_bf16 v[16:19], v[84:87], v[72:75], v[16:19]
	v_mfma_f32_16x16x32_bf16 v[12:15], v[88:91], v[72:75], v[12:15]
	v_mfma_f32_16x16x32_bf16 v[8:11], v[92:95], v[72:75], v[8:11]
	v_mfma_f32_16x16x32_bf16 v[4:7], v[80:83], v[76:79], v[4:7]
	v_mfma_f32_16x16x32_bf16 v[0:3], v[84:87], v[76:79], v[0:3]
	v_mfma_f32_16x16x32_bf16 v[28:31], v[88:91], v[76:79], v[28:31]
	v_mfma_f32_16x16x32_bf16 v[32:35], v[92:95], v[76:79], v[32:35]
	v_mov_b32_e32 v148, v179
	s_add_i32 m0, s73, 0x400
	s_add_u32 s98, s74, s46
	s_addc_u32 s99, s75, s47
	global_load_lds_dwordx4 v179, s[98:99]
	v_mfma_f32_16x16x32_bf16 v[60:63], v[112:115], v[96:99], v[60:63]
	v_mfma_f32_16x16x32_bf16 v[56:59], v[116:119], v[96:99], v[56:59]
	v_mfma_f32_16x16x32_bf16 v[52:55], v[120:123], v[96:99], v[52:55]
	v_mfma_f32_16x16x32_bf16 v[48:51], v[124:127], v[96:99], v[48:51]
	v_mfma_f32_16x16x32_bf16 v[44:47], v[112:115], v[100:103], v[44:47]
	v_mfma_f32_16x16x32_bf16 v[40:43], v[116:119], v[100:103], v[40:43]
	v_mfma_f32_16x16x32_bf16 v[36:39], v[120:123], v[100:103], v[36:39]
	v_mfma_f32_16x16x32_bf16 v[24:27], v[124:127], v[100:103], v[24:27]
	v_mov_b32_e32 v148, v178
	s_add_i32 m0, s73, 0x800
	s_add_u32 s100, s74, s48
	s_addc_u32 s101, s75, s49
	global_load_lds_dwordx4 v178, s[100:101]
	s_add_i32 s73, s10, 1
	v_mfma_f32_16x16x32_bf16 v[20:23], v[112:115], v[104:107], v[20:23]
	s_cmp_lg_u32 s10, 2
	s_cselect_b32 s10, s73, 0
	s_add_u32 s6, s6, 0x80
	v_mfma_f32_16x16x32_bf16 v[16:19], v[116:119], v[104:107], v[16:19]
	s_addc_u32 s7, s7, 0
	s_cmpk_eq_i32 s6, 0x680
	v_mfma_f32_16x16x32_bf16 v[12:15], v[120:123], v[104:107], v[12:15]
	v_mfma_f32_16x16x32_bf16 v[8:11], v[124:127], v[104:107], v[8:11]
	v_mfma_f32_16x16x32_bf16 v[4:7], v[112:115], v[108:111], v[4:7]
	v_mfma_f32_16x16x32_bf16 v[0:3], v[116:119], v[108:111], v[0:3]
	v_mfma_f32_16x16x32_bf16 v[28:31], v[120:123], v[108:111], v[28:31]
	v_mfma_f32_16x16x32_bf16 v[32:35], v[124:127], v[108:111], v[32:35]
	s_cbranch_scc0 .LBB0_1383
	s_waitcnt vmcnt(6) lgkmcnt(0)
	s_barrier
	s_mul_i32 s6, s10, 0xc000
	s_add_i32 s6, s6, 0
	v_add_u32_e32 v64, s6, v151
	v_add3_u32 v65, v64, s16, v169
	v_add3_u32 v64, v64, s5, v169
	v_add_u32_e32 v68, s6, v152
	ds_read_b128 v[124:127], v65
	ds_read_b128 v[120:123], v65 offset:2048
	ds_read_b128 v[100:103], v65 offset:4096
	ds_read_b128 v[96:99], v65 offset:6144
	ds_read_b128 v[108:111], v64 offset:32768
	ds_read_b128 v[112:115], v64 offset:34816
	ds_read_b128 v[116:119], v64 offset:36864
	ds_read_b128 v[104:107], v64 offset:38912
	v_add3_u32 v64, v68, s16, v169
	v_add3_u32 v68, v68, s5, v169
	ds_read_b128 v[92:95], v64
	ds_read_b128 v[88:91], v64 offset:2048
	ds_read_b128 v[72:75], v64 offset:4096
	ds_read_b128 v[64:67], v64 offset:6144
	ds_read_b128 v[76:79], v68 offset:32768
	ds_read_b128 v[80:83], v68 offset:34816
	ds_read_b128 v[84:87], v68 offset:36864
	ds_read_b128 v[68:71], v68 offset:38912
	s_waitcnt lgkmcnt(0)
	v_sub_co_u32_e64 v128, s[6:7], s10, 1
	s_and_b64 s[6:7], s[6:7], exec
	v_readfirstlane_b32 s6, v128
	s_cselect_b32 s73, 2, s6
	v_cndmask_b32_e64 v128, 0, 1, s[68:69]
	s_mov_b64 s[6:7], -1
	v_cmp_ne_u32_e64 s[8:9], 1, v128
	s_andn2_b64 vcc, exec, s[68:69]
	s_mul_i32 s72, s73, 0xc000
	s_cbranch_vccnz .LBB0_1386
	s_mul_i32 s11, s73, 0xc000
	s_mov_b64 s[6:7], 0

.LBB0_1472:
	s_waitcnt vmcnt(6) lgkmcnt(0)
	s_barrier
	s_waitcnt lgkmcnt(0)
	v_mfma_f32_16x16x32_bf16 v[124:127], v[52:55], v[64:67], v[124:127]
	s_mul_i32 s93, s90, 0xc000
	s_add_i32 s94, s93, 0xffff4000
	v_mfma_f32_16x16x32_bf16 v[120:123], v[48:51], v[64:67], v[120:123]
	s_cmp_lg_u32 s90, 0
	s_cselect_b32 vcc_lo, s94, 0x18000
	s_add_i32 vcc_hi, s17, vcc_lo
	v_mfma_f32_16x16x32_bf16 v[116:119], v[44:47], v[64:67], v[116:119]
	v_mfma_f32_16x16x32_bf16 v[64:67], v[40:43], v[64:67], v[112:115]
	v_mfma_f32_16x16x32_bf16 v[108:111], v[52:55], v[56:59], v[108:111]
	v_mfma_f32_16x16x32_bf16 v[104:107], v[48:51], v[56:59], v[104:107]
	v_mfma_f32_16x16x32_bf16 v[100:103], v[44:47], v[56:59], v[100:103]
	v_mfma_f32_16x16x32_bf16 v[56:59], v[40:43], v[56:59], v[96:99]
	s_add_u32 s94, s10, s6
	v_mov_b32_e32 v146, v164
	s_addc_u32 s95, s11, s7
	s_mov_b64 s[96:97], 0x4400180
	s_mov_b32 m0, vcc_hi
	s_add_u32 s98, s94, 0x4400180
	s_addc_u32 s99, s95, 0x0
	global_load_lds_dwordx4 v164, s[98:99]
	v_mfma_f32_16x16x32_bf16 v[92:95], v[52:55], v[36:39], v[92:95]
	v_mfma_f32_16x16x32_bf16 v[88:91], v[48:51], v[36:39], v[88:91]
	v_mfma_f32_16x16x32_bf16 v[84:87], v[44:47], v[36:39], v[84:87]
	v_mfma_f32_16x16x32_bf16 v[36:39], v[40:43], v[36:39], v[80:83]
	v_mfma_f32_16x16x32_bf16 v[52:55], v[52:55], v[32:35], v[76:79]
	v_mfma_f32_16x16x32_bf16 v[48:51], v[48:51], v[32:35], v[72:75]
	v_mfma_f32_16x16x32_bf16 v[44:47], v[44:47], v[32:35], v[68:71]
	v_mfma_f32_16x16x32_bf16 v[32:35], v[40:43], v[32:35], v[60:63]
	v_mov_b32_e32 v146, v165
	s_mov_b64 s[96:97], 0x440b180
	s_add_i32 m0, vcc_hi, 0x400
	s_add_u32 s100, s94, 0x440b180
	s_addc_u32 s101, s95, 0x0
	global_load_lds_dwordx4 v165, s[100:101]
	v_mfma_f32_16x16x32_bf16 v[124:127], v[20:23], v[28:31], v[124:127]
	v_mfma_f32_16x16x32_bf16 v[120:123], v[16:19], v[28:31], v[120:123]
	v_mfma_f32_16x16x32_bf16 v[116:119], v[12:15], v[28:31], v[116:119]
	v_mfma_f32_16x16x32_bf16 v[112:115], v[8:11], v[28:31], v[64:67]
	v_mfma_f32_16x16x32_bf16 v[108:111], v[20:23], v[24:27], v[108:111]
	v_mfma_f32_16x16x32_bf16 v[104:107], v[16:19], v[24:27], v[104:107]
	v_mfma_f32_16x16x32_bf16 v[100:103], v[12:15], v[24:27], v[100:103]
	v_mfma_f32_16x16x32_bf16 v[96:99], v[8:11], v[24:27], v[56:59]
	v_mov_b32_e32 v146, v164
	s_mov_b64 s[96:97], 0x4416180
	s_add_i32 m0, vcc_hi, 0x800
	s_add_u32 s98, s94, 0x4416180
	s_addc_u32 s99, s95, 0x0
	global_load_lds_dwordx4 v164, s[98:99]
	v_mfma_f32_16x16x32_bf16 v[92:95], v[20:23], v[4:7], v[92:95]
	s_waitcnt lgkmcnt(0)
	v_mfma_f32_16x16x32_bf16 v[88:91], v[16:19], v[4:7], v[88:91]
	v_mfma_f32_16x16x32_bf16 v[84:87], v[12:15], v[4:7], v[84:87]
	v_mfma_f32_16x16x32_bf16 v[80:83], v[8:11], v[4:7], v[36:39]
	v_mfma_f32_16x16x32_bf16 v[76:79], v[20:23], v[0:3], v[52:55]
	v_mfma_f32_16x16x32_bf16 v[72:75], v[16:19], v[0:3], v[48:51]
	v_mfma_f32_16x16x32_bf16 v[68:71], v[12:15], v[0:3], v[44:47]
	v_mfma_f32_16x16x32_bf16 v[60:63], v[8:11], v[0:3], v[32:35]
	s_barrier
	s_add_i32 s93, s93, 0
	v_add_u32_e32 v0, s93, v151
	v_add_u32_e32 v8, s93, v152
	s_add_i32 s93, vcc_lo, 0
	s_add_u32 s100, s94, 0x4421180
	s_addc_u32 s101, s95, 0x0
	s_mov_b64 s[94:95], 0x4421180
	s_add_i32 s94, s93, s16
	s_add_i32 m0, s94, 0xc00
	s_add_u32 s94, s91, s6
	s_addc_u32 s95, s92, s7
	global_load_lds_dwordx4 v165, s[100:101]
	s_add_i32 s93, s93, s28
	s_add_i32 m0, s93, 0x8000
	s_add_u32 s98, s94, 0x2980180
	s_addc_u32 s99, s95, 0x0
	global_load_lds_dwordx4 v164, s[98:99]
	s_add_i32 m0, s93, 0x8400
	s_add_u32 s100, s94, 0x298b180
	s_addc_u32 s101, s95, 0x0
	global_load_lds_dwordx4 v165, s[100:101]
	v_add3_u32 v1, v0, s33, v169
	v_add3_u32 v0, v0, s29, v169
	ds_read_b128 v[64:67], v1
	ds_read_b128 v[56:59], v1 offset:2048
	ds_read_b128 v[36:39], v1 offset:4096
	ds_read_b128 v[32:35], v1 offset:6144
	ds_read_b128 v[52:55], v0 offset:32768
	ds_read_b128 v[48:51], v0 offset:34816
	ds_read_b128 v[44:47], v0 offset:36864
	ds_read_b128 v[40:43], v0 offset:38912
	v_add3_u32 v0, v8, s33, v169
	v_add3_u32 v8, v8, s29, v169
	ds_read_b128 v[28:31], v0
	ds_read_b128 v[24:27], v0 offset:2048
	ds_read_b128 v[4:7], v0 offset:4096
	ds_read_b128 v[0:3], v0 offset:6144
	ds_read_b128 v[20:23], v8 offset:32768
	ds_read_b128 v[16:19], v8 offset:34816
	ds_read_b128 v[12:15], v8 offset:36864
	ds_read_b128 v[8:11], v8 offset:38912
	s_waitcnt lgkmcnt(0)
	v_mov_b32_e32 v146, v165
	s_mov_b64 s[96:97], 0x2980180
	v_mov_b32_e32 v146, v164
	v_mov_b32_e32 v146, v165
	s_mov_b64 s[94:95], 0x298b180
	s_add_i32 s93, s90, 1
	s_cmp_lg_u32 s90, 2
	s_cselect_b32 s90, s93, 0
	s_add_u32 s6, s6, 0x80
	s_addc_u32 s7, s7, 0
	s_cmpk_eq_i32 s6, 0x1480
	s_cbranch_scc0 .LBB0_1472
	s_waitcnt vmcnt(6) lgkmcnt(0)
	s_barrier
	s_waitcnt lgkmcnt(0)
	v_mfma_f32_16x16x32_bf16 v[124:127], v[52:55], v[64:67], v[124:127]
	s_mul_i32 s11, s90, 0xc000
	s_add_i32 s6, s11, 0xffff4000
	v_mfma_f32_16x16x32_bf16 v[120:123], v[48:51], v[64:67], v[120:123]
	s_cmp_lg_u32 s90, 0
	s_cselect_b32 s10, s6, 0x18000
	s_andn2_b64 vcc, exec, s[52:53]
	v_mfma_f32_16x16x32_bf16 v[116:119], v[44:47], v[64:67], v[116:119]
	v_mfma_f32_16x16x32_bf16 v[64:67], v[40:43], v[64:67], v[112:115]
	v_mfma_f32_16x16x32_bf16 v[108:111], v[52:55], v[56:59], v[108:111]
	s_nop 1
	v_cndmask_b32_e64 v112, 0, 1, s[52:53]
	v_cmp_ne_u32_e64 s[6:7], 1, v112
	v_mfma_f32_16x16x32_bf16 v[104:107], v[48:51], v[56:59], v[104:107]
	v_mfma_f32_16x16x32_bf16 v[100:103], v[44:47], v[56:59], v[100:103]
	v_mfma_f32_16x16x32_bf16 v[140:143], v[40:43], v[56:59], v[96:99]
	s_cbranch_vccnz .LBB0_1475
	s_add_u32 s92, s51, s8
	v_mov_b32_e32 v56, v164
	s_addc_u32 s93, s82, s9
	s_add_i32 m0, s17, s10
	s_nop 0
	global_load_lds_dwordx4 v56, s[92:93]

.LBB0_1499:
	s_waitcnt vmcnt(6) lgkmcnt(0)
	s_barrier
	s_mul_i32 s20, s10, 0xc000
	s_add_i32 s21, s20, 0
	v_add_u32_e32 v80, s21, v151
	v_add_u32_e32 v112, s21, v152
	s_add_i32 s20, s20, 0xffff4000
	s_cmp_lg_u32 s10, 0
	s_cselect_b32 s60, s20, 0x18000
	s_add_i32 s61, s60, 0
	s_add_u32 s20, s89, s4
	s_addc_u32 s21, s93, s5
	s_add_i32 s85, s61, s16
	v_mov_b32_e32 v128, v165
	s_add_i32 m0, s85, 0xc00
	s_nop 0
	global_load_lds_dwordx4 v128, s[20:21]
	s_add_u32 s20, s94, s4
	s_addc_u32 s21, s95, s5
	s_add_i32 s61, s61, s28
	v_mov_b32_e32 v128, v164
	s_add_i32 m0, s61, 0x8000
	s_nop 0
	global_load_lds_dwordx4 v128, s[20:21]
	s_add_u32 s20, s87, s4
	v_mov_b32_e32 v128, v165
	s_addc_u32 s21, s86, s5
	s_add_i32 m0, s61, 0x8400
	s_nop 0
	global_load_lds_dwordx4 v128, s[20:21]
	v_add3_u32 v76, v80, s33, v169
	v_add3_u32 v92, v80, s29, v169
	v_add3_u32 v108, v112, s33, v169
	v_add3_u32 v124, v112, s29, v169
	ds_read_b128 v[64:67], v76
	ds_read_b128 v[68:71], v76 offset:2048
	ds_read_b128 v[72:75], v76 offset:4096
	ds_read_b128 v[76:79], v76 offset:6144
	ds_read_b128 v[80:83], v92 offset:32768
	ds_read_b128 v[84:87], v92 offset:34816
	ds_read_b128 v[88:91], v92 offset:36864
	ds_read_b128 v[92:95], v92 offset:38912
	ds_read_b128 v[96:99], v108
	ds_read_b128 v[100:103], v108 offset:2048
	ds_read_b128 v[104:107], v108 offset:4096
	ds_read_b128 v[108:111], v108 offset:6144
	ds_read_b128 v[112:115], v124 offset:32768
	ds_read_b128 v[116:119], v124 offset:34816
	ds_read_b128 v[120:123], v124 offset:36864
	ds_read_b128 v[124:127], v124 offset:38912
	s_waitcnt lgkmcnt(0)
	s_waitcnt lgkmcnt(0)
	s_barrier
	s_waitcnt lgkmcnt(0)
	v_mfma_f32_16x16x32_bf16 v[60:63], v[80:83], v[64:67], v[60:63]
	s_add_i32 s60, s17, s60
	v_mfma_f32_16x16x32_bf16 v[56:59], v[84:87], v[64:67], v[56:59]
	v_mfma_f32_16x16x32_bf16 v[52:55], v[88:91], v[64:67], v[52:55]
	v_mfma_f32_16x16x32_bf16 v[48:51], v[92:95], v[64:67], v[48:51]
	v_mfma_f32_16x16x32_bf16 v[44:47], v[80:83], v[68:71], v[44:47]
	v_mfma_f32_16x16x32_bf16 v[40:43], v[84:87], v[68:71], v[40:43]
	v_mfma_f32_16x16x32_bf16 v[36:39], v[88:91], v[68:71], v[36:39]
	v_mfma_f32_16x16x32_bf16 v[0:3], v[92:95], v[68:71], v[0:3]
	s_add_u32 s20, s6, s4
	v_mov_b32_e32 v64, v164
	s_addc_u32 s21, s7, s5
	s_mov_b32 m0, s60
	s_nop 0
	global_load_lds_dwordx4 v64, s[20:21]
	v_mfma_f32_16x16x32_bf16 v[28:31], v[80:83], v[72:75], v[28:31]
	v_mfma_f32_16x16x32_bf16 v[24:27], v[84:87], v[72:75], v[24:27]
	v_mfma_f32_16x16x32_bf16 v[20:23], v[88:91], v[72:75], v[20:23]
	v_mfma_f32_16x16x32_bf16 v[16:19], v[92:95], v[72:75], v[16:19]
	v_mfma_f32_16x16x32_bf16 v[12:15], v[80:83], v[76:79], v[12:15]
	v_mfma_f32_16x16x32_bf16 v[8:11], v[84:87], v[76:79], v[8:11]
	v_mfma_f32_16x16x32_bf16 v[4:7], v[88:91], v[76:79], v[4:7]
	v_mfma_f32_16x16x32_bf16 v[32:35], v[92:95], v[76:79], v[32:35]
	s_add_u32 s20, s11, s4
	v_mov_b32_e32 v64, v165
	s_addc_u32 s21, s90, s5
	s_add_i32 m0, s60, 0x400
	s_nop 0
	global_load_lds_dwordx4 v64, s[20:21]
	v_mfma_f32_16x16x32_bf16 v[60:63], v[112:115], v[96:99], v[60:63]
	v_mfma_f32_16x16x32_bf16 v[56:59], v[116:119], v[96:99], v[56:59]
	v_mfma_f32_16x16x32_bf16 v[52:55], v[120:123], v[96:99], v[52:55]
	v_mfma_f32_16x16x32_bf16 v[48:51], v[124:127], v[96:99], v[48:51]
	v_mfma_f32_16x16x32_bf16 v[44:47], v[112:115], v[100:103], v[44:47]
	v_mfma_f32_16x16x32_bf16 v[40:43], v[116:119], v[100:103], v[40:43]
	v_mfma_f32_16x16x32_bf16 v[36:39], v[120:123], v[100:103], v[36:39]
	v_mfma_f32_16x16x32_bf16 v[0:3], v[124:127], v[100:103], v[0:3]
	s_add_u32 s20, s91, s4
	v_mov_b32_e32 v64, v164
	s_addc_u32 s21, s92, s5
	s_add_i32 m0, s60, 0x800
	s_nop 0
	global_load_lds_dwordx4 v64, s[20:21]
	s_add_i32 s20, s10, 1
	v_mfma_f32_16x16x32_bf16 v[28:31], v[112:115], v[104:107], v[28:31]
	s_cmp_lg_u32 s10, 2
	s_cselect_b32 s10, s20, 0
	s_add_u32 s4, s4, 0x80
	v_mfma_f32_16x16x32_bf16 v[24:27], v[116:119], v[104:107], v[24:27]
	s_addc_u32 s5, s5, 0
	s_cmpk_eq_i32 s4, 0x1480
	v_mfma_f32_16x16x32_bf16 v[20:23], v[120:123], v[104:107], v[20:23]
	v_mfma_f32_16x16x32_bf16 v[16:19], v[124:127], v[104:107], v[16:19]
	v_mfma_f32_16x16x32_bf16 v[12:15], v[112:115], v[108:111], v[12:15]
	v_mfma_f32_16x16x32_bf16 v[8:11], v[116:119], v[108:111], v[8:11]
	v_mfma_f32_16x16x32_bf16 v[4:7], v[120:123], v[108:111], v[4:7]
	v_mfma_f32_16x16x32_bf16 v[32:35], v[124:127], v[108:111], v[32:35]
	s_cbranch_scc0 .LBB0_1499
	s_waitcnt vmcnt(6) lgkmcnt(0)
	s_barrier
	s_mul_i32 s4, s10, 0xc000
	s_add_i32 s4, s4, 0
	v_add_u32_e32 v64, s4, v151
	v_add3_u32 v65, v64, s33, v169
	v_add3_u32 v64, v64, s29, v169
	v_add_u32_e32 v68, s4, v152
	ds_read_b128 v[124:127], v65
	ds_read_b128 v[120:123], v65 offset:2048
	ds_read_b128 v[96:99], v65 offset:4096
	ds_read_b128 v[92:95], v65 offset:6144
	ds_read_b128 v[108:111], v64 offset:32768
	ds_read_b128 v[112:115], v64 offset:34816
	ds_read_b128 v[116:119], v64 offset:36864
	ds_read_b128 v[100:103], v64 offset:38912
	v_add3_u32 v64, v68, s33, v169
	v_add3_u32 v68, v68, s29, v169
	ds_read_b128 v[88:91], v64
	ds_read_b128 v[104:107], v64 offset:2048
	ds_read_b128 v[72:75], v64 offset:4096
	ds_read_b128 v[64:67], v64 offset:6144
	ds_read_b128 v[76:79], v68 offset:32768
	ds_read_b128 v[80:83], v68 offset:34816
	ds_read_b128 v[84:87], v68 offset:36864
	ds_read_b128 v[68:71], v68 offset:38912
	s_waitcnt lgkmcnt(0)
	v_sub_co_u32_e64 v128, s[4:5], s10, 1
	s_and_b64 s[4:5], s[4:5], exec
	v_readfirstlane_b32 s4, v128
	s_cselect_b32 s21, 2, s4
	v_cndmask_b32_e64 v128, 0, 1, s[48:49]
	s_mov_b64 s[4:5], -1
	v_cmp_ne_u32_e64 s[6:7], 1, v128
	s_andn2_b64 vcc, exec, s[48:49]
	s_mul_i32 s20, s21, 0xc000
	s_cbranch_vccnz .LBB0_1502
	s_mul_i32 s11, s21, 0xc000
	s_mov_b64 s[4:5], 0

.LBB0_1580:
	v_add_u32_e32 v46, s9, v48
	v_ashrrev_i32_e32 v47, 31, v46
	v_add_u32_e32 v52, 1, v46
	v_lshlrev_b64 v[54:55], 11, v[46:47]
	v_ashrrev_i32_e32 v53, 31, v52
	v_lshl_add_u64 v[68:69], v[34:35], 0, v[54:55]
	v_lshl_add_u64 v[70:71], v[36:37], 0, v[54:55]
	v_lshlrev_b64 v[72:73], 11, v[52:53]
	v_lshlrev_b64 v[74:75], 12, v[52:53]
	global_load_dwordx4 v[52:55], v[68:69], off
	global_load_dwordx4 v[56:59], v[68:69], off offset:1024
	global_load_dwordx4 v[60:63], v[70:71], off
	global_load_dwordx4 v[64:67], v[70:71], off offset:1024
	v_lshlrev_b64 v[46:47], 12, v[46:47]
	v_lshl_add_u64 v[68:69], v[34:35], 0, v[72:73]
	v_lshl_add_u64 v[70:71], v[36:37], 0, v[72:73]
	v_lshl_add_u64 v[72:73], v[42:43], 0, v[74:75]
	v_lshl_add_u64 v[46:47], v[42:43], 0, v[46:47]
	s_add_i32 s9, s9, 2
	s_cmp_eq_u32 s9, 4
	s_waitcnt vmcnt(3)
	v_lshlrev_b32_e32 v76, 16, v54
	s_waitcnt vmcnt(2)
	v_lshlrev_b32_e32 v80, 16, v56
	v_and_b32_e32 v81, 0xffff0000, v56
	v_lshlrev_b32_e32 v82, 16, v57
	v_and_b32_e32 v83, 0xffff0000, v57
	s_waitcnt vmcnt(1)
	v_and_b32_e32 v57, 0xffff0000, v62
	v_and_b32_e32 v56, 0xffff0000, v60
	v_and_b32_e32 v77, 0xffff0000, v54
	v_lshlrev_b32_e32 v78, 16, v55
	v_and_b32_e32 v79, 0xffff0000, v55
	v_lshlrev_b32_e32 v84, 16, v58
	v_and_b32_e32 v85, 0xffff0000, v58
	v_lshlrev_b32_e32 v55, 16, v62
	v_lshlrev_b32_e32 v54, 16, v60
	v_lshlrev_b32_e32 v58, 16, v61
	v_and_b32_e32 v62, 0xffff0000, v61
	s_waitcnt vmcnt(0)
	v_lshlrev_b32_e32 v61, 16, v64
	v_lshlrev_b32_e32 v60, 16, v66
	v_and_b32_e32 v89, 0xffff0000, v64
	v_and_b32_e32 v88, 0xffff0000, v66
	v_lshlrev_b32_e32 v90, 16, v67
	v_and_b32_e32 v64, 0xffff0000, v67
	v_pk_mul_f32 v[66:67], v[56:57], v[56:57]
	v_lshlrev_b32_e32 v86, 16, v59
	v_and_b32_e32 v87, 0xffff0000, v59
	v_lshlrev_b32_e32 v59, 16, v63
	v_pk_mul_f32 v[92:93], v[88:89], v[88:89]
	v_mov_b32_e32 v96, v54
	v_mov_b32_e32 v97, v56
	v_mov_b32_e32 v56, v55
	v_pk_fma_f32 v[54:55], v[54:55], v[54:55], v[66:67]
	v_and_b32_e32 v63, 0xffff0000, v63
	v_lshlrev_b32_e32 v91, 16, v65
	v_pk_fma_f32 v[66:67], v[60:61], v[60:61], v[92:93]
	v_pk_fma_f32 v[54:55], v[58:59], v[58:59], v[54:55]
	v_and_b32_e32 v65, 0xffff0000, v65
	v_pk_fma_f32 v[66:67], v[90:91], v[90:91], v[66:67]
	v_pk_fma_f32 v[54:55], v[62:63], v[62:63], v[54:55]
	v_mov_b32_e32 v98, v91
	v_mov_b32_e32 v99, v65
	v_mov_b32_e32 v91, v64
	v_pk_fma_f32 v[64:65], v[64:65], v[64:65], v[66:67]
	v_add_f32_e32 v51, v54, v55
	v_add_f32_e32 v51, v51, v65
	v_add_f32_e32 v51, v64, v51
	ds_bpermute_b32 v54, v172, v51
	v_mov_b32_e32 v94, v58
	v_mov_b32_e32 v95, v62
	v_mov_b32_e32 v100, v61
	v_mov_b32_e32 v101, v89
	s_waitcnt lgkmcnt(0)
	v_add_f32_e32 v51, v51, v54
	ds_bpermute_b32 v54, v173, v51
	v_mov_b32_e32 v61, v88
	v_mov_b32_e32 v62, v59
	v_lshlrev_b32_e32 v74, 16, v52
	v_and_b32_e32 v75, 0xffff0000, v52
	s_waitcnt lgkmcnt(0)
	v_add_f32_e32 v51, v51, v54
	ds_bpermute_b32 v54, v174, v51
	v_lshlrev_b32_e32 v52, 16, v53
	v_and_b32_e32 v53, 0xffff0000, v53
	s_waitcnt lgkmcnt(0)
	v_add_f32_e32 v51, v51, v54
	ds_bpermute_b32 v54, v175, v51
	s_waitcnt lgkmcnt(0)
	v_add_f32_e32 v51, v51, v54
	ds_bpermute_b32 v54, v176, v51
	s_waitcnt lgkmcnt(0)
	v_add_f32_e32 v51, v51, v54
	ds_bpermute_b32 v54, v177, v51
	s_waitcnt lgkmcnt(0)
	v_add_f32_e32 v51, v51, v54
	v_fmamk_f32 v51, v51, 0x3a800000, v50
	v_mul_f32_e32 v54, 0x4b800000, v51
	v_cmp_gt_f32_e32 vcc, s7, v51
	s_nop 1
	v_cndmask_b32_e32 v51, v51, v54, vcc
	v_rsq_f32_e32 v51, v51
	s_nop 0
	v_mul_f32_e32 v54, 0x45800000, v51
	v_cndmask_b32_e32 v54, v51, v54, vcc
	v_pk_mul_f32 v[58:59], v[54:55], v[94:95] op_sel_hi:[0,1]
	v_pk_mul_f32 v[64:65], v[54:55], v[96:97] op_sel_hi:[0,1]
	v_pk_mul_f32 v[62:63], v[54:55], v[62:63] op_sel_hi:[0,1]
	v_pk_mul_f32 v[56:57], v[54:55], v[56:57] op_sel_hi:[0,1]
	v_pk_mul_f32 v[66:67], v[54:55], v[98:99] op_sel_hi:[0,1]
	v_pk_mul_f32 v[88:89], v[54:55], v[100:101] op_sel_hi:[0,1]
	v_pk_mul_f32 v[90:91], v[54:55], v[90:91] op_sel_hi:[0,1]
	v_pk_mul_f32 v[54:55], v[54:55], v[60:61] op_sel_hi:[0,1]
	v_pk_mul_f32 v[60:61], v[4:5], v[64:65]
	v_pk_mul_f32 v[58:59], v[6:7], v[58:59]
	v_pk_mul_f32 v[56:57], v[0:1], v[56:57]
	v_pk_mul_f32 v[62:63], v[2:3], v[62:63]
	v_pk_mul_f32 v[64:65], v[20:21], v[88:89]
	v_pk_mul_f32 v[66:67], v[22:23], v[66:67]
	v_pk_mul_f32 v[88:89], v[16:17], v[54:55]
	v_pk_mul_f32 v[90:91], v[18:19], v[90:91]
	v_pk_fma_f32 v[54:55], v[14:15], v[58:59], v[52:53]
	v_pk_fma_f32 v[52:53], v[12:13], v[60:61], v[74:75]
	v_pk_fma_f32 v[58:59], v[10:11], v[62:63], v[78:79]
	v_pk_fma_f32 v[56:57], v[8:9], v[56:57], v[76:77]
	v_pk_fma_f32 v[62:63], v[30:31], v[66:67], v[82:83]
	v_pk_fma_f32 v[60:61], v[28:29], v[64:65], v[80:81]
	v_pk_fma_f32 v[66:67], v[26:27], v[90:91], v[86:87]
	v_pk_fma_f32 v[64:65], v[24:25], v[88:89], v[84:85]
	global_store_dwordx4 v[46:47], v[52:55], off nt
	global_store_dwordx4 v[46:47], v[56:59], off offset:16 nt
	global_store_dwordx4 v[46:47], v[60:63], off offset:2048 nt
	global_store_dwordx4 v[46:47], v[64:67], off offset:2064 nt
	global_load_dwordx4 v[52:55], v[68:69], off
	s_nop 0
	global_load_dwordx4 v[56:59], v[70:71], off
	global_load_dwordx4 v[60:63], v[70:71], off offset:1024
	global_load_dwordx4 v[64:67], v[68:69], off offset:1024
	s_waitcnt vmcnt(3)
	v_lshlrev_b32_e32 v68, 16, v54
	s_waitcnt vmcnt(2)
	v_and_b32_e32 v79, 0xffff0000, v58
	v_and_b32_e32 v78, 0xffff0000, v56
	v_and_b32_e32 v69, 0xffff0000, v54
	v_lshlrev_b32_e32 v70, 16, v55
	v_and_b32_e32 v71, 0xffff0000, v55
	v_lshlrev_b32_e32 v55, 16, v58
	v_lshlrev_b32_e32 v54, 16, v56
	v_lshlrev_b32_e32 v80, 16, v57
	v_and_b32_e32 v58, 0xffff0000, v57
	s_waitcnt vmcnt(1)
	v_lshlrev_b32_e32 v57, 16, v60
	v_lshlrev_b32_e32 v56, 16, v62
	v_and_b32_e32 v83, 0xffff0000, v60
	v_and_b32_e32 v82, 0xffff0000, v62
	v_lshlrev_b32_e32 v84, 16, v63
	v_and_b32_e32 v60, 0xffff0000, v63
	v_pk_mul_f32 v[62:63], v[78:79], v[78:79]
	v_lshlrev_b32_e32 v81, 16, v59
	v_pk_mul_f32 v[86:87], v[82:83], v[82:83]
	v_mov_b32_e32 v90, v54
	v_mov_b32_e32 v91, v78
	v_mov_b32_e32 v78, v55
	v_pk_fma_f32 v[54:55], v[54:55], v[54:55], v[62:63]
	v_and_b32_e32 v59, 0xffff0000, v59
	v_lshlrev_b32_e32 v85, 16, v61
	v_pk_fma_f32 v[62:63], v[56:57], v[56:57], v[86:87]
	v_pk_fma_f32 v[54:55], v[80:81], v[80:81], v[54:55]
	v_and_b32_e32 v61, 0xffff0000, v61
	v_pk_fma_f32 v[62:63], v[84:85], v[84:85], v[62:63]
	v_pk_fma_f32 v[54:55], v[58:59], v[58:59], v[54:55]
	v_mov_b32_e32 v92, v85
	v_mov_b32_e32 v93, v61
	v_mov_b32_e32 v85, v60
	v_pk_fma_f32 v[60:61], v[60:61], v[60:61], v[62:63]
	v_add_f32_e32 v51, v54, v55
	v_add_f32_e32 v51, v51, v61
	v_add_f32_e32 v51, v60, v51
	ds_bpermute_b32 v54, v172, v51
	v_mov_b32_e32 v88, v80
	v_mov_b32_e32 v89, v58
	v_mov_b32_e32 v94, v57
	v_mov_b32_e32 v95, v83
	s_waitcnt lgkmcnt(0)
	v_add_f32_e32 v51, v51, v54
	ds_bpermute_b32 v54, v173, v51
	v_mov_b32_e32 v57, v82
	v_mov_b32_e32 v58, v81
	v_lshlrev_b32_e32 v46, 16, v52
	v_and_b32_e32 v47, 0xffff0000, v52
	s_waitcnt lgkmcnt(0)
	v_add_f32_e32 v51, v51, v54
	ds_bpermute_b32 v54, v174, v51
	v_lshlrev_b32_e32 v52, 16, v53
	v_and_b32_e32 v53, 0xffff0000, v53
	s_waitcnt vmcnt(0)
	v_lshlrev_b32_e32 v74, 16, v64
	v_and_b32_e32 v75, 0xffff0000, v64
	s_waitcnt lgkmcnt(0)
	v_add_f32_e32 v51, v51, v54
	ds_bpermute_b32 v54, v175, v51
	v_lshlrev_b32_e32 v64, 16, v65
	v_and_b32_e32 v65, 0xffff0000, v65
	v_lshlrev_b32_e32 v76, 16, v66
	v_and_b32_e32 v77, 0xffff0000, v66
	s_waitcnt lgkmcnt(0)
	v_add_f32_e32 v51, v51, v54
	ds_bpermute_b32 v54, v176, v51
	v_lshlrev_b32_e32 v66, 16, v67
	v_and_b32_e32 v67, 0xffff0000, v67
	s_waitcnt lgkmcnt(0)
	v_add_f32_e32 v51, v51, v54
	ds_bpermute_b32 v54, v177, v51
	s_waitcnt lgkmcnt(0)
	v_add_f32_e32 v51, v51, v54
	v_fmamk_f32 v51, v51, 0x3a800000, v50
	v_mul_f32_e32 v54, 0x4b800000, v51
	v_cmp_gt_f32_e32 vcc, s7, v51
	s_nop 1
	v_cndmask_b32_e32 v51, v51, v54, vcc
	v_rsq_f32_e32 v51, v51
	s_nop 0
	v_mul_f32_e32 v54, 0x45800000, v51
	v_cndmask_b32_e32 v54, v51, v54, vcc
	v_pk_mul_f32 v[60:61], v[54:55], v[88:89] op_sel_hi:[0,1]
	v_pk_mul_f32 v[62:63], v[54:55], v[90:91] op_sel_hi:[0,1]
	v_pk_mul_f32 v[58:59], v[54:55], v[58:59] op_sel_hi:[0,1]
	v_pk_mul_f32 v[78:79], v[54:55], v[78:79] op_sel_hi:[0,1]
	v_pk_mul_f32 v[80:81], v[54:55], v[92:93] op_sel_hi:[0,1]
	v_pk_mul_f32 v[82:83], v[54:55], v[94:95] op_sel_hi:[0,1]
	v_pk_mul_f32 v[84:85], v[54:55], v[84:85] op_sel_hi:[0,1]
	v_pk_mul_f32 v[54:55], v[54:55], v[56:57] op_sel_hi:[0,1]
	v_pk_mul_f32 v[56:57], v[4:5], v[62:63]
	v_pk_mul_f32 v[60:61], v[6:7], v[60:61]
	v_pk_mul_f32 v[62:63], v[0:1], v[78:79]
	v_pk_mul_f32 v[58:59], v[2:3], v[58:59]
	v_pk_mul_f32 v[78:79], v[20:21], v[82:83]
	v_pk_mul_f32 v[80:81], v[22:23], v[80:81]
	v_pk_mul_f32 v[82:83], v[16:17], v[54:55]
	v_pk_mul_f32 v[84:85], v[18:19], v[84:85]
	v_pk_fma_f32 v[54:55], v[14:15], v[60:61], v[52:53]
	v_pk_fma_f32 v[52:53], v[12:13], v[56:57], v[46:47]
	v_pk_fma_f32 v[58:59], v[10:11], v[58:59], v[70:71]
	v_pk_fma_f32 v[56:57], v[8:9], v[62:63], v[68:69]
	v_pk_fma_f32 v[62:63], v[30:31], v[80:81], v[64:65]
	v_pk_fma_f32 v[60:61], v[28:29], v[78:79], v[74:75]
	v_pk_fma_f32 v[66:67], v[26:27], v[84:85], v[66:67]
	v_pk_fma_f32 v[64:65], v[24:25], v[82:83], v[76:77]
	global_store_dwordx4 v[72:73], v[52:55], off nt
	global_store_dwordx4 v[72:73], v[56:59], off offset:16 nt
	global_store_dwordx4 v[72:73], v[60:63], off offset:2048 nt
	global_store_dwordx4 v[72:73], v[64:67], off offset:2064 nt
	s_cbranch_scc0 .LBB0_1580
	v_add_u32_e32 v145, s4, v145
	v_cmp_lt_i32_e32 vcc, s8, v145
	s_or_b64 s[0:1], vcc, s[0:1]
	v_add_u32_e32 v48, s5, v48
	s_andn2_b64 exec, exec, s[0:1]
	s_cbranch_execnz .LBB0_1579

	.amdhsa_kernel _Z4mega6Params
		.amdhsa_group_segment_fixed_size 0
		.amdhsa_private_segment_fixed_size 0
		.amdhsa_kernarg_size 440
		.amdhsa_user_sgpr_count 2
		.amdhsa_user_sgpr_dispatch_ptr 0
		.amdhsa_user_sgpr_queue_ptr 0
		.amdhsa_user_sgpr_kernarg_segment_ptr 1
		.amdhsa_user_sgpr_dispatch_id 0
		.amdhsa_user_sgpr_kernarg_preload_length 0
		.amdhsa_user_sgpr_kernarg_preload_offset 0
		.amdhsa_user_sgpr_private_segment_size 0
		.amdhsa_uses_dynamic_stack 0
		.amdhsa_enable_private_segment 0
		.amdhsa_system_sgpr_workgroup_id_x 1
		.amdhsa_system_sgpr_workgroup_id_y 0
		.amdhsa_system_sgpr_workgroup_id_z 0
		.amdhsa_system_sgpr_workgroup_info 0
		.amdhsa_system_vgpr_workitem_id 2
		.amdhsa_next_free_vgpr 224
		.amdhsa_next_free_sgpr 102
		.amdhsa_accum_offset 224
		.amdhsa_reserve_vcc 1
		.amdhsa_float_round_mode_32 0
		.amdhsa_float_round_mode_16_64 0
		.amdhsa_float_denorm_mode_32 3
		.amdhsa_float_denorm_mode_16_64 3
		.amdhsa_dx10_clamp 1
		.amdhsa_ieee_mode 1
		.amdhsa_fp16_overflow 0
		.amdhsa_tg_split 0
		.amdhsa_exception_fp_ieee_invalid_op 0
		.amdhsa_exception_fp_denorm_src 0
		.amdhsa_exception_fp_ieee_div_zero 0
		.amdhsa_exception_fp_ieee_overflow 0
		.amdhsa_exception_fp_ieee_underflow 0
		.amdhsa_exception_fp_ieee_inexact 0
		.amdhsa_exception_int_div_zero 0
	.end_amdhsa_kernel

amdhsa.kernels:
  - .agpr_count:     0
    .args:
      - .offset:         0
        .size:           184
        .value_kind:     by_value
      - .offset:         184
        .size:           4
        .value_kind:     hidden_block_count_x
      - .offset:         188
        .size:           4
        .value_kind:     hidden_block_count_y
      - .offset:         192
        .size:           4
        .value_kind:     hidden_block_count_z
      - .offset:         196
        .size:           2
        .value_kind:     hidden_group_size_x
      - .offset:         198
        .size:           2
        .value_kind:     hidden_group_size_y
      - .offset:         200
        .size:           2
        .value_kind:     hidden_group_size_z
      - .offset:         202
        .size:           2
        .value_kind:     hidden_remainder_x
      - .offset:         204
        .size:           2
        .value_kind:     hidden_remainder_y
      - .offset:         206
        .size:           2
        .value_kind:     hidden_remainder_z
      - .offset:         224
        .size:           8
        .value_kind:     hidden_global_offset_x
      - .offset:         232
        .size:           8
        .value_kind:     hidden_global_offset_y
      - .offset:         240
        .size:           8
        .value_kind:     hidden_global_offset_z
      - .offset:         248
        .size:           2
        .value_kind:     hidden_grid_dims
      - .offset:         272
        .size:           8
        .value_kind:     hidden_multigrid_sync_arg
      - .offset:         304
        .size:           4
        .value_kind:     hidden_dynamic_lds_size
    .group_segment_fixed_size: 0
    .kernarg_segment_align: 8
    .kernarg_segment_size: 440
    .language:       OpenCL C
    .language_version:
      - 2
      - 0
    .max_flat_workgroup_size: 512
    .name:           _Z4mega6Params
    .private_segment_fixed_size: 0
    .sgpr_count:     108
    .sgpr_spill_count: 82
    .symbol:         _Z4mega6Params.kd
    .uniform_work_group_size: 1
    .uses_dynamic_stack: false
    .vgpr_count:     224
    .vgpr_spill_count: 0
    .wavefront_size: 64
